# v46 plus GEMM K-loops: first K-iteration peeled with SrcC=0 on each accumulator first touch, accumulator zeroing removed
# speedup vs baseline: 1.0149x; 1.0046x over previous
; #define PG8_STAGE(bufoff, gbase, voff) do { _Pragma("unroll") for (int _i = 0; _i < 2; ++_i) \
;         __builtin_amdgcn_global_load_lds((const unsigned*)((const char*)(gbase) + (voff)[_i]), (PG8_LAS unsigned*)(lds + (bufoff) + ldsw + _i * 8192), 16, 0, 0); } while (0)
; #define PG8_LDA(dst, b, h) do { _Pragma("unroll") for (int m = 0; m < 4; ++m) _Pragma("unroll") for (int k = 0; k < 2; ++k) dst[m][k] = *(const PG8_LAS bf16x8*)(lds + PG8_SA(b, h) + aoff + m * 2048 + k * 1024); } while (0)
; #define PG8_LDB(dst, b, h) do { _Pragma("unroll") for (int n = 0; n < 2; ++n) _Pragma("unroll") for (int k = 0; k < 2; ++k) dst[n][k] = *(const PG8_LAS bf16x8*)(lds + PG8_SB(b, h) + boff + n * 2048 + k * 1024); } while (0)
; #define PG8_MMA(ai, bj, At, Bt) do { __builtin_amdgcn_s_setprio(1); _Pragma("unroll") for (int m = 0; m < 4; ++m) _Pragma("unroll") for (int n = 0; n < 2; ++n) _Pragma("unroll") for (int k = 0; k < 2; ++k) \
;         acc[ai][bj][m][n] = __builtin_amdgcn_mfma_f32_16x16x32_bf16(Bt[n][k], At[m][k], acc[ai][bj][m][n], 0, 0, 0); __builtin_amdgcn_s_setprio(0); } while (0)
; #define PG8_WAIT_V(n) asm volatile("s_waitcnt vmcnt(" #n ")" ::: "memory")
; #define PG8_BAR __builtin_amdgcn_s_barrier()
; template <class Epi, class Sched, bool ALIGN_EPI = false, bool SP2 = false>
; __device__ __forceinline__ void gemm_phase(PG8_LAS unsigned char* lds, const Gemm g, const Sched& S, const Epi& E, int wave_s_) {
;     ...
;         for (int t = 0; t < nt; t += 2) {
;             const bool last = (t == nt - 2);
;             const char* a1 = cA + (size_t)(t + 1) * kstep;
;             const char* a2 = last ? nA : cA + (size_t)(t + 2) * kstep; const char* b2 = last ? nB : cB + (size_t)(t + 2) * kstep;
;             const char* a3 = a2 + kstep; const char* b3 = b2 + kstep;
;             if (last && has_next) S.a_ready(nxt);
;             if constexpr (SP2) {
;             PG8_LDB(B0, 0, 0); PG8_LDB(B1, 0, 1); PG8_SCHED; PG8_LDA(At, 0, 0); PG8_STAGE(PG8_SA(1, 1), a1 + hstep, voffA);
;             PG8_WAIT_V(8); PG8_WAIT_L(0); PG8_BAR; PG8_MMA(0, 0, At, B0); PG8_MMA(0, 1, At, B1); PG8_BAR; PG8_SCHED;
;             PG8_LDA(At, 0, 1); PG8_STAGE(PG8_SB(0, 0), b2, voffB); PG8_STAGE(PG8_SB(0, 1), b2 + hstep, voffB); PG8_STAGE(PG8_SA(0, 0), a2, voffA);
;             PG8_WAIT_V(8); PG8_WAIT_L(0); PG8_BAR; PG8_MMA(1, 0, At, B0); PG8_MMA(1, 1, At, B1); PG8_BAR; PG8_SCHED;
.LBB0_206:
	s_add_u32 s17, s22, 0x100
	s_addc_u32 s48, s23, 0
	s_add_u32 s22, s24, 0x40080
	v_mov_b32_e32 v0, 0
	s_addc_u32 s23, s25, 0
	s_mov_b32 s49, -2
	s_add_u32 s24, s22, 0xfffc0080
	s_addc_u32 s25, s23, -1
	s_add_i32 s50, 0, 0x10000
	s_cmp_eq_u32 s49, 12
	s_cselect_b32 s27, s9, s25
	s_cselect_b32 s26, s8, s24
	s_cselect_b32 s25, s19, s48
	s_cselect_b32 s24, s18, s17
	s_add_i32 s52, 0, 0x14000
	v_add_u32_e32 v152, s50, v138
	v_add_u32_e32 v168, s52, v138
	ds_read_b128 v[140:143], v152
	ds_read_b128 v[144:147], v152 offset:1024
	ds_read_b128 v[148:151], v152 offset:2048
	ds_read_b128 v[152:155], v152 offset:3072
	ds_read_b128 v[156:159], v168
	ds_read_b128 v[160:163], v168 offset:1024
	ds_read_b128 v[164:167], v168 offset:2048
	ds_read_b128 v[168:171], v168 offset:3072
	v_lshl_add_u64 v[214:215], s[22:23], 0, v[136:137]
	s_add_i32 m0, s35, 0xc000
	ds_read_b128 v[172:175], v139
	ds_read_b128 v[176:179], v139 offset:1024
	ds_read_b128 v[180:183], v139 offset:2048
	ds_read_b128 v[184:187], v139 offset:3072
	ds_read_b128 v[188:191], v139 offset:4096
	ds_read_b128 v[192:195], v139 offset:5120
	ds_read_b128 v[206:209], v139 offset:6144
	ds_read_b128 v[210:213], v139 offset:7168
	global_load_lds_dwordx4 v[214:215], off
	v_lshl_add_u64 v[214:215], s[22:23], 0, v[134:135]
	s_add_i32 m0, s35, 0xe000
	s_nop 0
	global_load_lds_dwordx4 v[214:215], off
	s_waitcnt vmcnt(8)
	s_waitcnt lgkmcnt(0)
	s_barrier
	s_setprio 1
	s_waitcnt lgkmcnt(0)
	v_mfma_f32_16x16x32_bf16 v[124:127], v[140:143], v[172:175], 0
	v_mfma_f32_16x16x32_bf16 v[116:119], v[148:151], v[172:175], 0
	v_mfma_f32_16x16x32_bf16 v[108:111], v[140:143], v[180:183], 0
	v_mfma_f32_16x16x32_bf16 v[100:103], v[148:151], v[180:183], 0
	v_mfma_f32_16x16x32_bf16 v[92:95], v[140:143], v[188:191], 0
	v_mfma_f32_16x16x32_bf16 v[84:87], v[148:151], v[188:191], 0
	v_mfma_f32_16x16x32_bf16 v[76:79], v[140:143], v[206:209], 0
	v_mfma_f32_16x16x32_bf16 v[68:71], v[148:151], v[206:209], 0
	v_mfma_f32_16x16x32_bf16 v[124:127], v[144:147], v[176:179], v[124:127]
	v_mfma_f32_16x16x32_bf16 v[116:119], v[152:155], v[176:179], v[116:119]
	v_mfma_f32_16x16x32_bf16 v[108:111], v[144:147], v[184:187], v[108:111]
	v_mfma_f32_16x16x32_bf16 v[100:103], v[152:155], v[184:187], v[100:103]
	v_mfma_f32_16x16x32_bf16 v[92:95], v[144:147], v[192:195], v[92:95]
	v_mfma_f32_16x16x32_bf16 v[84:87], v[152:155], v[192:195], v[84:87]
	v_mfma_f32_16x16x32_bf16 v[76:79], v[144:147], v[210:213], v[76:79]
	v_mfma_f32_16x16x32_bf16 v[68:71], v[152:155], v[210:213], v[68:71]
	s_setprio 0
	s_setprio 1
	v_mfma_f32_16x16x32_bf16 v[120:123], v[156:159], v[172:175], 0
	v_mfma_f32_16x16x32_bf16 v[112:115], v[164:167], v[172:175], 0
	v_mfma_f32_16x16x32_bf16 v[104:107], v[156:159], v[180:183], 0
	v_mfma_f32_16x16x32_bf16 v[96:99], v[164:167], v[180:183], 0
	v_mfma_f32_16x16x32_bf16 v[88:91], v[156:159], v[188:191], 0
	v_mfma_f32_16x16x32_bf16 v[80:83], v[164:167], v[188:191], 0
	v_mfma_f32_16x16x32_bf16 v[72:75], v[156:159], v[206:209], 0
	v_mfma_f32_16x16x32_bf16 v[64:67], v[164:167], v[206:209], 0
	v_mfma_f32_16x16x32_bf16 v[120:123], v[160:163], v[176:179], v[120:123]
	v_mfma_f32_16x16x32_bf16 v[112:115], v[168:171], v[176:179], v[112:115]
	v_mfma_f32_16x16x32_bf16 v[104:107], v[160:163], v[184:187], v[104:107]
	v_mfma_f32_16x16x32_bf16 v[96:99], v[168:171], v[184:187], v[96:99]
	v_mfma_f32_16x16x32_bf16 v[88:91], v[160:163], v[192:195], v[88:91]
	v_mfma_f32_16x16x32_bf16 v[80:83], v[168:171], v[192:195], v[80:83]
	v_mfma_f32_16x16x32_bf16 v[72:75], v[160:163], v[210:213], v[72:75]
	v_mfma_f32_16x16x32_bf16 v[64:67], v[168:171], v[210:213], v[64:67]
	s_setprio 0
	s_barrier
	s_add_i32 s50, s50, s34
	v_lshl_add_u64 v[214:215], s[24:25], 0, v[196:197]
	s_mov_b32 m0, s50
	ds_read_b128 v[172:175], v139 offset:16384
	ds_read_b128 v[176:179], v139 offset:17408
	ds_read_b128 v[180:183], v139 offset:18432
	ds_read_b128 v[184:187], v139 offset:19456
	ds_read_b128 v[188:191], v139 offset:20480
	ds_read_b128 v[192:195], v139 offset:21504
	ds_read_b128 v[206:209], v139 offset:22528
	ds_read_b128 v[210:213], v139 offset:23552
	global_load_lds_dwordx4 v[214:215], off
	s_add_i32 m0, s50, 0x2000
	s_add_u32 s50, s24, 0x40000
	v_lshl_add_u64 v[216:217], s[24:25], 0, v[132:133]
	s_addc_u32 s51, s25, 0
	s_add_i32 s52, s52, s34
	global_load_lds_dwordx4 v[216:217], off
	v_lshl_add_u64 v[218:219], s[50:51], 0, v[196:197]
	s_mov_b32 m0, s52
	v_lshl_add_u64 v[220:221], s[26:27], 0, v[130:131]
	global_load_lds_dwordx4 v[218:219], off
	v_lshl_add_u64 v[218:219], s[50:51], 0, v[132:133]
	s_add_i32 m0, s52, 0x2000
	s_nop 0
	global_load_lds_dwordx4 v[218:219], off
	v_lshl_add_u64 v[218:219], s[26:27], 0, v[128:129]
	s_mov_b32 m0, s35
	s_nop 0
	global_load_lds_dwordx4 v[218:219], off
	s_mov_b32 m0, s36
	s_nop 0
	global_load_lds_dwordx4 v[220:221], off
	s_waitcnt vmcnt(8)
	s_waitcnt lgkmcnt(0)
	s_barrier
; #define PG8_STAGE(bufoff, gbase, voff) do { _Pragma("unroll") for (int _i = 0; _i < 2; ++_i) \
;         __builtin_amdgcn_global_load_lds((const unsigned*)((const char*)(gbase) + (voff)[_i]), (PG8_LAS unsigned*)(lds + (bufoff) + ldsw + _i * 8192), 16, 0, 0); } while (0)
; #define PG8_LDA(dst, b, h) do { _Pragma("unroll") for (int m = 0; m < 4; ++m) _Pragma("unroll") for (int k = 0; k < 2; ++k) dst[m][k] = *(const PG8_LAS bf16x8*)(lds + PG8_SA(b, h) + aoff + m * 2048 + k * 1024); } while (0)
; #define PG8_LDB(dst, b, h) do { _Pragma("unroll") for (int n = 0; n < 2; ++n) _Pragma("unroll") for (int k = 0; k < 2; ++k) dst[n][k] = *(const PG8_LAS bf16x8*)(lds + PG8_SB(b, h) + boff + n * 2048 + k * 1024); } while (0)
; #define PG8_MMA(ai, bj, At, Bt) do { __builtin_amdgcn_s_setprio(1); _Pragma("unroll") for (int m = 0; m < 4; ++m) _Pragma("unroll") for (int n = 0; n < 2; ++n) _Pragma("unroll") for (int k = 0; k < 2; ++k) \
;         acc[ai][bj][m][n] = __builtin_amdgcn_mfma_f32_16x16x32_bf16(Bt[n][k], At[m][k], acc[ai][bj][m][n], 0, 0, 0); __builtin_amdgcn_s_setprio(0); } while (0)
; #define PG8_WAIT_V(n) asm volatile("s_waitcnt vmcnt(" #n ")" ::: "memory")
; #define PG8_WAIT_L(n) asm volatile("s_waitcnt lgkmcnt(" #n ")" ::: "memory")
; #define PG8_BAR __builtin_amdgcn_s_barrier()
; #define PG8_SCHED __builtin_amdgcn_sched_barrier(0)
; template <class Epi, class Sched, bool ALIGN_EPI = false, bool SP2 = false>
; __device__ __forceinline__ void gemm_phase(PG8_LAS unsigned char* lds, const Gemm g, const Sched& S, const Epi& E, int wave_s_) {
;     ...
;             PG8_WAIT_V(8); PG8_WAIT_L(0); PG8_BAR; PG8_MMA(1, 0, At, B0); PG8_MMA(1, 1, At, B1); PG8_BAR; PG8_SCHED;
;             PG8_LDB(B0, 1, 0); PG8_LDB(B1, 1, 1); PG8_SCHED; PG8_LDA(At, 1, 0); PG8_STAGE(PG8_SA(0, 1), a2 + hstep, voffA);
;             PG8_WAIT_V(8); PG8_WAIT_L(0); PG8_BAR; PG8_MMA(0, 0, At, B0); PG8_MMA(0, 1, At, B1); PG8_BAR; PG8_SCHED;
	s_setprio 1
	s_waitcnt lgkmcnt(0)
	v_mfma_f32_16x16x32_bf16 v[60:63], v[140:143], v[172:175], 0
	v_mfma_f32_16x16x32_bf16 v[52:55], v[148:151], v[172:175], 0
	v_mfma_f32_16x16x32_bf16 v[44:47], v[140:143], v[180:183], 0
	v_mfma_f32_16x16x32_bf16 v[36:39], v[148:151], v[180:183], 0
	v_mfma_f32_16x16x32_bf16 v[28:31], v[140:143], v[188:191], 0
	v_mfma_f32_16x16x32_bf16 v[20:23], v[148:151], v[188:191], 0
	v_mfma_f32_16x16x32_bf16 v[12:15], v[140:143], v[206:209], 0
	v_mfma_f32_16x16x32_bf16 v[4:7], v[148:151], v[206:209], 0
	v_mfma_f32_16x16x32_bf16 v[60:63], v[144:147], v[176:179], v[60:63]
	v_mfma_f32_16x16x32_bf16 v[52:55], v[152:155], v[176:179], v[52:55]
	v_mfma_f32_16x16x32_bf16 v[44:47], v[144:147], v[184:187], v[44:47]
	v_mfma_f32_16x16x32_bf16 v[36:39], v[152:155], v[184:187], v[36:39]
	v_mfma_f32_16x16x32_bf16 v[28:31], v[144:147], v[192:195], v[28:31]
	v_mfma_f32_16x16x32_bf16 v[20:23], v[152:155], v[192:195], v[20:23]
	v_mfma_f32_16x16x32_bf16 v[12:15], v[144:147], v[210:213], v[12:15]
	v_mfma_f32_16x16x32_bf16 v[4:7], v[152:155], v[210:213], v[4:7]
	s_setprio 0
	s_setprio 1
	v_mfma_f32_16x16x32_bf16 v[56:59], v[156:159], v[172:175], 0
	v_mfma_f32_16x16x32_bf16 v[48:51], v[164:167], v[172:175], 0
	v_mfma_f32_16x16x32_bf16 v[40:43], v[156:159], v[180:183], 0
	v_mfma_f32_16x16x32_bf16 v[32:35], v[164:167], v[180:183], 0
	v_mfma_f32_16x16x32_bf16 v[24:27], v[156:159], v[188:191], 0
	v_mfma_f32_16x16x32_bf16 v[16:19], v[164:167], v[188:191], 0
	v_mfma_f32_16x16x32_bf16 v[8:11], v[156:159], v[206:209], 0
	v_mfma_f32_16x16x32_bf16 v[0:3], v[164:167], v[206:209], 0
	v_mfma_f32_16x16x32_bf16 v[56:59], v[160:163], v[176:179], v[56:59]
	v_mfma_f32_16x16x32_bf16 v[48:51], v[168:171], v[176:179], v[48:51]
	v_mfma_f32_16x16x32_bf16 v[40:43], v[160:163], v[184:187], v[40:43]
	v_mfma_f32_16x16x32_bf16 v[32:35], v[168:171], v[184:187], v[32:35]
	v_mfma_f32_16x16x32_bf16 v[24:27], v[160:163], v[192:195], v[24:27]
	v_mfma_f32_16x16x32_bf16 v[16:19], v[168:171], v[192:195], v[16:19]
	v_mfma_f32_16x16x32_bf16 v[8:11], v[160:163], v[210:213], v[8:11]
	v_mfma_f32_16x16x32_bf16 v[0:3], v[168:171], v[210:213], v[0:3]
	s_setprio 0
	s_barrier
	s_add_i32 s50, 0, 0x18000
	s_add_i32 s51, 0, 0x1c000
	v_add_u32_e32 v152, s50, v138
	v_add_u32_e32 v168, s51, v138
	ds_read_b128 v[140:143], v152
	ds_read_b128 v[144:147], v152 offset:1024
	ds_read_b128 v[148:151], v152 offset:2048
	ds_read_b128 v[152:155], v152 offset:3072
	ds_read_b128 v[156:159], v168
	ds_read_b128 v[160:163], v168 offset:1024
	ds_read_b128 v[164:167], v168 offset:2048
	ds_read_b128 v[168:171], v168 offset:3072
	s_add_u32 s26, s26, 0x40000
	s_addc_u32 s27, s27, 0
	s_mov_b32 m0, s37
	v_lshl_add_u64 v[222:223], s[26:27], 0, v[128:129]
	ds_read_b128 v[172:175], v139 offset:32768
	ds_read_b128 v[176:179], v139 offset:33792
	ds_read_b128 v[180:183], v139 offset:34816
	ds_read_b128 v[184:187], v139 offset:35840
	ds_read_b128 v[188:191], v139 offset:36864
	ds_read_b128 v[192:195], v139 offset:37888
	ds_read_b128 v[206:209], v139 offset:38912
	ds_read_b128 v[210:213], v139 offset:39936
	global_load_lds_dwordx4 v[222:223], off
	v_lshl_add_u64 v[222:223], s[26:27], 0, v[130:131]
	s_mov_b32 m0, s38
	s_nop 0
	global_load_lds_dwordx4 v[222:223], off
	s_waitcnt vmcnt(8)
	s_waitcnt lgkmcnt(0)
	s_barrier
	s_setprio 1
	s_waitcnt lgkmcnt(0)
	v_mfma_f32_16x16x32_bf16 v[124:127], v[140:143], v[172:175], v[124:127]
	v_mfma_f32_16x16x32_bf16 v[116:119], v[148:151], v[172:175], v[116:119]
	v_mfma_f32_16x16x32_bf16 v[108:111], v[140:143], v[180:183], v[108:111]
	v_mfma_f32_16x16x32_bf16 v[100:103], v[148:151], v[180:183], v[100:103]
	v_mfma_f32_16x16x32_bf16 v[92:95], v[140:143], v[188:191], v[92:95]
	v_mfma_f32_16x16x32_bf16 v[84:87], v[148:151], v[188:191], v[84:87]
	v_mfma_f32_16x16x32_bf16 v[76:79], v[140:143], v[206:209], v[76:79]
	v_mfma_f32_16x16x32_bf16 v[68:71], v[148:151], v[206:209], v[68:71]
	v_mfma_f32_16x16x32_bf16 v[124:127], v[144:147], v[176:179], v[124:127]
	v_mfma_f32_16x16x32_bf16 v[116:119], v[152:155], v[176:179], v[116:119]
	v_mfma_f32_16x16x32_bf16 v[108:111], v[144:147], v[184:187], v[108:111]
	v_mfma_f32_16x16x32_bf16 v[100:103], v[152:155], v[184:187], v[100:103]
	v_mfma_f32_16x16x32_bf16 v[92:95], v[144:147], v[192:195], v[92:95]
	v_mfma_f32_16x16x32_bf16 v[84:87], v[152:155], v[192:195], v[84:87]
	v_mfma_f32_16x16x32_bf16 v[76:79], v[144:147], v[210:213], v[76:79]
	v_mfma_f32_16x16x32_bf16 v[68:71], v[152:155], v[210:213], v[68:71]
	s_setprio 0
	s_setprio 1
	v_mfma_f32_16x16x32_bf16 v[120:123], v[156:159], v[172:175], v[120:123]
	v_mfma_f32_16x16x32_bf16 v[112:115], v[164:167], v[172:175], v[112:115]
	v_mfma_f32_16x16x32_bf16 v[104:107], v[156:159], v[180:183], v[104:107]
	v_mfma_f32_16x16x32_bf16 v[96:99], v[164:167], v[180:183], v[96:99]
	v_mfma_f32_16x16x32_bf16 v[88:91], v[156:159], v[188:191], v[88:91]
	v_mfma_f32_16x16x32_bf16 v[80:83], v[164:167], v[188:191], v[80:83]
	v_mfma_f32_16x16x32_bf16 v[72:75], v[156:159], v[206:209], v[72:75]
	v_mfma_f32_16x16x32_bf16 v[64:67], v[164:167], v[206:209], v[64:67]
	v_mfma_f32_16x16x32_bf16 v[120:123], v[160:163], v[176:179], v[120:123]
	v_mfma_f32_16x16x32_bf16 v[112:115], v[168:171], v[176:179], v[112:115]
	v_mfma_f32_16x16x32_bf16 v[104:107], v[160:163], v[184:187], v[104:107]
	v_mfma_f32_16x16x32_bf16 v[96:99], v[168:171], v[184:187], v[96:99]
	v_mfma_f32_16x16x32_bf16 v[88:91], v[160:163], v[192:195], v[88:91]
	v_mfma_f32_16x16x32_bf16 v[80:83], v[168:171], v[192:195], v[80:83]
	v_mfma_f32_16x16x32_bf16 v[72:75], v[160:163], v[210:213], v[72:75]
	v_mfma_f32_16x16x32_bf16 v[64:67], v[168:171], v[210:213], v[64:67]
	s_setprio 0
	s_barrier
; #define PG8_STAGE(bufoff, gbase, voff) do { _Pragma("unroll") for (int _i = 0; _i < 2; ++_i) \
;         __builtin_amdgcn_global_load_lds((const unsigned*)((const char*)(gbase) + (voff)[_i]), (PG8_LAS unsigned*)(lds + (bufoff) + ldsw + _i * 8192), 16, 0, 0); } while (0)
; #define PG8_LDA(dst, b, h) do { _Pragma("unroll") for (int m = 0; m < 4; ++m) _Pragma("unroll") for (int k = 0; k < 2; ++k) dst[m][k] = *(const PG8_LAS bf16x8*)(lds + PG8_SA(b, h) + aoff + m * 2048 + k * 1024); } while (0)
; #define PG8_MMA(ai, bj, At, Bt) do { __builtin_amdgcn_s_setprio(1); _Pragma("unroll") for (int m = 0; m < 4; ++m) _Pragma("unroll") for (int n = 0; n < 2; ++n) _Pragma("unroll") for (int k = 0; k < 2; ++k) \
;         acc[ai][bj][m][n] = __builtin_amdgcn_mfma_f32_16x16x32_bf16(Bt[n][k], At[m][k], acc[ai][bj][m][n], 0, 0, 0); __builtin_amdgcn_s_setprio(0); } while (0)
; #define PG8_WAIT_V(n) asm volatile("s_waitcnt vmcnt(" #n ")" ::: "memory")
; #define PG8_WAIT_L(n) asm volatile("s_waitcnt lgkmcnt(" #n ")" ::: "memory")
; #define PG8_BAR __builtin_amdgcn_s_barrier()
; #define PG8_SCHED __builtin_amdgcn_sched_barrier(0)
; template <class Epi, class Sched, bool ALIGN_EPI = false, bool SP2 = false>
; __device__ __forceinline__ void gemm_phase(PG8_LAS unsigned char* lds, const Gemm g, const Sched& S, const Epi& E, int wave_s_) {
;     ...
;         for (int t = 0; t < nt; t += 2) {
;     ...
;             PG8_LDA(At, 1, 1); PG8_STAGE(PG8_SB(1, 0), b3, voffB); PG8_STAGE(PG8_SB(1, 1), b3 + hstep, voffB); PG8_STAGE(PG8_SA(1, 0), a3, voffA);
;             PG8_WAIT_V(8); PG8_WAIT_L(0); PG8_BAR; PG8_MMA(1, 0, At, B0); PG8_MMA(1, 1, At, B1); PG8_BAR; PG8_SCHED;
	s_add_i32 s26, s50, s34
	v_lshl_add_u64 v[214:215], v[214:215], 0, s[76:77]
	s_mov_b32 m0, s26
	ds_read_b128 v[172:175], v139 offset:49152
	ds_read_b128 v[176:179], v139 offset:50176
	ds_read_b128 v[180:183], v139 offset:51200
	ds_read_b128 v[184:187], v139 offset:52224
	ds_read_b128 v[188:191], v139 offset:53248
	ds_read_b128 v[192:195], v139 offset:54272
	ds_read_b128 v[206:209], v139 offset:55296
	ds_read_b128 v[210:213], v139 offset:56320
	global_load_lds_dwordx4 v[214:215], off
	s_add_i32 m0, s26, 0x2000
	s_add_u32 s24, s24, 0x40080
	v_lshl_add_u64 v[214:215], v[216:217], 0, s[76:77]
	s_addc_u32 s25, s25, 0
	s_add_i32 s26, s51, s34
	global_load_lds_dwordx4 v[214:215], off
	v_lshl_add_u64 v[214:215], s[24:25], 0, v[196:197]
	s_mov_b32 m0, s26
	s_nop 0
	global_load_lds_dwordx4 v[214:215], off
	v_lshl_add_u64 v[214:215], s[24:25], 0, v[132:133]
	s_add_i32 m0, s26, 0x2000
	s_nop 0
	global_load_lds_dwordx4 v[214:215], off
	v_lshl_add_u64 v[214:215], v[218:219], 0, s[76:77]
	s_mov_b32 m0, s41
	s_nop 0
	global_load_lds_dwordx4 v[214:215], off
	v_lshl_add_u64 v[214:215], v[220:221], 0, s[76:77]
	s_mov_b32 m0, s42
	s_nop 0
	global_load_lds_dwordx4 v[214:215], off
	s_waitcnt vmcnt(8)
	s_waitcnt lgkmcnt(0)
	s_barrier
	s_setprio 1
	s_waitcnt lgkmcnt(0)
	v_mfma_f32_16x16x32_bf16 v[60:63], v[140:143], v[172:175], v[60:63]
	v_mfma_f32_16x16x32_bf16 v[52:55], v[148:151], v[172:175], v[52:55]
	v_mfma_f32_16x16x32_bf16 v[44:47], v[140:143], v[180:183], v[44:47]
	v_mfma_f32_16x16x32_bf16 v[36:39], v[148:151], v[180:183], v[36:39]
	v_mfma_f32_16x16x32_bf16 v[28:31], v[140:143], v[188:191], v[28:31]
	v_mfma_f32_16x16x32_bf16 v[20:23], v[148:151], v[188:191], v[20:23]
	v_mfma_f32_16x16x32_bf16 v[12:15], v[140:143], v[206:209], v[12:15]
	v_mfma_f32_16x16x32_bf16 v[4:7], v[148:151], v[206:209], v[4:7]
	v_mfma_f32_16x16x32_bf16 v[60:63], v[144:147], v[176:179], v[60:63]
	v_mfma_f32_16x16x32_bf16 v[52:55], v[152:155], v[176:179], v[52:55]
	v_mfma_f32_16x16x32_bf16 v[44:47], v[144:147], v[184:187], v[44:47]
	v_mfma_f32_16x16x32_bf16 v[36:39], v[152:155], v[184:187], v[36:39]
	v_mfma_f32_16x16x32_bf16 v[28:31], v[144:147], v[192:195], v[28:31]
	v_mfma_f32_16x16x32_bf16 v[20:23], v[152:155], v[192:195], v[20:23]
	v_mfma_f32_16x16x32_bf16 v[12:15], v[144:147], v[210:213], v[12:15]
	v_mfma_f32_16x16x32_bf16 v[4:7], v[152:155], v[210:213], v[4:7]
	s_setprio 0
	s_setprio 1
	v_mfma_f32_16x16x32_bf16 v[56:59], v[156:159], v[172:175], v[56:59]
	v_mfma_f32_16x16x32_bf16 v[48:51], v[164:167], v[172:175], v[48:51]
	v_mfma_f32_16x16x32_bf16 v[40:43], v[156:159], v[180:183], v[40:43]
	v_mfma_f32_16x16x32_bf16 v[32:35], v[164:167], v[180:183], v[32:35]
	v_mfma_f32_16x16x32_bf16 v[24:27], v[156:159], v[188:191], v[24:27]
	v_mfma_f32_16x16x32_bf16 v[16:19], v[164:167], v[188:191], v[16:19]
	v_mfma_f32_16x16x32_bf16 v[8:11], v[156:159], v[206:209], v[8:11]
	v_mfma_f32_16x16x32_bf16 v[0:3], v[164:167], v[206:209], v[0:3]
	v_mfma_f32_16x16x32_bf16 v[56:59], v[160:163], v[176:179], v[56:59]
	v_mfma_f32_16x16x32_bf16 v[48:51], v[168:171], v[176:179], v[48:51]
	v_mfma_f32_16x16x32_bf16 v[40:43], v[160:163], v[184:187], v[40:43]
	v_mfma_f32_16x16x32_bf16 v[32:35], v[168:171], v[184:187], v[32:35]
	v_mfma_f32_16x16x32_bf16 v[24:27], v[160:163], v[192:195], v[24:27]
	v_mfma_f32_16x16x32_bf16 v[16:19], v[168:171], v[192:195], v[16:19]
	v_mfma_f32_16x16x32_bf16 v[8:11], v[160:163], v[210:213], v[8:11]
	v_mfma_f32_16x16x32_bf16 v[0:3], v[168:171], v[210:213], v[0:3]
	s_setprio 0
	s_barrier
	s_add_i32 s49, s49, 2
	s_add_u32 s17, s17, 0x100
	s_addc_u32 s48, s48, 0
	s_add_u32 s22, s22, 0x100
	s_addc_u32 s23, s23, 0
	s_cmp_gt_u32 s49, 13
	s_cbranch_scc0 .LBB0_207
	s_branch .Lpeel_exit_0

; #define PG8_BAR __builtin_amdgcn_s_barrier()
; template <class Epi, class Sched, bool ALIGN_EPI = false, bool SP2 = false>
; __device__ __forceinline__ void gemm_phase(PG8_LAS unsigned char* lds, const Gemm g, const Sched& S, const Epi& E, int wave_s_) {
;     ...
;         if constexpr (ALIGN_EPI) { if (wr == 0) PG8_BAR; }
.Lpeel_exit_0:
	s_and_b64 vcc, exec, s[14:15]
	s_cbranch_vccz .LBB0_210
	s_barrier

; #define PG8_STAGE(bufoff, gbase, voff) do { _Pragma("unroll") for (int _i = 0; _i < 2; ++_i) \
;         __builtin_amdgcn_global_load_lds((const unsigned*)((const char*)(gbase) + (voff)[_i]), (PG8_LAS unsigned*)(lds + (bufoff) + ldsw + _i * 8192), 16, 0, 0); } while (0)
; #define PG8_LDA(dst, b, h) do { _Pragma("unroll") for (int m = 0; m < 4; ++m) _Pragma("unroll") for (int k = 0; k < 2; ++k) dst[m][k] = *(const PG8_LAS bf16x8*)(lds + PG8_SA(b, h) + aoff + m * 2048 + k * 1024); } while (0)
; #define PG8_LDB(dst, b, h) do { _Pragma("unroll") for (int n = 0; n < 2; ++n) _Pragma("unroll") for (int k = 0; k < 2; ++k) dst[n][k] = *(const PG8_LAS bf16x8*)(lds + PG8_SB(b, h) + boff + n * 2048 + k * 1024); } while (0)
; #define PG8_WAIT_V(n) asm volatile("s_waitcnt vmcnt(" #n ")" ::: "memory")
; #define PG8_WAIT_L(n) asm volatile("s_waitcnt lgkmcnt(" #n ")" ::: "memory")
; #define PG8_BAR __builtin_amdgcn_s_barrier()
; #define PG8_SCHED __builtin_amdgcn_sched_barrier(0)
;     __device__ __forceinline__ int nt_of(const Unit& u) const { return (u.pm >> 12) ? ktper : kt; }
; template <class Epi, class Sched, bool ALIGN_EPI = false, bool SP2 = false>
; __device__ __forceinline__ void gemm_phase(PG8_LAS unsigned char* lds, const Gemm g, const Sched& S, const Epi& E, int wave_s_) {
;     ...
;         const int nt = S.nt_of(cur);
;         for (int t = 0; t < nt; t += 2) {
;             const bool last = (t == nt - 2);
;             const char* a1 = cA + (size_t)(t + 1) * kstep;
;             const char* a2 = last ? nA : cA + (size_t)(t + 2) * kstep; const char* b2 = last ? nB : cB + (size_t)(t + 2) * kstep;
;             const char* a3 = a2 + kstep; const char* b3 = b2 + kstep;
;             if (last && has_next) S.a_ready(nxt);
;             if constexpr (SP2) {
;             PG8_LDB(B0, 0, 0); PG8_LDB(B1, 0, 1); PG8_SCHED; PG8_LDA(At, 0, 0); PG8_STAGE(PG8_SA(1, 1), a1 + hstep, voffA);
;             PG8_WAIT_V(8); PG8_WAIT_L(0); PG8_BAR; PG8_MMA(0, 0, At, B0); PG8_MMA(0, 1, At, B1); PG8_BAR; PG8_SCHED;
;             PG8_LDA(At, 0, 1); PG8_STAGE(PG8_SB(0, 0), b2, voffB); PG8_STAGE(PG8_SB(0, 1), b2 + hstep, voffB); PG8_STAGE(PG8_SA(0, 0), a2, voffA);
;             PG8_WAIT_V(8); PG8_WAIT_L(0); PG8_BAR; PG8_MMA(1, 0, At, B0); PG8_MMA(1, 1, At, B1); PG8_BAR; PG8_SCHED;
.LBB0_297:
	s_cmpk_gt_u32 s57, 0xfff
	s_cselect_b64 s[30:31], -1, 0
	s_cmpk_lt_u32 s57, 0x1000
	s_cselect_b64 s[8:9], -1, 0
	s_and_b64 s[34:35], s[8:9], exec
	s_cselect_b32 s59, 44, 4
	s_add_i32 s60, s59, -2
	s_add_u32 s61, s12, 0x100
	v_mov_b32_e32 v0, 0
	s_addc_u32 s62, s13, 0
	s_mov_b32 s34, 0
	s_add_i32 s63, s34, 2
	s_add_u32 s12, s10, 0x100
	s_addc_u32 s13, s11, 0
	s_add_i32 s64, 0, 0x10000
	s_cmp_eq_u32 s60, s34
	s_cselect_b32 s37, s27, s13
	s_cselect_b32 s36, s26, s12
	s_cselect_b32 s35, s29, s62
	s_cselect_b32 s34, s28, s61
	s_add_i32 s65, 0, 0x14000
	v_add_u32_e32 v80, s64, v226
	v_add_u32_e32 v100, s65, v226
	ds_read_b128 v[64:67], v80
	ds_read_b128 v[68:71], v80 offset:1024
	ds_read_b128 v[76:79], v80 offset:2048
	ds_read_b128 v[80:83], v80 offset:3072
	ds_read_b128 v[88:91], v100
	ds_read_b128 v[92:95], v100 offset:1024
	ds_read_b128 v[96:99], v100 offset:2048
	ds_read_b128 v[100:103], v100 offset:3072
	v_lshl_add_u64 v[208:209], s[10:11], 0, v[206:207]
	s_add_i32 m0, s42, 0xc000
	ds_read_b128 v[160:163], v227
	ds_read_b128 v[164:167], v227 offset:1024
	ds_read_b128 v[168:171], v227 offset:2048
	ds_read_b128 v[172:175], v227 offset:3072
	ds_read_b128 v[176:179], v227 offset:4096
	ds_read_b128 v[180:183], v227 offset:5120
	ds_read_b128 v[184:187], v227 offset:6144
	ds_read_b128 v[188:191], v227 offset:7168
	global_load_lds_dwordx4 v[208:209], off
	v_lshl_add_u64 v[208:209], s[10:11], 0, v[194:195]
	s_add_i32 m0, s42, 0xe000
	s_nop 0
	global_load_lds_dwordx4 v[208:209], off
	s_waitcnt vmcnt(8)
	s_waitcnt lgkmcnt(0)
	s_barrier
	s_setprio 1
	s_waitcnt lgkmcnt(0)
	v_mfma_f32_16x16x32_bf16 v[156:159], v[64:67], v[160:163], 0
	v_mfma_f32_16x16x32_bf16 v[152:155], v[76:79], v[160:163], 0
	v_mfma_f32_16x16x32_bf16 v[144:147], v[64:67], v[168:171], 0
	v_mfma_f32_16x16x32_bf16 v[136:139], v[76:79], v[168:171], 0
	v_mfma_f32_16x16x32_bf16 v[124:127], v[64:67], v[176:179], 0
	v_mfma_f32_16x16x32_bf16 v[120:123], v[76:79], v[176:179], 0
	v_mfma_f32_16x16x32_bf16 v[112:115], v[64:67], v[184:187], 0
	v_mfma_f32_16x16x32_bf16 v[104:107], v[76:79], v[184:187], 0
	v_mfma_f32_16x16x32_bf16 v[156:159], v[68:71], v[164:167], v[156:159]
	v_mfma_f32_16x16x32_bf16 v[152:155], v[80:83], v[164:167], v[152:155]
	v_mfma_f32_16x16x32_bf16 v[144:147], v[68:71], v[172:175], v[144:147]
	v_mfma_f32_16x16x32_bf16 v[136:139], v[80:83], v[172:175], v[136:139]
	v_mfma_f32_16x16x32_bf16 v[124:127], v[68:71], v[180:183], v[124:127]
	v_mfma_f32_16x16x32_bf16 v[120:123], v[80:83], v[180:183], v[120:123]
	v_mfma_f32_16x16x32_bf16 v[112:115], v[68:71], v[188:191], v[112:115]
	v_mfma_f32_16x16x32_bf16 v[104:107], v[80:83], v[188:191], v[104:107]
	s_setprio 0
	s_setprio 1
	v_mfma_f32_16x16x32_bf16 v[148:151], v[88:91], v[160:163], 0
	v_mfma_f32_16x16x32_bf16 v[140:143], v[96:99], v[160:163], 0
	v_mfma_f32_16x16x32_bf16 v[132:135], v[88:91], v[168:171], 0
	v_mfma_f32_16x16x32_bf16 v[128:131], v[96:99], v[168:171], 0
	v_mfma_f32_16x16x32_bf16 v[116:119], v[88:91], v[176:179], 0
	v_mfma_f32_16x16x32_bf16 v[108:111], v[96:99], v[176:179], 0
	v_mfma_f32_16x16x32_bf16 v[84:87], v[88:91], v[184:187], 0
	v_mfma_f32_16x16x32_bf16 v[72:75], v[96:99], v[184:187], 0
	v_mfma_f32_16x16x32_bf16 v[148:151], v[92:95], v[164:167], v[148:151]
	v_mfma_f32_16x16x32_bf16 v[140:143], v[100:103], v[164:167], v[140:143]
	v_mfma_f32_16x16x32_bf16 v[132:135], v[92:95], v[172:175], v[132:135]
	v_mfma_f32_16x16x32_bf16 v[128:131], v[100:103], v[172:175], v[128:131]
	v_mfma_f32_16x16x32_bf16 v[116:119], v[92:95], v[180:183], v[116:119]
	v_mfma_f32_16x16x32_bf16 v[108:111], v[100:103], v[180:183], v[108:111]
	v_mfma_f32_16x16x32_bf16 v[84:87], v[92:95], v[188:191], v[84:87]
	v_mfma_f32_16x16x32_bf16 v[72:75], v[100:103], v[188:191], v[72:75]
	s_setprio 0
	s_barrier
	s_add_i32 s10, s64, s41
	v_lshl_add_u64 v[208:209], s[34:35], 0, v[196:197]
	s_mov_b32 m0, s10
	ds_read_b128 v[160:163], v227 offset:16384
	ds_read_b128 v[164:167], v227 offset:17408
	ds_read_b128 v[168:171], v227 offset:18432
	ds_read_b128 v[172:175], v227 offset:19456
	ds_read_b128 v[176:179], v227 offset:20480
	ds_read_b128 v[180:183], v227 offset:21504
	ds_read_b128 v[184:187], v227 offset:22528
	ds_read_b128 v[188:191], v227 offset:23552
	global_load_lds_dwordx4 v[208:209], off
	s_add_i32 m0, s10, 0x2000
	s_add_u32 s10, s34, 0xb0000
	v_lshl_add_u64 v[210:211], s[34:35], 0, v[192:193]
	s_addc_u32 s11, s35, 0
	s_add_i32 s64, s65, s41
	global_load_lds_dwordx4 v[210:211], off
	v_lshl_add_u64 v[212:213], s[10:11], 0, v[196:197]
	s_mov_b32 m0, s64
	v_lshl_add_u64 v[214:215], s[36:37], 0, v[192:193]
	global_load_lds_dwordx4 v[212:213], off
	v_lshl_add_u64 v[212:213], s[10:11], 0, v[192:193]
	s_add_i32 m0, s64, 0x2000
	s_nop 0
	global_load_lds_dwordx4 v[212:213], off
	v_lshl_add_u64 v[212:213], s[36:37], 0, v[196:197]
	s_mov_b32 m0, s42
	s_nop 0
	global_load_lds_dwordx4 v[212:213], off
	s_mov_b32 m0, s43
	s_nop 0
	global_load_lds_dwordx4 v[214:215], off
	s_waitcnt vmcnt(8)
	s_waitcnt lgkmcnt(0)
	s_barrier
; #define PG8_STAGE(bufoff, gbase, voff) do { _Pragma("unroll") for (int _i = 0; _i < 2; ++_i) \
;         __builtin_amdgcn_global_load_lds((const unsigned*)((const char*)(gbase) + (voff)[_i]), (PG8_LAS unsigned*)(lds + (bufoff) + ldsw + _i * 8192), 16, 0, 0); } while (0)
; #define PG8_LDA(dst, b, h) do { _Pragma("unroll") for (int m = 0; m < 4; ++m) _Pragma("unroll") for (int k = 0; k < 2; ++k) dst[m][k] = *(const PG8_LAS bf16x8*)(lds + PG8_SA(b, h) + aoff + m * 2048 + k * 1024); } while (0)
; #define PG8_LDB(dst, b, h) do { _Pragma("unroll") for (int n = 0; n < 2; ++n) _Pragma("unroll") for (int k = 0; k < 2; ++k) dst[n][k] = *(const PG8_LAS bf16x8*)(lds + PG8_SB(b, h) + boff + n * 2048 + k * 1024); } while (0)
; #define PG8_MMA(ai, bj, At, Bt) do { __builtin_amdgcn_s_setprio(1); _Pragma("unroll") for (int m = 0; m < 4; ++m) _Pragma("unroll") for (int n = 0; n < 2; ++n) _Pragma("unroll") for (int k = 0; k < 2; ++k) \
;         acc[ai][bj][m][n] = __builtin_amdgcn_mfma_f32_16x16x32_bf16(Bt[n][k], At[m][k], acc[ai][bj][m][n], 0, 0, 0); __builtin_amdgcn_s_setprio(0); } while (0)
; #define PG8_WAIT_V(n) asm volatile("s_waitcnt vmcnt(" #n ")" ::: "memory")
; #define PG8_WAIT_L(n) asm volatile("s_waitcnt lgkmcnt(" #n ")" ::: "memory")
; #define PG8_BAR __builtin_amdgcn_s_barrier()
; #define PG8_SCHED __builtin_amdgcn_sched_barrier(0)
; template <class Epi, class Sched, bool ALIGN_EPI = false, bool SP2 = false>
; __device__ __forceinline__ void gemm_phase(PG8_LAS unsigned char* lds, const Gemm g, const Sched& S, const Epi& E, int wave_s_) {
;     ...
;             PG8_WAIT_V(8); PG8_WAIT_L(0); PG8_BAR; PG8_MMA(1, 0, At, B0); PG8_MMA(1, 1, At, B1); PG8_BAR; PG8_SCHED;
;             PG8_LDB(B0, 1, 0); PG8_LDB(B1, 1, 1); PG8_SCHED; PG8_LDA(At, 1, 0); PG8_STAGE(PG8_SA(0, 1), a2 + hstep, voffA);
;             PG8_WAIT_V(8); PG8_WAIT_L(0); PG8_BAR; PG8_MMA(0, 0, At, B0); PG8_MMA(0, 1, At, B1); PG8_BAR; PG8_SCHED;
	s_setprio 1
	s_waitcnt lgkmcnt(0)
	v_mfma_f32_16x16x32_bf16 v[60:63], v[64:67], v[160:163], 0
	v_mfma_f32_16x16x32_bf16 v[56:59], v[76:79], v[160:163], 0
	v_mfma_f32_16x16x32_bf16 v[48:51], v[64:67], v[168:171], 0
	v_mfma_f32_16x16x32_bf16 v[40:43], v[76:79], v[168:171], 0
	v_mfma_f32_16x16x32_bf16 v[28:31], v[64:67], v[176:179], 0
	v_mfma_f32_16x16x32_bf16 v[24:27], v[76:79], v[176:179], 0
	v_mfma_f32_16x16x32_bf16 v[16:19], v[64:67], v[184:187], 0
	v_mfma_f32_16x16x32_bf16 v[8:11], v[76:79], v[184:187], 0
	v_mfma_f32_16x16x32_bf16 v[60:63], v[68:71], v[164:167], v[60:63]
	v_mfma_f32_16x16x32_bf16 v[56:59], v[80:83], v[164:167], v[56:59]
	v_mfma_f32_16x16x32_bf16 v[48:51], v[68:71], v[172:175], v[48:51]
	v_mfma_f32_16x16x32_bf16 v[40:43], v[80:83], v[172:175], v[40:43]
	v_mfma_f32_16x16x32_bf16 v[28:31], v[68:71], v[180:183], v[28:31]
	v_mfma_f32_16x16x32_bf16 v[24:27], v[80:83], v[180:183], v[24:27]
	v_mfma_f32_16x16x32_bf16 v[16:19], v[68:71], v[188:191], v[16:19]
	v_mfma_f32_16x16x32_bf16 v[8:11], v[80:83], v[188:191], v[8:11]
	s_setprio 0
	s_setprio 1
	v_mfma_f32_16x16x32_bf16 v[52:55], v[88:91], v[160:163], 0
	v_mfma_f32_16x16x32_bf16 v[44:47], v[96:99], v[160:163], 0
	v_mfma_f32_16x16x32_bf16 v[36:39], v[88:91], v[168:171], 0
	v_mfma_f32_16x16x32_bf16 v[32:35], v[96:99], v[168:171], 0
	v_mfma_f32_16x16x32_bf16 v[20:23], v[88:91], v[176:179], 0
	v_mfma_f32_16x16x32_bf16 v[12:15], v[96:99], v[176:179], 0
	v_mfma_f32_16x16x32_bf16 v[4:7], v[88:91], v[184:187], 0
	v_mfma_f32_16x16x32_bf16 v[0:3], v[96:99], v[184:187], 0
	v_mfma_f32_16x16x32_bf16 v[52:55], v[92:95], v[164:167], v[52:55]
	v_mfma_f32_16x16x32_bf16 v[44:47], v[100:103], v[164:167], v[44:47]
	v_mfma_f32_16x16x32_bf16 v[36:39], v[92:95], v[172:175], v[36:39]
	v_mfma_f32_16x16x32_bf16 v[32:35], v[100:103], v[172:175], v[32:35]
	v_mfma_f32_16x16x32_bf16 v[20:23], v[92:95], v[180:183], v[20:23]
	v_mfma_f32_16x16x32_bf16 v[12:15], v[100:103], v[180:183], v[12:15]
	v_mfma_f32_16x16x32_bf16 v[4:7], v[92:95], v[188:191], v[4:7]
	v_mfma_f32_16x16x32_bf16 v[0:3], v[100:103], v[188:191], v[0:3]
	s_setprio 0
	s_barrier
	s_add_i32 s64, 0, 0x18000
	s_add_i32 s65, 0, 0x1c000
	v_add_u32_e32 v80, s64, v226
	v_add_u32_e32 v100, s65, v226
	ds_read_b128 v[64:67], v80
	ds_read_b128 v[68:71], v80 offset:1024
	ds_read_b128 v[76:79], v80 offset:2048
	ds_read_b128 v[80:83], v80 offset:3072
	ds_read_b128 v[88:91], v100
	ds_read_b128 v[92:95], v100 offset:1024
	ds_read_b128 v[96:99], v100 offset:2048
	ds_read_b128 v[100:103], v100 offset:3072
	s_add_u32 s10, s36, 0xb0000
	s_addc_u32 s11, s37, 0
	s_mov_b32 m0, s44
	v_lshl_add_u64 v[216:217], s[10:11], 0, v[196:197]
	ds_read_b128 v[160:163], v227 offset:32768
	ds_read_b128 v[164:167], v227 offset:33792
	ds_read_b128 v[168:171], v227 offset:34816
	ds_read_b128 v[172:175], v227 offset:35840
	ds_read_b128 v[176:179], v227 offset:36864
	ds_read_b128 v[180:183], v227 offset:37888
	ds_read_b128 v[184:187], v227 offset:38912
	ds_read_b128 v[188:191], v227 offset:39936
	global_load_lds_dwordx4 v[216:217], off
	v_lshl_add_u64 v[216:217], s[10:11], 0, v[192:193]
	s_mov_b32 m0, s45
	s_nop 0
	global_load_lds_dwordx4 v[216:217], off
	s_waitcnt vmcnt(8)
	s_waitcnt lgkmcnt(0)
	s_barrier
	s_setprio 1
	s_waitcnt lgkmcnt(0)
	v_mfma_f32_16x16x32_bf16 v[156:159], v[64:67], v[160:163], v[156:159]
	v_mfma_f32_16x16x32_bf16 v[152:155], v[76:79], v[160:163], v[152:155]
	v_mfma_f32_16x16x32_bf16 v[144:147], v[64:67], v[168:171], v[144:147]
	v_mfma_f32_16x16x32_bf16 v[136:139], v[76:79], v[168:171], v[136:139]
	v_mfma_f32_16x16x32_bf16 v[124:127], v[64:67], v[176:179], v[124:127]
	v_mfma_f32_16x16x32_bf16 v[120:123], v[76:79], v[176:179], v[120:123]
	v_mfma_f32_16x16x32_bf16 v[112:115], v[64:67], v[184:187], v[112:115]
	v_mfma_f32_16x16x32_bf16 v[104:107], v[76:79], v[184:187], v[104:107]
	v_mfma_f32_16x16x32_bf16 v[156:159], v[68:71], v[164:167], v[156:159]
	v_mfma_f32_16x16x32_bf16 v[152:155], v[80:83], v[164:167], v[152:155]
	v_mfma_f32_16x16x32_bf16 v[144:147], v[68:71], v[172:175], v[144:147]
	v_mfma_f32_16x16x32_bf16 v[136:139], v[80:83], v[172:175], v[136:139]
	v_mfma_f32_16x16x32_bf16 v[124:127], v[68:71], v[180:183], v[124:127]
	v_mfma_f32_16x16x32_bf16 v[120:123], v[80:83], v[180:183], v[120:123]
	v_mfma_f32_16x16x32_bf16 v[112:115], v[68:71], v[188:191], v[112:115]
	v_mfma_f32_16x16x32_bf16 v[104:107], v[80:83], v[188:191], v[104:107]
	s_setprio 0
	s_setprio 1
	v_mfma_f32_16x16x32_bf16 v[148:151], v[88:91], v[160:163], v[148:151]
	v_mfma_f32_16x16x32_bf16 v[140:143], v[96:99], v[160:163], v[140:143]
	v_mfma_f32_16x16x32_bf16 v[132:135], v[88:91], v[168:171], v[132:135]
	v_mfma_f32_16x16x32_bf16 v[128:131], v[96:99], v[168:171], v[128:131]
	v_mfma_f32_16x16x32_bf16 v[116:119], v[88:91], v[176:179], v[116:119]
	v_mfma_f32_16x16x32_bf16 v[108:111], v[96:99], v[176:179], v[108:111]
	v_mfma_f32_16x16x32_bf16 v[84:87], v[88:91], v[184:187], v[84:87]
	v_mfma_f32_16x16x32_bf16 v[72:75], v[96:99], v[184:187], v[72:75]
	v_mfma_f32_16x16x32_bf16 v[148:151], v[92:95], v[164:167], v[148:151]
	v_mfma_f32_16x16x32_bf16 v[140:143], v[100:103], v[164:167], v[140:143]
	v_mfma_f32_16x16x32_bf16 v[132:135], v[92:95], v[172:175], v[132:135]
	v_mfma_f32_16x16x32_bf16 v[128:131], v[100:103], v[172:175], v[128:131]
	v_mfma_f32_16x16x32_bf16 v[116:119], v[92:95], v[180:183], v[116:119]
	v_mfma_f32_16x16x32_bf16 v[108:111], v[100:103], v[180:183], v[108:111]
	v_mfma_f32_16x16x32_bf16 v[84:87], v[92:95], v[188:191], v[84:87]
	v_mfma_f32_16x16x32_bf16 v[72:75], v[100:103], v[188:191], v[72:75]
	s_setprio 0
	s_barrier
; #define PG8_STAGE(bufoff, gbase, voff) do { _Pragma("unroll") for (int _i = 0; _i < 2; ++_i) \
;         __builtin_amdgcn_global_load_lds((const unsigned*)((const char*)(gbase) + (voff)[_i]), (PG8_LAS unsigned*)(lds + (bufoff) + ldsw + _i * 8192), 16, 0, 0); } while (0)
; #define PG8_LDA(dst, b, h) do { _Pragma("unroll") for (int m = 0; m < 4; ++m) _Pragma("unroll") for (int k = 0; k < 2; ++k) dst[m][k] = *(const PG8_LAS bf16x8*)(lds + PG8_SA(b, h) + aoff + m * 2048 + k * 1024); } while (0)
; #define PG8_MMA(ai, bj, At, Bt) do { __builtin_amdgcn_s_setprio(1); _Pragma("unroll") for (int m = 0; m < 4; ++m) _Pragma("unroll") for (int n = 0; n < 2; ++n) _Pragma("unroll") for (int k = 0; k < 2; ++k) \
;         acc[ai][bj][m][n] = __builtin_amdgcn_mfma_f32_16x16x32_bf16(Bt[n][k], At[m][k], acc[ai][bj][m][n], 0, 0, 0); __builtin_amdgcn_s_setprio(0); } while (0)
; #define PG8_WAIT_V(n) asm volatile("s_waitcnt vmcnt(" #n ")" ::: "memory")
; #define PG8_WAIT_L(n) asm volatile("s_waitcnt lgkmcnt(" #n ")" ::: "memory")
; #define PG8_BAR __builtin_amdgcn_s_barrier()
; #define PG8_SCHED __builtin_amdgcn_sched_barrier(0)
; template <class Epi, class Sched, bool ALIGN_EPI = false, bool SP2 = false>
; __device__ __forceinline__ void gemm_phase(PG8_LAS unsigned char* lds, const Gemm g, const Sched& S, const Epi& E, int wave_s_) {
;     ...
;         for (int t = 0; t < nt; t += 2) {
;     ...
;             PG8_LDA(At, 1, 1); PG8_STAGE(PG8_SB(1, 0), b3, voffB); PG8_STAGE(PG8_SB(1, 1), b3 + hstep, voffB); PG8_STAGE(PG8_SA(1, 0), a3, voffA);
;             PG8_WAIT_V(8); PG8_WAIT_L(0); PG8_BAR; PG8_MMA(1, 0, At, B0); PG8_MMA(1, 1, At, B1); PG8_BAR; PG8_SCHED;
	s_add_i32 s10, s64, s41
	v_lshl_add_u64 v[208:209], v[208:209], 0, s[76:77]
	s_mov_b32 m0, s10
	ds_read_b128 v[160:163], v227 offset:49152
	ds_read_b128 v[164:167], v227 offset:50176
	ds_read_b128 v[168:171], v227 offset:51200
	ds_read_b128 v[172:175], v227 offset:52224
	ds_read_b128 v[176:179], v227 offset:53248
	ds_read_b128 v[180:183], v227 offset:54272
	ds_read_b128 v[184:187], v227 offset:55296
	ds_read_b128 v[188:191], v227 offset:56320
	global_load_lds_dwordx4 v[208:209], off
	s_add_i32 m0, s10, 0x2000
	s_add_u32 s10, s34, 0xb0080
	v_lshl_add_u64 v[208:209], v[210:211], 0, s[76:77]
	s_addc_u32 s11, s35, 0
	s_add_i32 s34, s65, s41
	global_load_lds_dwordx4 v[208:209], off
	v_lshl_add_u64 v[208:209], s[10:11], 0, v[196:197]
	s_mov_b32 m0, s34
	s_nop 0
	global_load_lds_dwordx4 v[208:209], off
	v_lshl_add_u64 v[208:209], s[10:11], 0, v[192:193]
	s_add_i32 m0, s34, 0x2000
	s_nop 0
	global_load_lds_dwordx4 v[208:209], off
	v_lshl_add_u64 v[208:209], v[212:213], 0, s[76:77]
	s_mov_b32 m0, s48
	s_nop 0
	global_load_lds_dwordx4 v[208:209], off
	v_lshl_add_u64 v[208:209], v[214:215], 0, s[76:77]
	s_mov_b32 m0, s49
	s_nop 0
	global_load_lds_dwordx4 v[208:209], off
	s_waitcnt vmcnt(8)
	s_waitcnt lgkmcnt(0)
	s_barrier
	s_setprio 1
	s_waitcnt lgkmcnt(0)
	v_mfma_f32_16x16x32_bf16 v[60:63], v[64:67], v[160:163], v[60:63]
	v_mfma_f32_16x16x32_bf16 v[56:59], v[76:79], v[160:163], v[56:59]
	v_mfma_f32_16x16x32_bf16 v[48:51], v[64:67], v[168:171], v[48:51]
	v_mfma_f32_16x16x32_bf16 v[40:43], v[76:79], v[168:171], v[40:43]
	v_mfma_f32_16x16x32_bf16 v[28:31], v[64:67], v[176:179], v[28:31]
	v_mfma_f32_16x16x32_bf16 v[24:27], v[76:79], v[176:179], v[24:27]
	v_mfma_f32_16x16x32_bf16 v[16:19], v[64:67], v[184:187], v[16:19]
	v_mfma_f32_16x16x32_bf16 v[8:11], v[76:79], v[184:187], v[8:11]
	v_mfma_f32_16x16x32_bf16 v[60:63], v[68:71], v[164:167], v[60:63]
	v_mfma_f32_16x16x32_bf16 v[56:59], v[80:83], v[164:167], v[56:59]
	v_mfma_f32_16x16x32_bf16 v[48:51], v[68:71], v[172:175], v[48:51]
	v_mfma_f32_16x16x32_bf16 v[40:43], v[80:83], v[172:175], v[40:43]
	v_mfma_f32_16x16x32_bf16 v[28:31], v[68:71], v[180:183], v[28:31]
	v_mfma_f32_16x16x32_bf16 v[24:27], v[80:83], v[180:183], v[24:27]
	v_mfma_f32_16x16x32_bf16 v[16:19], v[68:71], v[188:191], v[16:19]
	v_mfma_f32_16x16x32_bf16 v[8:11], v[80:83], v[188:191], v[8:11]
	s_setprio 0
	s_setprio 1
	v_mfma_f32_16x16x32_bf16 v[52:55], v[88:91], v[160:163], v[52:55]
	v_mfma_f32_16x16x32_bf16 v[44:47], v[96:99], v[160:163], v[44:47]
	v_mfma_f32_16x16x32_bf16 v[36:39], v[88:91], v[168:171], v[36:39]
	v_mfma_f32_16x16x32_bf16 v[32:35], v[96:99], v[168:171], v[32:35]
	v_mfma_f32_16x16x32_bf16 v[20:23], v[88:91], v[176:179], v[20:23]
	v_mfma_f32_16x16x32_bf16 v[12:15], v[96:99], v[176:179], v[12:15]
	v_mfma_f32_16x16x32_bf16 v[4:7], v[88:91], v[184:187], v[4:7]
	v_mfma_f32_16x16x32_bf16 v[0:3], v[96:99], v[184:187], v[0:3]
	v_mfma_f32_16x16x32_bf16 v[52:55], v[92:95], v[164:167], v[52:55]
	v_mfma_f32_16x16x32_bf16 v[44:47], v[100:103], v[164:167], v[44:47]
	v_mfma_f32_16x16x32_bf16 v[36:39], v[92:95], v[172:175], v[36:39]
	v_mfma_f32_16x16x32_bf16 v[32:35], v[100:103], v[172:175], v[32:35]
	v_mfma_f32_16x16x32_bf16 v[20:23], v[92:95], v[180:183], v[20:23]
	v_mfma_f32_16x16x32_bf16 v[12:15], v[100:103], v[180:183], v[12:15]
	v_mfma_f32_16x16x32_bf16 v[4:7], v[92:95], v[188:191], v[4:7]
	v_mfma_f32_16x16x32_bf16 v[0:3], v[100:103], v[188:191], v[0:3]
	s_setprio 0
	s_barrier
	s_add_u32 s61, s61, 0x100
	s_addc_u32 s62, s62, 0
	s_cmp_ge_u32 s63, s59
	s_mov_b64 s[10:11], s[12:13]
	s_mov_b32 s34, s63
	s_cbranch_scc0 .LBB0_298
	s_branch .Lpeel_exit_1

; #define PG8_BAR __builtin_amdgcn_s_barrier()
; template <class Epi, class Sched, bool ALIGN_EPI = false, bool SP2 = false>
; __device__ __forceinline__ void gemm_phase(PG8_LAS unsigned char* lds, const Gemm g, const Sched& S, const Epi& E, int wave_s_) {
;     ...
;         if constexpr (ALIGN_EPI) { if (wr == 0) PG8_BAR; }
.Lpeel_exit_1:
	s_and_b64 vcc, exec, s[22:23]
	s_cbranch_vccz .LBB0_301
	s_barrier

; #define PG8_STAGE(bufoff, gbase, voff) do { _Pragma("unroll") for (int _i = 0; _i < 2; ++_i) \
;         __builtin_amdgcn_global_load_lds((const unsigned*)((const char*)(gbase) + (voff)[_i]), (PG8_LAS unsigned*)(lds + (bufoff) + ldsw + _i * 8192), 16, 0, 0); } while (0)
; #define PG8_LDA(dst, b, h) do { _Pragma("unroll") for (int m = 0; m < 4; ++m) _Pragma("unroll") for (int k = 0; k < 2; ++k) dst[m][k] = *(const PG8_LAS bf16x8*)(lds + PG8_SA(b, h) + aoff + m * 2048 + k * 1024); } while (0)
; #define PG8_LDB(dst, b, h) do { _Pragma("unroll") for (int n = 0; n < 2; ++n) _Pragma("unroll") for (int k = 0; k < 2; ++k) dst[n][k] = *(const PG8_LAS bf16x8*)(lds + PG8_SB(b, h) + boff + n * 2048 + k * 1024); } while (0)
; #define PG8_MMA(ai, bj, At, Bt) do { __builtin_amdgcn_s_setprio(1); _Pragma("unroll") for (int m = 0; m < 4; ++m) _Pragma("unroll") for (int n = 0; n < 2; ++n) _Pragma("unroll") for (int k = 0; k < 2; ++k) \
;         acc[ai][bj][m][n] = __builtin_amdgcn_mfma_f32_16x16x32_bf16(Bt[n][k], At[m][k], acc[ai][bj][m][n], 0, 0, 0); __builtin_amdgcn_s_setprio(0); } while (0)
; #define PG8_WAIT_V(n) asm volatile("s_waitcnt vmcnt(" #n ")" ::: "memory")
; #define PG8_BAR __builtin_amdgcn_s_barrier()
; template <class Epi, class Sched, bool ALIGN_EPI = false, bool SP2 = false>
; __device__ __forceinline__ void gemm_phase(PG8_LAS unsigned char* lds, const Gemm g, const Sched& S, const Epi& E, int wave_s_) {
;     ...
;         for (int t = 0; t < nt; t += 2) {
;             const bool last = (t == nt - 2);
;             const char* a1 = cA + (size_t)(t + 1) * kstep;
;             const char* a2 = last ? nA : cA + (size_t)(t + 2) * kstep; const char* b2 = last ? nB : cB + (size_t)(t + 2) * kstep;
;             const char* a3 = a2 + kstep; const char* b3 = b2 + kstep;
;             if (last && has_next) S.a_ready(nxt);
;             if constexpr (SP2) {
;             PG8_LDB(B0, 0, 0); PG8_LDB(B1, 0, 1); PG8_SCHED; PG8_LDA(At, 0, 0); PG8_STAGE(PG8_SA(1, 1), a1 + hstep, voffA);
;             PG8_WAIT_V(8); PG8_WAIT_L(0); PG8_BAR; PG8_MMA(0, 0, At, B0); PG8_MMA(0, 1, At, B1); PG8_BAR; PG8_SCHED;
;             PG8_LDA(At, 0, 1); PG8_STAGE(PG8_SB(0, 0), b2, voffB); PG8_STAGE(PG8_SB(0, 1), b2 + hstep, voffB); PG8_STAGE(PG8_SA(0, 0), a2, voffA);
;             PG8_WAIT_V(8); PG8_WAIT_L(0); PG8_BAR; PG8_MMA(1, 0, At, B0); PG8_MMA(1, 1, At, B1); PG8_BAR; PG8_SCHED;
.LBB0_561:
	s_add_u32 s6, s12, 0x40080
	s_addc_u32 s7, s13, 0
	s_add_u32 s9, s10, 0x100
	v_mov_b32_e32 v0, 0
	s_addc_u32 s14, s11, 0
	s_mov_b32 s15, -2
	s_add_u32 s10, s6, 0xfffc0080
	s_addc_u32 s11, s7, -1
	s_add_i32 s16, 0, 0x10000
	s_cmp_eq_u32 s15, 12
	s_cselect_b32 s13, s61, s11
	s_cselect_b32 s12, s60, s10
	s_cselect_b32 s11, s63, s14
	s_cselect_b32 s10, s62, s9
	s_add_i32 s18, 0, 0x14000
	v_add_u32_e32 v154, s16, v152
	v_add_u32_e32 v170, s18, v152
	ds_read_b128 v[128:131], v154
	ds_read_b128 v[144:147], v154 offset:1024
	ds_read_b128 v[148:151], v154 offset:2048
	ds_read_b128 v[154:157], v154 offset:3072
	ds_read_b128 v[158:161], v170
	ds_read_b128 v[162:165], v170 offset:1024
	ds_read_b128 v[166:169], v170 offset:2048
	ds_read_b128 v[170:173], v170 offset:3072
	v_lshl_add_u64 v[194:195], s[6:7], 0, v[140:141]
	s_add_i32 m0, s93, 0xc000
	ds_read_b128 v[174:177], v153
	ds_read_b128 v[178:181], v153 offset:1024
	ds_read_b128 v[182:185], v153 offset:2048
	ds_read_b128 v[186:189], v153 offset:3072
	ds_read_b128 v[190:193], v153 offset:4096
	ds_read_b128 v[206:209], v153 offset:5120
	ds_read_b128 v[210:213], v153 offset:6144
	ds_read_b128 v[214:217], v153 offset:7168
	global_load_lds_dwordx4 v[194:195], off
	v_lshl_add_u64 v[194:195], s[6:7], 0, v[142:143]
	s_add_i32 m0, s93, 0xe000
	s_nop 0
	global_load_lds_dwordx4 v[194:195], off
	s_waitcnt vmcnt(8)
	s_waitcnt lgkmcnt(0)
	s_barrier
	s_setprio 1
	s_waitcnt lgkmcnt(0)
	v_mfma_f32_16x16x32_bf16 v[124:127], v[128:131], v[174:177], 0
	v_mfma_f32_16x16x32_bf16 v[120:123], v[148:151], v[174:177], 0
	v_mfma_f32_16x16x32_bf16 v[116:119], v[128:131], v[182:185], 0
	v_mfma_f32_16x16x32_bf16 v[112:115], v[148:151], v[182:185], 0
	v_mfma_f32_16x16x32_bf16 v[108:111], v[128:131], v[190:193], 0
	v_mfma_f32_16x16x32_bf16 v[104:107], v[148:151], v[190:193], 0
	v_mfma_f32_16x16x32_bf16 v[100:103], v[128:131], v[210:213], 0
	v_mfma_f32_16x16x32_bf16 v[96:99], v[148:151], v[210:213], 0
	v_mfma_f32_16x16x32_bf16 v[124:127], v[144:147], v[178:181], v[124:127]
	v_mfma_f32_16x16x32_bf16 v[120:123], v[154:157], v[178:181], v[120:123]
	v_mfma_f32_16x16x32_bf16 v[116:119], v[144:147], v[186:189], v[116:119]
	v_mfma_f32_16x16x32_bf16 v[112:115], v[154:157], v[186:189], v[112:115]
	v_mfma_f32_16x16x32_bf16 v[108:111], v[144:147], v[206:209], v[108:111]
	v_mfma_f32_16x16x32_bf16 v[104:107], v[154:157], v[206:209], v[104:107]
	v_mfma_f32_16x16x32_bf16 v[100:103], v[144:147], v[214:217], v[100:103]
	v_mfma_f32_16x16x32_bf16 v[96:99], v[154:157], v[214:217], v[96:99]
	s_setprio 0
	s_setprio 1
	v_mfma_f32_16x16x32_bf16 v[60:63], v[158:161], v[174:177], 0
	v_mfma_f32_16x16x32_bf16 v[56:59], v[166:169], v[174:177], 0
	v_mfma_f32_16x16x32_bf16 v[52:55], v[158:161], v[182:185], 0
	v_mfma_f32_16x16x32_bf16 v[48:51], v[166:169], v[182:185], 0
	v_mfma_f32_16x16x32_bf16 v[44:47], v[158:161], v[190:193], 0
	v_mfma_f32_16x16x32_bf16 v[40:43], v[166:169], v[190:193], 0
	v_mfma_f32_16x16x32_bf16 v[36:39], v[158:161], v[210:213], 0
	v_mfma_f32_16x16x32_bf16 v[32:35], v[166:169], v[210:213], 0
	v_mfma_f32_16x16x32_bf16 v[60:63], v[162:165], v[178:181], v[60:63]
	v_mfma_f32_16x16x32_bf16 v[56:59], v[170:173], v[178:181], v[56:59]
	v_mfma_f32_16x16x32_bf16 v[52:55], v[162:165], v[186:189], v[52:55]
	v_mfma_f32_16x16x32_bf16 v[48:51], v[170:173], v[186:189], v[48:51]
	v_mfma_f32_16x16x32_bf16 v[44:47], v[162:165], v[206:209], v[44:47]
	v_mfma_f32_16x16x32_bf16 v[40:43], v[170:173], v[206:209], v[40:43]
	v_mfma_f32_16x16x32_bf16 v[36:39], v[162:165], v[214:217], v[36:39]
	v_mfma_f32_16x16x32_bf16 v[32:35], v[170:173], v[214:217], v[32:35]
	s_setprio 0
	s_barrier
	s_add_i32 s16, s16, s92
	v_lshl_add_u64 v[194:195], s[10:11], 0, v[134:135]
	s_mov_b32 m0, s16
	ds_read_b128 v[174:177], v153 offset:16384
	ds_read_b128 v[178:181], v153 offset:17408
	ds_read_b128 v[182:185], v153 offset:18432
	ds_read_b128 v[186:189], v153 offset:19456
	ds_read_b128 v[190:193], v153 offset:20480
	ds_read_b128 v[206:209], v153 offset:21504
	ds_read_b128 v[210:213], v153 offset:22528
	ds_read_b128 v[214:217], v153 offset:23552
	global_load_lds_dwordx4 v[194:195], off
	s_add_i32 m0, s16, 0x2000
	s_add_u32 s16, s10, 0x40000
	v_lshl_add_u64 v[218:219], s[10:11], 0, v[138:139]
	s_addc_u32 s17, s11, 0
	s_add_i32 s18, s18, s92
	global_load_lds_dwordx4 v[218:219], off
	v_lshl_add_u64 v[220:221], s[16:17], 0, v[134:135]
	s_mov_b32 m0, s18
	v_lshl_add_u64 v[222:223], s[12:13], 0, v[136:137]
	global_load_lds_dwordx4 v[220:221], off
	v_lshl_add_u64 v[220:221], s[16:17], 0, v[138:139]
	s_add_i32 m0, s18, 0x2000
	s_nop 0
	global_load_lds_dwordx4 v[220:221], off
	v_lshl_add_u64 v[220:221], s[12:13], 0, v[132:133]
	s_mov_b32 m0, s93
	s_nop 0
	global_load_lds_dwordx4 v[220:221], off
	s_mov_b32 m0, s94
	s_nop 0
	global_load_lds_dwordx4 v[222:223], off
	s_waitcnt vmcnt(8)
	s_waitcnt lgkmcnt(0)
	s_barrier
; #define PG8_STAGE(bufoff, gbase, voff) do { _Pragma("unroll") for (int _i = 0; _i < 2; ++_i) \
;         __builtin_amdgcn_global_load_lds((const unsigned*)((const char*)(gbase) + (voff)[_i]), (PG8_LAS unsigned*)(lds + (bufoff) + ldsw + _i * 8192), 16, 0, 0); } while (0)
; #define PG8_LDA(dst, b, h) do { _Pragma("unroll") for (int m = 0; m < 4; ++m) _Pragma("unroll") for (int k = 0; k < 2; ++k) dst[m][k] = *(const PG8_LAS bf16x8*)(lds + PG8_SA(b, h) + aoff + m * 2048 + k * 1024); } while (0)
; #define PG8_LDB(dst, b, h) do { _Pragma("unroll") for (int n = 0; n < 2; ++n) _Pragma("unroll") for (int k = 0; k < 2; ++k) dst[n][k] = *(const PG8_LAS bf16x8*)(lds + PG8_SB(b, h) + boff + n * 2048 + k * 1024); } while (0)
; #define PG8_MMA(ai, bj, At, Bt) do { __builtin_amdgcn_s_setprio(1); _Pragma("unroll") for (int m = 0; m < 4; ++m) _Pragma("unroll") for (int n = 0; n < 2; ++n) _Pragma("unroll") for (int k = 0; k < 2; ++k) \
;         acc[ai][bj][m][n] = __builtin_amdgcn_mfma_f32_16x16x32_bf16(Bt[n][k], At[m][k], acc[ai][bj][m][n], 0, 0, 0); __builtin_amdgcn_s_setprio(0); } while (0)
; #define PG8_WAIT_V(n) asm volatile("s_waitcnt vmcnt(" #n ")" ::: "memory")
; #define PG8_WAIT_L(n) asm volatile("s_waitcnt lgkmcnt(" #n ")" ::: "memory")
; #define PG8_BAR __builtin_amdgcn_s_barrier()
; #define PG8_SCHED __builtin_amdgcn_sched_barrier(0)
; template <class Epi, class Sched, bool ALIGN_EPI = false, bool SP2 = false>
; __device__ __forceinline__ void gemm_phase(PG8_LAS unsigned char* lds, const Gemm g, const Sched& S, const Epi& E, int wave_s_) {
;     ...
;             PG8_WAIT_V(8); PG8_WAIT_L(0); PG8_BAR; PG8_MMA(1, 0, At, B0); PG8_MMA(1, 1, At, B1); PG8_BAR; PG8_SCHED;
;             PG8_LDB(B0, 1, 0); PG8_LDB(B1, 1, 1); PG8_SCHED; PG8_LDA(At, 1, 0); PG8_STAGE(PG8_SA(0, 1), a2 + hstep, voffA);
;             PG8_WAIT_V(8); PG8_WAIT_L(0); PG8_BAR; PG8_MMA(0, 0, At, B0); PG8_MMA(0, 1, At, B1); PG8_BAR; PG8_SCHED;
	s_setprio 1
	s_waitcnt lgkmcnt(0)
	v_mfma_f32_16x16x32_bf16 v[92:95], v[128:131], v[174:177], 0
	v_mfma_f32_16x16x32_bf16 v[88:91], v[148:151], v[174:177], 0
	v_mfma_f32_16x16x32_bf16 v[84:87], v[128:131], v[182:185], 0
	v_mfma_f32_16x16x32_bf16 v[80:83], v[148:151], v[182:185], 0
	v_mfma_f32_16x16x32_bf16 v[76:79], v[128:131], v[190:193], 0
	v_mfma_f32_16x16x32_bf16 v[72:75], v[148:151], v[190:193], 0
	v_mfma_f32_16x16x32_bf16 v[68:71], v[128:131], v[210:213], 0
	v_mfma_f32_16x16x32_bf16 v[64:67], v[148:151], v[210:213], 0
	v_mfma_f32_16x16x32_bf16 v[92:95], v[144:147], v[178:181], v[92:95]
	v_mfma_f32_16x16x32_bf16 v[88:91], v[154:157], v[178:181], v[88:91]
	v_mfma_f32_16x16x32_bf16 v[84:87], v[144:147], v[186:189], v[84:87]
	v_mfma_f32_16x16x32_bf16 v[80:83], v[154:157], v[186:189], v[80:83]
	v_mfma_f32_16x16x32_bf16 v[76:79], v[144:147], v[206:209], v[76:79]
	v_mfma_f32_16x16x32_bf16 v[72:75], v[154:157], v[206:209], v[72:75]
	v_mfma_f32_16x16x32_bf16 v[68:71], v[144:147], v[214:217], v[68:71]
	v_mfma_f32_16x16x32_bf16 v[64:67], v[154:157], v[214:217], v[64:67]
	s_setprio 0
	s_setprio 1
	v_mfma_f32_16x16x32_bf16 v[28:31], v[158:161], v[174:177], 0
	v_mfma_f32_16x16x32_bf16 v[24:27], v[166:169], v[174:177], 0
	v_mfma_f32_16x16x32_bf16 v[20:23], v[158:161], v[182:185], 0
	v_mfma_f32_16x16x32_bf16 v[16:19], v[166:169], v[182:185], 0
	v_mfma_f32_16x16x32_bf16 v[12:15], v[158:161], v[190:193], 0
	v_mfma_f32_16x16x32_bf16 v[8:11], v[166:169], v[190:193], 0
	v_mfma_f32_16x16x32_bf16 v[4:7], v[158:161], v[210:213], 0
	v_mfma_f32_16x16x32_bf16 v[0:3], v[166:169], v[210:213], 0
	v_mfma_f32_16x16x32_bf16 v[28:31], v[162:165], v[178:181], v[28:31]
	v_mfma_f32_16x16x32_bf16 v[24:27], v[170:173], v[178:181], v[24:27]
	v_mfma_f32_16x16x32_bf16 v[20:23], v[162:165], v[186:189], v[20:23]
	v_mfma_f32_16x16x32_bf16 v[16:19], v[170:173], v[186:189], v[16:19]
	v_mfma_f32_16x16x32_bf16 v[12:15], v[162:165], v[206:209], v[12:15]
	v_mfma_f32_16x16x32_bf16 v[8:11], v[170:173], v[206:209], v[8:11]
	v_mfma_f32_16x16x32_bf16 v[4:7], v[162:165], v[214:217], v[4:7]
	v_mfma_f32_16x16x32_bf16 v[0:3], v[170:173], v[214:217], v[0:3]
	s_setprio 0
	s_barrier
	s_add_i32 s16, 0, 0x18000
	s_add_i32 s17, 0, 0x1c000
	v_add_u32_e32 v154, s16, v152
	v_add_u32_e32 v170, s17, v152
	ds_read_b128 v[128:131], v154
	ds_read_b128 v[144:147], v154 offset:1024
	ds_read_b128 v[148:151], v154 offset:2048
	ds_read_b128 v[154:157], v154 offset:3072
	ds_read_b128 v[158:161], v170
	ds_read_b128 v[162:165], v170 offset:1024
	ds_read_b128 v[166:169], v170 offset:2048
	ds_read_b128 v[170:173], v170 offset:3072
	s_add_u32 s12, s12, 0x40000
	s_addc_u32 s13, s13, 0
	s_mov_b32 m0, s95
	v_lshl_add_u64 v[224:225], s[12:13], 0, v[132:133]
	ds_read_b128 v[174:177], v153 offset:32768
	ds_read_b128 v[178:181], v153 offset:33792
	ds_read_b128 v[182:185], v153 offset:34816
	ds_read_b128 v[186:189], v153 offset:35840
	ds_read_b128 v[190:193], v153 offset:36864
	ds_read_b128 v[206:209], v153 offset:37888
	ds_read_b128 v[210:213], v153 offset:38912
	ds_read_b128 v[214:217], v153 offset:39936
	global_load_lds_dwordx4 v[224:225], off
	v_lshl_add_u64 v[224:225], s[12:13], 0, v[136:137]
	s_mov_b32 m0, s96
	s_nop 0
	global_load_lds_dwordx4 v[224:225], off
	s_waitcnt vmcnt(8)
	s_waitcnt lgkmcnt(0)
	s_barrier
	s_setprio 1
	s_waitcnt lgkmcnt(0)
	v_mfma_f32_16x16x32_bf16 v[124:127], v[128:131], v[174:177], v[124:127]
	v_mfma_f32_16x16x32_bf16 v[120:123], v[148:151], v[174:177], v[120:123]
	v_mfma_f32_16x16x32_bf16 v[116:119], v[128:131], v[182:185], v[116:119]
	v_mfma_f32_16x16x32_bf16 v[112:115], v[148:151], v[182:185], v[112:115]
	v_mfma_f32_16x16x32_bf16 v[108:111], v[128:131], v[190:193], v[108:111]
	v_mfma_f32_16x16x32_bf16 v[104:107], v[148:151], v[190:193], v[104:107]
	v_mfma_f32_16x16x32_bf16 v[100:103], v[128:131], v[210:213], v[100:103]
	v_mfma_f32_16x16x32_bf16 v[96:99], v[148:151], v[210:213], v[96:99]
	v_mfma_f32_16x16x32_bf16 v[124:127], v[144:147], v[178:181], v[124:127]
	v_mfma_f32_16x16x32_bf16 v[120:123], v[154:157], v[178:181], v[120:123]
	v_mfma_f32_16x16x32_bf16 v[116:119], v[144:147], v[186:189], v[116:119]
	v_mfma_f32_16x16x32_bf16 v[112:115], v[154:157], v[186:189], v[112:115]
	v_mfma_f32_16x16x32_bf16 v[108:111], v[144:147], v[206:209], v[108:111]
	v_mfma_f32_16x16x32_bf16 v[104:107], v[154:157], v[206:209], v[104:107]
	v_mfma_f32_16x16x32_bf16 v[100:103], v[144:147], v[214:217], v[100:103]
	v_mfma_f32_16x16x32_bf16 v[96:99], v[154:157], v[214:217], v[96:99]
	s_setprio 0
	s_setprio 1
	v_mfma_f32_16x16x32_bf16 v[60:63], v[158:161], v[174:177], v[60:63]
	v_mfma_f32_16x16x32_bf16 v[56:59], v[166:169], v[174:177], v[56:59]
	v_mfma_f32_16x16x32_bf16 v[52:55], v[158:161], v[182:185], v[52:55]
	v_mfma_f32_16x16x32_bf16 v[48:51], v[166:169], v[182:185], v[48:51]
	v_mfma_f32_16x16x32_bf16 v[44:47], v[158:161], v[190:193], v[44:47]
	v_mfma_f32_16x16x32_bf16 v[40:43], v[166:169], v[190:193], v[40:43]
	v_mfma_f32_16x16x32_bf16 v[36:39], v[158:161], v[210:213], v[36:39]
	v_mfma_f32_16x16x32_bf16 v[32:35], v[166:169], v[210:213], v[32:35]
	v_mfma_f32_16x16x32_bf16 v[60:63], v[162:165], v[178:181], v[60:63]
	v_mfma_f32_16x16x32_bf16 v[56:59], v[170:173], v[178:181], v[56:59]
	v_mfma_f32_16x16x32_bf16 v[52:55], v[162:165], v[186:189], v[52:55]
	v_mfma_f32_16x16x32_bf16 v[48:51], v[170:173], v[186:189], v[48:51]
	v_mfma_f32_16x16x32_bf16 v[44:47], v[162:165], v[206:209], v[44:47]
	v_mfma_f32_16x16x32_bf16 v[40:43], v[170:173], v[206:209], v[40:43]
	v_mfma_f32_16x16x32_bf16 v[36:39], v[162:165], v[214:217], v[36:39]
	v_mfma_f32_16x16x32_bf16 v[32:35], v[170:173], v[214:217], v[32:35]
	s_setprio 0
	s_barrier
; #define PG8_STAGE(bufoff, gbase, voff) do { _Pragma("unroll") for (int _i = 0; _i < 2; ++_i) \
;         __builtin_amdgcn_global_load_lds((const unsigned*)((const char*)(gbase) + (voff)[_i]), (PG8_LAS unsigned*)(lds + (bufoff) + ldsw + _i * 8192), 16, 0, 0); } while (0)
; #define PG8_LDA(dst, b, h) do { _Pragma("unroll") for (int m = 0; m < 4; ++m) _Pragma("unroll") for (int k = 0; k < 2; ++k) dst[m][k] = *(const PG8_LAS bf16x8*)(lds + PG8_SA(b, h) + aoff + m * 2048 + k * 1024); } while (0)
; #define PG8_MMA(ai, bj, At, Bt) do { __builtin_amdgcn_s_setprio(1); _Pragma("unroll") for (int m = 0; m < 4; ++m) _Pragma("unroll") for (int n = 0; n < 2; ++n) _Pragma("unroll") for (int k = 0; k < 2; ++k) \
;         acc[ai][bj][m][n] = __builtin_amdgcn_mfma_f32_16x16x32_bf16(Bt[n][k], At[m][k], acc[ai][bj][m][n], 0, 0, 0); __builtin_amdgcn_s_setprio(0); } while (0)
; #define PG8_WAIT_V(n) asm volatile("s_waitcnt vmcnt(" #n ")" ::: "memory")
; #define PG8_WAIT_L(n) asm volatile("s_waitcnt lgkmcnt(" #n ")" ::: "memory")
; #define PG8_BAR __builtin_amdgcn_s_barrier()
; #define PG8_SCHED __builtin_amdgcn_sched_barrier(0)
; template <class Epi, class Sched, bool ALIGN_EPI = false, bool SP2 = false>
; __device__ __forceinline__ void gemm_phase(PG8_LAS unsigned char* lds, const Gemm g, const Sched& S, const Epi& E, int wave_s_) {
;     ...
;         for (int t = 0; t < nt; t += 2) {
;     ...
;             PG8_LDA(At, 1, 1); PG8_STAGE(PG8_SB(1, 0), b3, voffB); PG8_STAGE(PG8_SB(1, 1), b3 + hstep, voffB); PG8_STAGE(PG8_SA(1, 0), a3, voffA);
;             PG8_WAIT_V(8); PG8_WAIT_L(0); PG8_BAR; PG8_MMA(1, 0, At, B0); PG8_MMA(1, 1, At, B1); PG8_BAR; PG8_SCHED;
	s_add_i32 s12, s16, s92
	v_lshl_add_u64 v[194:195], v[194:195], 0, s[76:77]
	s_mov_b32 m0, s12
	ds_read_b128 v[174:177], v153 offset:49152
	ds_read_b128 v[178:181], v153 offset:50176
	ds_read_b128 v[182:185], v153 offset:51200
	ds_read_b128 v[186:189], v153 offset:52224
	ds_read_b128 v[190:193], v153 offset:53248
	ds_read_b128 v[206:209], v153 offset:54272
	ds_read_b128 v[210:213], v153 offset:55296
	ds_read_b128 v[214:217], v153 offset:56320
	global_load_lds_dwordx4 v[194:195], off
	s_add_i32 m0, s12, 0x2000
	s_add_u32 s10, s10, 0x40080
	v_lshl_add_u64 v[194:195], v[218:219], 0, s[76:77]
	s_addc_u32 s11, s11, 0
	s_add_i32 s12, s17, s92
	global_load_lds_dwordx4 v[194:195], off
	v_lshl_add_u64 v[194:195], s[10:11], 0, v[134:135]
	s_mov_b32 m0, s12
	s_nop 0
	global_load_lds_dwordx4 v[194:195], off
	v_lshl_add_u64 v[194:195], s[10:11], 0, v[138:139]
	s_add_i32 m0, s12, 0x2000
	s_nop 0
	global_load_lds_dwordx4 v[194:195], off
	v_lshl_add_u64 v[194:195], v[220:221], 0, s[76:77]
	s_mov_b32 m0, s48
	s_nop 0
	global_load_lds_dwordx4 v[194:195], off
	v_lshl_add_u64 v[194:195], v[222:223], 0, s[76:77]
	s_mov_b32 m0, s49
	s_nop 0
	global_load_lds_dwordx4 v[194:195], off
	s_waitcnt vmcnt(8)
	s_waitcnt lgkmcnt(0)
	s_barrier
	s_setprio 1
	s_waitcnt lgkmcnt(0)
	v_mfma_f32_16x16x32_bf16 v[92:95], v[128:131], v[174:177], v[92:95]
	v_mfma_f32_16x16x32_bf16 v[88:91], v[148:151], v[174:177], v[88:91]
	v_mfma_f32_16x16x32_bf16 v[84:87], v[128:131], v[182:185], v[84:87]
	v_mfma_f32_16x16x32_bf16 v[80:83], v[148:151], v[182:185], v[80:83]
	v_mfma_f32_16x16x32_bf16 v[76:79], v[128:131], v[190:193], v[76:79]
	v_mfma_f32_16x16x32_bf16 v[72:75], v[148:151], v[190:193], v[72:75]
	v_mfma_f32_16x16x32_bf16 v[68:71], v[128:131], v[210:213], v[68:71]
	v_mfma_f32_16x16x32_bf16 v[64:67], v[148:151], v[210:213], v[64:67]
	v_mfma_f32_16x16x32_bf16 v[92:95], v[144:147], v[178:181], v[92:95]
	v_mfma_f32_16x16x32_bf16 v[88:91], v[154:157], v[178:181], v[88:91]
	v_mfma_f32_16x16x32_bf16 v[84:87], v[144:147], v[186:189], v[84:87]
	v_mfma_f32_16x16x32_bf16 v[80:83], v[154:157], v[186:189], v[80:83]
	v_mfma_f32_16x16x32_bf16 v[76:79], v[144:147], v[206:209], v[76:79]
	v_mfma_f32_16x16x32_bf16 v[72:75], v[154:157], v[206:209], v[72:75]
	v_mfma_f32_16x16x32_bf16 v[68:71], v[144:147], v[214:217], v[68:71]
	v_mfma_f32_16x16x32_bf16 v[64:67], v[154:157], v[214:217], v[64:67]
	s_setprio 0
	s_setprio 1
	v_mfma_f32_16x16x32_bf16 v[28:31], v[158:161], v[174:177], v[28:31]
	v_mfma_f32_16x16x32_bf16 v[24:27], v[166:169], v[174:177], v[24:27]
	v_mfma_f32_16x16x32_bf16 v[20:23], v[158:161], v[182:185], v[20:23]
	v_mfma_f32_16x16x32_bf16 v[16:19], v[166:169], v[182:185], v[16:19]
	v_mfma_f32_16x16x32_bf16 v[12:15], v[158:161], v[190:193], v[12:15]
	v_mfma_f32_16x16x32_bf16 v[8:11], v[166:169], v[190:193], v[8:11]
	v_mfma_f32_16x16x32_bf16 v[4:7], v[158:161], v[210:213], v[4:7]
	v_mfma_f32_16x16x32_bf16 v[0:3], v[166:169], v[210:213], v[0:3]
	v_mfma_f32_16x16x32_bf16 v[28:31], v[162:165], v[178:181], v[28:31]
	v_mfma_f32_16x16x32_bf16 v[24:27], v[170:173], v[178:181], v[24:27]
	v_mfma_f32_16x16x32_bf16 v[20:23], v[162:165], v[186:189], v[20:23]
	v_mfma_f32_16x16x32_bf16 v[16:19], v[170:173], v[186:189], v[16:19]
	v_mfma_f32_16x16x32_bf16 v[12:15], v[162:165], v[206:209], v[12:15]
	v_mfma_f32_16x16x32_bf16 v[8:11], v[170:173], v[206:209], v[8:11]
	v_mfma_f32_16x16x32_bf16 v[4:7], v[162:165], v[214:217], v[4:7]
	v_mfma_f32_16x16x32_bf16 v[0:3], v[170:173], v[214:217], v[0:3]
	s_setprio 0
	s_barrier
	s_add_i32 s15, s15, 2
	s_add_u32 s6, s6, 0x100
	s_addc_u32 s7, s7, 0
	s_add_u32 s9, s9, 0x100
	s_addc_u32 s14, s14, 0
	s_cmp_gt_u32 s15, 13
	s_cbranch_scc0 .LBB0_562
	s_branch .Lpeel_exit_2

; #define PG8_BAR __builtin_amdgcn_s_barrier()
; template <class Epi, class Sched, bool ALIGN_EPI = false, bool SP2 = false>
; __device__ __forceinline__ void gemm_phase(PG8_LAS unsigned char* lds, const Gemm g, const Sched& S, const Epi& E, int wave_s_) {
;     ...
;         if constexpr (ALIGN_EPI) { if (wr == 0) PG8_BAR; }
.Lpeel_exit_2:
	s_and_b64 vcc, exec, s[52:53]
	s_cbranch_vccz .LBB0_565
	s_barrier

; #define PG8_STAGE(bufoff, gbase, voff) do { _Pragma("unroll") for (int _i = 0; _i < 2; ++_i) \
;         __builtin_amdgcn_global_load_lds((const unsigned*)((const char*)(gbase) + (voff)[_i]), (PG8_LAS unsigned*)(lds + (bufoff) + ldsw + _i * 8192), 16, 0, 0); } while (0)
; #define PG8_LDA(dst, b, h) do { _Pragma("unroll") for (int m = 0; m < 4; ++m) _Pragma("unroll") for (int k = 0; k < 2; ++k) dst[m][k] = *(const PG8_LAS bf16x8*)(lds + PG8_SA(b, h) + aoff + m * 2048 + k * 1024); } while (0)
; #define PG8_LDB(dst, b, h) do { _Pragma("unroll") for (int n = 0; n < 2; ++n) _Pragma("unroll") for (int k = 0; k < 2; ++k) dst[n][k] = *(const PG8_LAS bf16x8*)(lds + PG8_SB(b, h) + boff + n * 2048 + k * 1024); } while (0)
; #define PG8_MMA(ai, bj, At, Bt) do { __builtin_amdgcn_s_setprio(1); _Pragma("unroll") for (int m = 0; m < 4; ++m) _Pragma("unroll") for (int n = 0; n < 2; ++n) _Pragma("unroll") for (int k = 0; k < 2; ++k) \
;         acc[ai][bj][m][n] = __builtin_amdgcn_mfma_f32_16x16x32_bf16(Bt[n][k], At[m][k], acc[ai][bj][m][n], 0, 0, 0); __builtin_amdgcn_s_setprio(0); } while (0)
; #define PG8_WAIT_V(n) asm volatile("s_waitcnt vmcnt(" #n ")" ::: "memory")
; #define PG8_BAR __builtin_amdgcn_s_barrier()
; template <class Epi, class Sched, bool ALIGN_EPI = false, bool SP2 = false>
; __device__ __forceinline__ void gemm_phase(PG8_LAS unsigned char* lds, const Gemm g, const Sched& S, const Epi& E, int wave_s_) {
;     ...
;         for (int t = 0; t < nt; t += 2) {
;             const bool last = (t == nt - 2);
;             const char* a1 = cA + (size_t)(t + 1) * kstep;
;             const char* a2 = last ? nA : cA + (size_t)(t + 2) * kstep; const char* b2 = last ? nB : cB + (size_t)(t + 2) * kstep;
;             const char* a3 = a2 + kstep; const char* b3 = b2 + kstep;
;             if (last && has_next) S.a_ready(nxt);
;             if constexpr (SP2) {
;             PG8_LDB(B0, 0, 0); PG8_LDB(B1, 0, 1); PG8_SCHED; PG8_LDA(At, 0, 0); PG8_STAGE(PG8_SA(1, 1), a1 + hstep, voffA);
;             PG8_WAIT_V(8); PG8_WAIT_L(0); PG8_BAR; PG8_MMA(0, 0, At, B0); PG8_MMA(0, 1, At, B1); PG8_BAR; PG8_SCHED;
;             PG8_LDA(At, 0, 1); PG8_STAGE(PG8_SB(0, 0), b2, voffB); PG8_STAGE(PG8_SB(0, 1), b2 + hstep, voffB); PG8_STAGE(PG8_SA(0, 0), a2, voffA);
;             PG8_WAIT_V(8); PG8_WAIT_L(0); PG8_BAR; PG8_MMA(1, 0, At, B0); PG8_MMA(1, 1, At, B1); PG8_BAR; PG8_SCHED;
.LBB0_1184:
	s_add_u32 s18, s18, 0x40080
	s_addc_u32 s19, s19, 0
	s_add_u32 s15, s20, 0x100
	v_mov_b32_e32 v0, 0
	s_addc_u32 s44, s21, 0
	s_mov_b32 s45, -2
	s_add_u32 s20, s18, 0xfffc0080
	s_addc_u32 s21, s19, -1
	s_add_i32 s46, 0, 0x10000
	s_cmp_eq_u32 s45, 12
	s_cselect_b32 s23, s7, s21
	s_cselect_b32 s22, s6, s20
	s_cselect_b32 s21, s17, s44
	s_cselect_b32 s20, s16, s15
	s_add_i32 s48, 0, 0x14000
	v_add_u32_e32 v148, s46, v134
	v_add_u32_e32 v164, s48, v134
	ds_read_b128 v[136:139], v148
	ds_read_b128 v[140:143], v148 offset:1024
	ds_read_b128 v[144:147], v148 offset:2048
	ds_read_b128 v[148:151], v148 offset:3072
	ds_read_b128 v[152:155], v164
	ds_read_b128 v[156:159], v164 offset:1024
	ds_read_b128 v[160:163], v164 offset:2048
	ds_read_b128 v[164:167], v164 offset:3072
	v_lshl_add_u64 v[210:211], s[18:19], 0, v[130:131]
	s_add_i32 m0, s30, 0xc000
	ds_read_b128 v[168:171], v135
	ds_read_b128 v[172:175], v135 offset:1024
	ds_read_b128 v[176:179], v135 offset:2048
	ds_read_b128 v[180:183], v135 offset:3072
	ds_read_b128 v[184:187], v135 offset:4096
	ds_read_b128 v[188:191], v135 offset:5120
	ds_read_b128 v[192:195], v135 offset:6144
	ds_read_b128 v[206:209], v135 offset:7168
	global_load_lds_dwordx4 v[210:211], off
	v_lshl_add_u64 v[210:211], s[18:19], 0, v[132:133]
	s_add_i32 m0, s30, 0xe000
	s_nop 0
	global_load_lds_dwordx4 v[210:211], off
	s_waitcnt vmcnt(8)
	s_waitcnt lgkmcnt(0)
	s_barrier
	s_setprio 1
	s_waitcnt lgkmcnt(0)
	v_mfma_f32_16x16x32_bf16 v[124:127], v[136:139], v[168:171], 0
	v_mfma_f32_16x16x32_bf16 v[120:123], v[144:147], v[168:171], 0
	v_mfma_f32_16x16x32_bf16 v[116:119], v[136:139], v[176:179], 0
	v_mfma_f32_16x16x32_bf16 v[112:115], v[144:147], v[176:179], 0
	v_mfma_f32_16x16x32_bf16 v[108:111], v[136:139], v[184:187], 0
	v_mfma_f32_16x16x32_bf16 v[100:103], v[144:147], v[184:187], 0
	v_mfma_f32_16x16x32_bf16 v[92:95], v[136:139], v[192:195], 0
	v_mfma_f32_16x16x32_bf16 v[84:87], v[144:147], v[192:195], 0
	v_mfma_f32_16x16x32_bf16 v[124:127], v[140:143], v[172:175], v[124:127]
	v_mfma_f32_16x16x32_bf16 v[120:123], v[148:151], v[172:175], v[120:123]
	v_mfma_f32_16x16x32_bf16 v[116:119], v[140:143], v[180:183], v[116:119]
	v_mfma_f32_16x16x32_bf16 v[112:115], v[148:151], v[180:183], v[112:115]
	v_mfma_f32_16x16x32_bf16 v[108:111], v[140:143], v[188:191], v[108:111]
	v_mfma_f32_16x16x32_bf16 v[100:103], v[148:151], v[188:191], v[100:103]
	v_mfma_f32_16x16x32_bf16 v[92:95], v[140:143], v[206:209], v[92:95]
	v_mfma_f32_16x16x32_bf16 v[84:87], v[148:151], v[206:209], v[84:87]
	s_setprio 0
	s_setprio 1
	v_mfma_f32_16x16x32_bf16 v[104:107], v[152:155], v[168:171], 0
	v_mfma_f32_16x16x32_bf16 v[96:99], v[160:163], v[168:171], 0
	v_mfma_f32_16x16x32_bf16 v[88:91], v[152:155], v[176:179], 0
	v_mfma_f32_16x16x32_bf16 v[80:83], v[160:163], v[176:179], 0
	v_mfma_f32_16x16x32_bf16 v[76:79], v[152:155], v[184:187], 0
	v_mfma_f32_16x16x32_bf16 v[72:75], v[160:163], v[184:187], 0
	v_mfma_f32_16x16x32_bf16 v[68:71], v[152:155], v[192:195], 0
	v_mfma_f32_16x16x32_bf16 v[64:67], v[160:163], v[192:195], 0
	v_mfma_f32_16x16x32_bf16 v[104:107], v[156:159], v[172:175], v[104:107]
	v_mfma_f32_16x16x32_bf16 v[96:99], v[164:167], v[172:175], v[96:99]
	v_mfma_f32_16x16x32_bf16 v[88:91], v[156:159], v[180:183], v[88:91]
	v_mfma_f32_16x16x32_bf16 v[80:83], v[164:167], v[180:183], v[80:83]
	v_mfma_f32_16x16x32_bf16 v[76:79], v[156:159], v[188:191], v[76:79]
	v_mfma_f32_16x16x32_bf16 v[72:75], v[164:167], v[188:191], v[72:75]
	v_mfma_f32_16x16x32_bf16 v[68:71], v[156:159], v[206:209], v[68:71]
	v_mfma_f32_16x16x32_bf16 v[64:67], v[164:167], v[206:209], v[64:67]
	s_setprio 0
	s_barrier
	s_add_i32 s46, s46, s29
	v_lshl_add_u64 v[210:211], s[20:21], 0, v[196:197]
	s_mov_b32 m0, s46
	ds_read_b128 v[168:171], v135 offset:16384
	ds_read_b128 v[172:175], v135 offset:17408
	ds_read_b128 v[176:179], v135 offset:18432
	ds_read_b128 v[180:183], v135 offset:19456
	ds_read_b128 v[184:187], v135 offset:20480
	ds_read_b128 v[188:191], v135 offset:21504
	ds_read_b128 v[192:195], v135 offset:22528
	ds_read_b128 v[206:209], v135 offset:23552
	global_load_lds_dwordx4 v[210:211], off
	s_add_i32 m0, s46, 0x2000
	s_add_u32 s46, s20, 0x40000
	v_lshl_add_u64 v[212:213], s[20:21], 0, v[128:129]
	s_addc_u32 s47, s21, 0
	s_add_i32 s48, s48, s29
	global_load_lds_dwordx4 v[212:213], off
	v_lshl_add_u64 v[214:215], s[46:47], 0, v[196:197]
	s_mov_b32 m0, s48
	v_lshl_add_u64 v[216:217], s[22:23], 0, v[128:129]
	global_load_lds_dwordx4 v[214:215], off
	v_lshl_add_u64 v[214:215], s[46:47], 0, v[128:129]
	s_add_i32 m0, s48, 0x2000
	s_nop 0
	global_load_lds_dwordx4 v[214:215], off
	v_lshl_add_u64 v[214:215], s[22:23], 0, v[196:197]
	s_mov_b32 m0, s30
	s_nop 0
	global_load_lds_dwordx4 v[214:215], off
	s_mov_b32 m0, s31
	s_nop 0
	global_load_lds_dwordx4 v[216:217], off
	s_waitcnt vmcnt(8)
	s_waitcnt lgkmcnt(0)
	s_barrier
; #define PG8_STAGE(bufoff, gbase, voff) do { _Pragma("unroll") for (int _i = 0; _i < 2; ++_i) \
;         __builtin_amdgcn_global_load_lds((const unsigned*)((const char*)(gbase) + (voff)[_i]), (PG8_LAS unsigned*)(lds + (bufoff) + ldsw + _i * 8192), 16, 0, 0); } while (0)
; #define PG8_LDA(dst, b, h) do { _Pragma("unroll") for (int m = 0; m < 4; ++m) _Pragma("unroll") for (int k = 0; k < 2; ++k) dst[m][k] = *(const PG8_LAS bf16x8*)(lds + PG8_SA(b, h) + aoff + m * 2048 + k * 1024); } while (0)
; #define PG8_LDB(dst, b, h) do { _Pragma("unroll") for (int n = 0; n < 2; ++n) _Pragma("unroll") for (int k = 0; k < 2; ++k) dst[n][k] = *(const PG8_LAS bf16x8*)(lds + PG8_SB(b, h) + boff + n * 2048 + k * 1024); } while (0)
; #define PG8_MMA(ai, bj, At, Bt) do { __builtin_amdgcn_s_setprio(1); _Pragma("unroll") for (int m = 0; m < 4; ++m) _Pragma("unroll") for (int n = 0; n < 2; ++n) _Pragma("unroll") for (int k = 0; k < 2; ++k) \
;         acc[ai][bj][m][n] = __builtin_amdgcn_mfma_f32_16x16x32_bf16(Bt[n][k], At[m][k], acc[ai][bj][m][n], 0, 0, 0); __builtin_amdgcn_s_setprio(0); } while (0)
; #define PG8_WAIT_V(n) asm volatile("s_waitcnt vmcnt(" #n ")" ::: "memory")
; #define PG8_WAIT_L(n) asm volatile("s_waitcnt lgkmcnt(" #n ")" ::: "memory")
; #define PG8_BAR __builtin_amdgcn_s_barrier()
; #define PG8_SCHED __builtin_amdgcn_sched_barrier(0)
; template <class Epi, class Sched, bool ALIGN_EPI = false, bool SP2 = false>
; __device__ __forceinline__ void gemm_phase(PG8_LAS unsigned char* lds, const Gemm g, const Sched& S, const Epi& E, int wave_s_) {
;     ...
;             PG8_WAIT_V(8); PG8_WAIT_L(0); PG8_BAR; PG8_MMA(1, 0, At, B0); PG8_MMA(1, 1, At, B1); PG8_BAR; PG8_SCHED;
;             PG8_LDB(B0, 1, 0); PG8_LDB(B1, 1, 1); PG8_SCHED; PG8_LDA(At, 1, 0); PG8_STAGE(PG8_SA(0, 1), a2 + hstep, voffA);
;             PG8_WAIT_V(8); PG8_WAIT_L(0); PG8_BAR; PG8_MMA(0, 0, At, B0); PG8_MMA(0, 1, At, B1); PG8_BAR; PG8_SCHED;
	s_setprio 1
	s_waitcnt lgkmcnt(0)
	v_mfma_f32_16x16x32_bf16 v[60:63], v[136:139], v[168:171], 0
	v_mfma_f32_16x16x32_bf16 v[56:59], v[144:147], v[168:171], 0
	v_mfma_f32_16x16x32_bf16 v[52:55], v[136:139], v[176:179], 0
	v_mfma_f32_16x16x32_bf16 v[48:51], v[144:147], v[176:179], 0
	v_mfma_f32_16x16x32_bf16 v[44:47], v[136:139], v[184:187], 0
	v_mfma_f32_16x16x32_bf16 v[36:39], v[144:147], v[184:187], 0
	v_mfma_f32_16x16x32_bf16 v[28:31], v[136:139], v[192:195], 0
	v_mfma_f32_16x16x32_bf16 v[20:23], v[144:147], v[192:195], 0
	v_mfma_f32_16x16x32_bf16 v[60:63], v[140:143], v[172:175], v[60:63]
	v_mfma_f32_16x16x32_bf16 v[56:59], v[148:151], v[172:175], v[56:59]
	v_mfma_f32_16x16x32_bf16 v[52:55], v[140:143], v[180:183], v[52:55]
	v_mfma_f32_16x16x32_bf16 v[48:51], v[148:151], v[180:183], v[48:51]
	v_mfma_f32_16x16x32_bf16 v[44:47], v[140:143], v[188:191], v[44:47]
	v_mfma_f32_16x16x32_bf16 v[36:39], v[148:151], v[188:191], v[36:39]
	v_mfma_f32_16x16x32_bf16 v[28:31], v[140:143], v[206:209], v[28:31]
	v_mfma_f32_16x16x32_bf16 v[20:23], v[148:151], v[206:209], v[20:23]
	s_setprio 0
	s_setprio 1
	v_mfma_f32_16x16x32_bf16 v[40:43], v[152:155], v[168:171], 0
	v_mfma_f32_16x16x32_bf16 v[32:35], v[160:163], v[168:171], 0
	v_mfma_f32_16x16x32_bf16 v[24:27], v[152:155], v[176:179], 0
	v_mfma_f32_16x16x32_bf16 v[16:19], v[160:163], v[176:179], 0
	v_mfma_f32_16x16x32_bf16 v[12:15], v[152:155], v[184:187], 0
	v_mfma_f32_16x16x32_bf16 v[8:11], v[160:163], v[184:187], 0
	v_mfma_f32_16x16x32_bf16 v[4:7], v[152:155], v[192:195], 0
	v_mfma_f32_16x16x32_bf16 v[0:3], v[160:163], v[192:195], 0
	v_mfma_f32_16x16x32_bf16 v[40:43], v[156:159], v[172:175], v[40:43]
	v_mfma_f32_16x16x32_bf16 v[32:35], v[164:167], v[172:175], v[32:35]
	v_mfma_f32_16x16x32_bf16 v[24:27], v[156:159], v[180:183], v[24:27]
	v_mfma_f32_16x16x32_bf16 v[16:19], v[164:167], v[180:183], v[16:19]
	v_mfma_f32_16x16x32_bf16 v[12:15], v[156:159], v[188:191], v[12:15]
	v_mfma_f32_16x16x32_bf16 v[8:11], v[164:167], v[188:191], v[8:11]
	v_mfma_f32_16x16x32_bf16 v[4:7], v[156:159], v[206:209], v[4:7]
	v_mfma_f32_16x16x32_bf16 v[0:3], v[164:167], v[206:209], v[0:3]
	s_setprio 0
	s_barrier
	s_add_i32 s46, 0, 0x18000
	s_add_i32 s47, 0, 0x1c000
	v_add_u32_e32 v148, s46, v134
	v_add_u32_e32 v164, s47, v134
	ds_read_b128 v[136:139], v148
	ds_read_b128 v[140:143], v148 offset:1024
	ds_read_b128 v[144:147], v148 offset:2048
	ds_read_b128 v[148:151], v148 offset:3072
	ds_read_b128 v[152:155], v164
	ds_read_b128 v[156:159], v164 offset:1024
	ds_read_b128 v[160:163], v164 offset:2048
	ds_read_b128 v[164:167], v164 offset:3072
	s_add_u32 s22, s22, 0x40000
	s_addc_u32 s23, s23, 0
	s_mov_b32 m0, s33
	v_lshl_add_u64 v[218:219], s[22:23], 0, v[196:197]
	ds_read_b128 v[168:171], v135 offset:32768
	ds_read_b128 v[172:175], v135 offset:33792
	ds_read_b128 v[176:179], v135 offset:34816
	ds_read_b128 v[180:183], v135 offset:35840
	ds_read_b128 v[184:187], v135 offset:36864
	ds_read_b128 v[188:191], v135 offset:37888
	ds_read_b128 v[192:195], v135 offset:38912
	ds_read_b128 v[206:209], v135 offset:39936
	global_load_lds_dwordx4 v[218:219], off
	v_lshl_add_u64 v[218:219], s[22:23], 0, v[128:129]
	s_mov_b32 m0, s34
	s_nop 0
	global_load_lds_dwordx4 v[218:219], off
	s_waitcnt vmcnt(8)
	s_waitcnt lgkmcnt(0)
	s_barrier
	s_setprio 1
	s_waitcnt lgkmcnt(0)
	v_mfma_f32_16x16x32_bf16 v[124:127], v[136:139], v[168:171], v[124:127]
	v_mfma_f32_16x16x32_bf16 v[120:123], v[144:147], v[168:171], v[120:123]
	v_mfma_f32_16x16x32_bf16 v[116:119], v[136:139], v[176:179], v[116:119]
	v_mfma_f32_16x16x32_bf16 v[112:115], v[144:147], v[176:179], v[112:115]
	v_mfma_f32_16x16x32_bf16 v[108:111], v[136:139], v[184:187], v[108:111]
	v_mfma_f32_16x16x32_bf16 v[100:103], v[144:147], v[184:187], v[100:103]
	v_mfma_f32_16x16x32_bf16 v[92:95], v[136:139], v[192:195], v[92:95]
	v_mfma_f32_16x16x32_bf16 v[84:87], v[144:147], v[192:195], v[84:87]
	v_mfma_f32_16x16x32_bf16 v[124:127], v[140:143], v[172:175], v[124:127]
	v_mfma_f32_16x16x32_bf16 v[120:123], v[148:151], v[172:175], v[120:123]
	v_mfma_f32_16x16x32_bf16 v[116:119], v[140:143], v[180:183], v[116:119]
	v_mfma_f32_16x16x32_bf16 v[112:115], v[148:151], v[180:183], v[112:115]
	v_mfma_f32_16x16x32_bf16 v[108:111], v[140:143], v[188:191], v[108:111]
	v_mfma_f32_16x16x32_bf16 v[100:103], v[148:151], v[188:191], v[100:103]
	v_mfma_f32_16x16x32_bf16 v[92:95], v[140:143], v[206:209], v[92:95]
	v_mfma_f32_16x16x32_bf16 v[84:87], v[148:151], v[206:209], v[84:87]
	s_setprio 0
	s_setprio 1
	v_mfma_f32_16x16x32_bf16 v[104:107], v[152:155], v[168:171], v[104:107]
	v_mfma_f32_16x16x32_bf16 v[96:99], v[160:163], v[168:171], v[96:99]
	v_mfma_f32_16x16x32_bf16 v[88:91], v[152:155], v[176:179], v[88:91]
	v_mfma_f32_16x16x32_bf16 v[80:83], v[160:163], v[176:179], v[80:83]
	v_mfma_f32_16x16x32_bf16 v[76:79], v[152:155], v[184:187], v[76:79]
	v_mfma_f32_16x16x32_bf16 v[72:75], v[160:163], v[184:187], v[72:75]
	v_mfma_f32_16x16x32_bf16 v[68:71], v[152:155], v[192:195], v[68:71]
	v_mfma_f32_16x16x32_bf16 v[64:67], v[160:163], v[192:195], v[64:67]
	v_mfma_f32_16x16x32_bf16 v[104:107], v[156:159], v[172:175], v[104:107]
	v_mfma_f32_16x16x32_bf16 v[96:99], v[164:167], v[172:175], v[96:99]
	v_mfma_f32_16x16x32_bf16 v[88:91], v[156:159], v[180:183], v[88:91]
	v_mfma_f32_16x16x32_bf16 v[80:83], v[164:167], v[180:183], v[80:83]
	v_mfma_f32_16x16x32_bf16 v[76:79], v[156:159], v[188:191], v[76:79]
	v_mfma_f32_16x16x32_bf16 v[72:75], v[164:167], v[188:191], v[72:75]
	v_mfma_f32_16x16x32_bf16 v[68:71], v[156:159], v[206:209], v[68:71]
	v_mfma_f32_16x16x32_bf16 v[64:67], v[164:167], v[206:209], v[64:67]
	s_setprio 0
	s_barrier
; #define PG8_STAGE(bufoff, gbase, voff) do { _Pragma("unroll") for (int _i = 0; _i < 2; ++_i) \
;         __builtin_amdgcn_global_load_lds((const unsigned*)((const char*)(gbase) + (voff)[_i]), (PG8_LAS unsigned*)(lds + (bufoff) + ldsw + _i * 8192), 16, 0, 0); } while (0)
; #define PG8_LDA(dst, b, h) do { _Pragma("unroll") for (int m = 0; m < 4; ++m) _Pragma("unroll") for (int k = 0; k < 2; ++k) dst[m][k] = *(const PG8_LAS bf16x8*)(lds + PG8_SA(b, h) + aoff + m * 2048 + k * 1024); } while (0)
; #define PG8_MMA(ai, bj, At, Bt) do { __builtin_amdgcn_s_setprio(1); _Pragma("unroll") for (int m = 0; m < 4; ++m) _Pragma("unroll") for (int n = 0; n < 2; ++n) _Pragma("unroll") for (int k = 0; k < 2; ++k) \
;         acc[ai][bj][m][n] = __builtin_amdgcn_mfma_f32_16x16x32_bf16(Bt[n][k], At[m][k], acc[ai][bj][m][n], 0, 0, 0); __builtin_amdgcn_s_setprio(0); } while (0)
; #define PG8_WAIT_V(n) asm volatile("s_waitcnt vmcnt(" #n ")" ::: "memory")
; #define PG8_WAIT_L(n) asm volatile("s_waitcnt lgkmcnt(" #n ")" ::: "memory")
; #define PG8_BAR __builtin_amdgcn_s_barrier()
; #define PG8_SCHED __builtin_amdgcn_sched_barrier(0)
; template <class Epi, class Sched, bool ALIGN_EPI = false, bool SP2 = false>
; __device__ __forceinline__ void gemm_phase(PG8_LAS unsigned char* lds, const Gemm g, const Sched& S, const Epi& E, int wave_s_) {
;     ...
;         for (int t = 0; t < nt; t += 2) {
;     ...
;             PG8_LDA(At, 1, 1); PG8_STAGE(PG8_SB(1, 0), b3, voffB); PG8_STAGE(PG8_SB(1, 1), b3 + hstep, voffB); PG8_STAGE(PG8_SA(1, 0), a3, voffA);
;             PG8_WAIT_V(8); PG8_WAIT_L(0); PG8_BAR; PG8_MMA(1, 0, At, B0); PG8_MMA(1, 1, At, B1); PG8_BAR; PG8_SCHED;
	s_add_i32 s22, s46, s29
	v_lshl_add_u64 v[210:211], v[210:211], 0, s[76:77]
	s_mov_b32 m0, s22
	ds_read_b128 v[168:171], v135 offset:49152
	ds_read_b128 v[172:175], v135 offset:50176
	ds_read_b128 v[176:179], v135 offset:51200
	ds_read_b128 v[180:183], v135 offset:52224
	ds_read_b128 v[184:187], v135 offset:53248
	ds_read_b128 v[188:191], v135 offset:54272
	ds_read_b128 v[192:195], v135 offset:55296
	ds_read_b128 v[206:209], v135 offset:56320
	global_load_lds_dwordx4 v[210:211], off
	s_add_i32 m0, s22, 0x2000
	s_add_u32 s20, s20, 0x40080
	v_lshl_add_u64 v[210:211], v[212:213], 0, s[76:77]
	s_addc_u32 s21, s21, 0
	s_add_i32 s22, s47, s29
	global_load_lds_dwordx4 v[210:211], off
	v_lshl_add_u64 v[210:211], s[20:21], 0, v[196:197]
	s_mov_b32 m0, s22
	s_nop 0
	global_load_lds_dwordx4 v[210:211], off
	v_lshl_add_u64 v[210:211], s[20:21], 0, v[128:129]
	s_add_i32 m0, s22, 0x2000
	s_nop 0
	global_load_lds_dwordx4 v[210:211], off
	v_lshl_add_u64 v[210:211], v[214:215], 0, s[76:77]
	s_mov_b32 m0, s38
	s_nop 0
	global_load_lds_dwordx4 v[210:211], off
	v_lshl_add_u64 v[210:211], v[216:217], 0, s[76:77]
	s_mov_b32 m0, s39
	s_nop 0
	global_load_lds_dwordx4 v[210:211], off
	s_waitcnt vmcnt(8)
	s_waitcnt lgkmcnt(0)
	s_barrier
	s_setprio 1
	s_waitcnt lgkmcnt(0)
	v_mfma_f32_16x16x32_bf16 v[60:63], v[136:139], v[168:171], v[60:63]
	v_mfma_f32_16x16x32_bf16 v[56:59], v[144:147], v[168:171], v[56:59]
	v_mfma_f32_16x16x32_bf16 v[52:55], v[136:139], v[176:179], v[52:55]
	v_mfma_f32_16x16x32_bf16 v[48:51], v[144:147], v[176:179], v[48:51]
	v_mfma_f32_16x16x32_bf16 v[44:47], v[136:139], v[184:187], v[44:47]
	v_mfma_f32_16x16x32_bf16 v[36:39], v[144:147], v[184:187], v[36:39]
	v_mfma_f32_16x16x32_bf16 v[28:31], v[136:139], v[192:195], v[28:31]
	v_mfma_f32_16x16x32_bf16 v[20:23], v[144:147], v[192:195], v[20:23]
	v_mfma_f32_16x16x32_bf16 v[60:63], v[140:143], v[172:175], v[60:63]
	v_mfma_f32_16x16x32_bf16 v[56:59], v[148:151], v[172:175], v[56:59]
	v_mfma_f32_16x16x32_bf16 v[52:55], v[140:143], v[180:183], v[52:55]
	v_mfma_f32_16x16x32_bf16 v[48:51], v[148:151], v[180:183], v[48:51]
	v_mfma_f32_16x16x32_bf16 v[44:47], v[140:143], v[188:191], v[44:47]
	v_mfma_f32_16x16x32_bf16 v[36:39], v[148:151], v[188:191], v[36:39]
	v_mfma_f32_16x16x32_bf16 v[28:31], v[140:143], v[206:209], v[28:31]
	v_mfma_f32_16x16x32_bf16 v[20:23], v[148:151], v[206:209], v[20:23]
	s_setprio 0
	s_setprio 1
	v_mfma_f32_16x16x32_bf16 v[40:43], v[152:155], v[168:171], v[40:43]
	v_mfma_f32_16x16x32_bf16 v[32:35], v[160:163], v[168:171], v[32:35]
	v_mfma_f32_16x16x32_bf16 v[24:27], v[152:155], v[176:179], v[24:27]
	v_mfma_f32_16x16x32_bf16 v[16:19], v[160:163], v[176:179], v[16:19]
	v_mfma_f32_16x16x32_bf16 v[12:15], v[152:155], v[184:187], v[12:15]
	v_mfma_f32_16x16x32_bf16 v[8:11], v[160:163], v[184:187], v[8:11]
	v_mfma_f32_16x16x32_bf16 v[4:7], v[152:155], v[192:195], v[4:7]
	v_mfma_f32_16x16x32_bf16 v[0:3], v[160:163], v[192:195], v[0:3]
	v_mfma_f32_16x16x32_bf16 v[40:43], v[156:159], v[172:175], v[40:43]
	v_mfma_f32_16x16x32_bf16 v[32:35], v[164:167], v[172:175], v[32:35]
	v_mfma_f32_16x16x32_bf16 v[24:27], v[156:159], v[180:183], v[24:27]
	v_mfma_f32_16x16x32_bf16 v[16:19], v[164:167], v[180:183], v[16:19]
	v_mfma_f32_16x16x32_bf16 v[12:15], v[156:159], v[188:191], v[12:15]
	v_mfma_f32_16x16x32_bf16 v[8:11], v[164:167], v[188:191], v[8:11]
	v_mfma_f32_16x16x32_bf16 v[4:7], v[156:159], v[206:209], v[4:7]
	v_mfma_f32_16x16x32_bf16 v[0:3], v[164:167], v[206:209], v[0:3]
	s_setprio 0
	s_barrier
	s_add_i32 s45, s45, 2
	s_add_u32 s18, s18, 0x100
	s_addc_u32 s19, s19, 0
	s_add_u32 s15, s15, 0x100
	s_addc_u32 s44, s44, 0
	s_cmp_gt_u32 s45, 13
	s_cbranch_scc0 .LBB0_1185
	s_branch .Lpeel_exit_3

; #define PG8_BAR __builtin_amdgcn_s_barrier()
; template <class Epi, class Sched, bool ALIGN_EPI = false, bool SP2 = false>
; __device__ __forceinline__ void gemm_phase(PG8_LAS unsigned char* lds, const Gemm g, const Sched& S, const Epi& E, int wave_s_) {
;     ...
;         if constexpr (ALIGN_EPI) { if (wr == 0) PG8_BAR; }
.Lpeel_exit_3:
	s_and_b64 vcc, exec, s[12:13]
	s_cbranch_vccz .LBB0_1188
	s_barrier

; #define PG8_STAGE(bufoff, gbase, voff) do { _Pragma("unroll") for (int _i = 0; _i < 2; ++_i) \
;         __builtin_amdgcn_global_load_lds((const unsigned*)((const char*)(gbase) + (voff)[_i]), (PG8_LAS unsigned*)(lds + (bufoff) + ldsw + _i * 8192), 16, 0, 0); } while (0)
; #define PG8_LDA(dst, b, h) do { _Pragma("unroll") for (int m = 0; m < 4; ++m) _Pragma("unroll") for (int k = 0; k < 2; ++k) dst[m][k] = *(const PG8_LAS bf16x8*)(lds + PG8_SA(b, h) + aoff + m * 2048 + k * 1024); } while (0)
; #define PG8_LDB(dst, b, h) do { _Pragma("unroll") for (int n = 0; n < 2; ++n) _Pragma("unroll") for (int k = 0; k < 2; ++k) dst[n][k] = *(const PG8_LAS bf16x8*)(lds + PG8_SB(b, h) + boff + n * 2048 + k * 1024); } while (0)
; #define PG8_MMA(ai, bj, At, Bt) do { __builtin_amdgcn_s_setprio(1); _Pragma("unroll") for (int m = 0; m < 4; ++m) _Pragma("unroll") for (int n = 0; n < 2; ++n) _Pragma("unroll") for (int k = 0; k < 2; ++k) \
;         acc[ai][bj][m][n] = __builtin_amdgcn_mfma_f32_16x16x32_bf16(Bt[n][k], At[m][k], acc[ai][bj][m][n], 0, 0, 0); __builtin_amdgcn_s_setprio(0); } while (0)
; #define PG8_WAIT_V(n) asm volatile("s_waitcnt vmcnt(" #n ")" ::: "memory")
; #define PG8_BAR __builtin_amdgcn_s_barrier()
; template <class Epi, class Sched, bool ALIGN_EPI = false, bool SP2 = false>
; __device__ __forceinline__ void gemm_phase(PG8_LAS unsigned char* lds, const Gemm g, const Sched& S, const Epi& E, int wave_s_) {
;     ...
;         for (int t = 0; t < nt; t += 2) {
;             const bool last = (t == nt - 2);
;             const char* a1 = cA + (size_t)(t + 1) * kstep;
;             const char* a2 = last ? nA : cA + (size_t)(t + 2) * kstep; const char* b2 = last ? nB : cB + (size_t)(t + 2) * kstep;
;             const char* a3 = a2 + kstep; const char* b3 = b2 + kstep;
;             if (last && has_next) S.a_ready(nxt);
;             if constexpr (SP2) {
;             PG8_LDB(B0, 0, 0); PG8_LDB(B1, 0, 1); PG8_SCHED; PG8_LDA(At, 0, 0); PG8_STAGE(PG8_SA(1, 1), a1 + hstep, voffA);
;             PG8_WAIT_V(8); PG8_WAIT_L(0); PG8_BAR; PG8_MMA(0, 0, At, B0); PG8_MMA(0, 1, At, B1); PG8_BAR; PG8_SCHED;
;             PG8_LDA(At, 0, 1); PG8_STAGE(PG8_SB(0, 0), b2, voffB); PG8_STAGE(PG8_SB(0, 1), b2 + hstep, voffB); PG8_STAGE(PG8_SA(0, 0), a2, voffA);
;             PG8_WAIT_V(8); PG8_WAIT_L(0); PG8_BAR; PG8_MMA(1, 0, At, B0); PG8_MMA(1, 1, At, B1); PG8_BAR; PG8_SCHED;
.LBB0_1337:
	s_add_u32 s45, s18, 0x100
	v_mov_b32_e32 v0, 0
	s_addc_u32 s46, s19, 0
	s_mov_b32 s47, -2
	s_add_u32 s18, s16, 0x100
	s_addc_u32 s19, s17, 0
	s_add_i32 s48, 0, 0x10000
	s_cmp_eq_u32 s47, 2
	s_cselect_b32 s23, s7, s19
	s_cselect_b32 s22, s6, s18
	s_cselect_b32 s21, s15, s46
	s_cselect_b32 s20, s14, s45
	s_add_i32 s49, 0, 0x14000
	v_add_u32_e32 v152, s48, v142
	v_add_u32_e32 v168, s49, v142
	ds_read_b128 v[138:141], v152
	ds_read_b128 v[144:147], v152 offset:1024
	ds_read_b128 v[148:151], v152 offset:2048
	ds_read_b128 v[152:155], v152 offset:3072
	ds_read_b128 v[156:159], v168
	ds_read_b128 v[160:163], v168 offset:1024
	ds_read_b128 v[164:167], v168 offset:2048
	ds_read_b128 v[168:171], v168 offset:3072
	v_lshl_add_u64 v[214:215], s[16:17], 0, v[134:135]
	s_add_i32 m0, s30, 0xc000
	ds_read_b128 v[172:175], v143
	ds_read_b128 v[176:179], v143 offset:1024
	ds_read_b128 v[180:183], v143 offset:2048
	ds_read_b128 v[184:187], v143 offset:3072
	ds_read_b128 v[188:191], v143 offset:4096
	ds_read_b128 v[192:195], v143 offset:5120
	ds_read_b128 v[206:209], v143 offset:6144
	ds_read_b128 v[210:213], v143 offset:7168
	global_load_lds_dwordx4 v[214:215], off
	v_lshl_add_u64 v[214:215], s[16:17], 0, v[136:137]
	s_add_i32 m0, s30, 0xe000
	s_nop 0
	global_load_lds_dwordx4 v[214:215], off
	s_waitcnt vmcnt(8)
	s_waitcnt lgkmcnt(0)
	s_barrier
	s_setprio 1
	s_waitcnt lgkmcnt(0)
	v_mfma_f32_16x16x32_bf16 v[124:127], v[138:141], v[172:175], 0
	v_mfma_f32_16x16x32_bf16 v[120:123], v[148:151], v[172:175], 0
	v_mfma_f32_16x16x32_bf16 v[116:119], v[138:141], v[180:183], 0
	v_mfma_f32_16x16x32_bf16 v[108:111], v[148:151], v[180:183], 0
	v_mfma_f32_16x16x32_bf16 v[100:103], v[138:141], v[188:191], 0
	v_mfma_f32_16x16x32_bf16 v[92:95], v[148:151], v[188:191], 0
	v_mfma_f32_16x16x32_bf16 v[84:87], v[138:141], v[206:209], 0
	v_mfma_f32_16x16x32_bf16 v[76:79], v[148:151], v[206:209], 0
	v_mfma_f32_16x16x32_bf16 v[124:127], v[144:147], v[176:179], v[124:127]
	v_mfma_f32_16x16x32_bf16 v[120:123], v[152:155], v[176:179], v[120:123]
	v_mfma_f32_16x16x32_bf16 v[116:119], v[144:147], v[184:187], v[116:119]
	v_mfma_f32_16x16x32_bf16 v[108:111], v[152:155], v[184:187], v[108:111]
	v_mfma_f32_16x16x32_bf16 v[100:103], v[144:147], v[192:195], v[100:103]
	v_mfma_f32_16x16x32_bf16 v[92:95], v[152:155], v[192:195], v[92:95]
	v_mfma_f32_16x16x32_bf16 v[84:87], v[144:147], v[210:213], v[84:87]
	v_mfma_f32_16x16x32_bf16 v[76:79], v[152:155], v[210:213], v[76:79]
	s_setprio 0
	s_setprio 1
	v_mfma_f32_16x16x32_bf16 v[112:115], v[156:159], v[172:175], 0
	v_mfma_f32_16x16x32_bf16 v[104:107], v[164:167], v[172:175], 0
	v_mfma_f32_16x16x32_bf16 v[96:99], v[156:159], v[180:183], 0
	v_mfma_f32_16x16x32_bf16 v[88:91], v[164:167], v[180:183], 0
	v_mfma_f32_16x16x32_bf16 v[80:83], v[156:159], v[188:191], 0
	v_mfma_f32_16x16x32_bf16 v[72:75], v[164:167], v[188:191], 0
	v_mfma_f32_16x16x32_bf16 v[68:71], v[156:159], v[206:209], 0
	v_mfma_f32_16x16x32_bf16 v[64:67], v[164:167], v[206:209], 0
	v_mfma_f32_16x16x32_bf16 v[112:115], v[160:163], v[176:179], v[112:115]
	v_mfma_f32_16x16x32_bf16 v[104:107], v[168:171], v[176:179], v[104:107]
	v_mfma_f32_16x16x32_bf16 v[96:99], v[160:163], v[184:187], v[96:99]
	v_mfma_f32_16x16x32_bf16 v[88:91], v[168:171], v[184:187], v[88:91]
	v_mfma_f32_16x16x32_bf16 v[80:83], v[160:163], v[192:195], v[80:83]
	v_mfma_f32_16x16x32_bf16 v[72:75], v[168:171], v[192:195], v[72:75]
	v_mfma_f32_16x16x32_bf16 v[68:71], v[160:163], v[210:213], v[68:71]
	v_mfma_f32_16x16x32_bf16 v[64:67], v[168:171], v[210:213], v[64:67]
	s_setprio 0
	s_barrier
	s_add_i32 s16, s48, s29
	v_lshl_add_u64 v[214:215], s[20:21], 0, v[196:197]
	s_mov_b32 m0, s16
	ds_read_b128 v[172:175], v143 offset:16384
	ds_read_b128 v[176:179], v143 offset:17408
	ds_read_b128 v[180:183], v143 offset:18432
	ds_read_b128 v[184:187], v143 offset:19456
	ds_read_b128 v[188:191], v143 offset:20480
	ds_read_b128 v[192:195], v143 offset:21504
	ds_read_b128 v[206:209], v143 offset:22528
	ds_read_b128 v[210:213], v143 offset:23552
	global_load_lds_dwordx4 v[214:215], off
	s_add_i32 m0, s16, 0x2000
	s_add_u32 s16, s20, 0x18000
	v_lshl_add_u64 v[216:217], s[20:21], 0, v[132:133]
	s_addc_u32 s17, s21, 0
	s_add_i32 s48, s49, s29
	global_load_lds_dwordx4 v[216:217], off
	v_lshl_add_u64 v[218:219], s[16:17], 0, v[196:197]
	s_mov_b32 m0, s48
	v_lshl_add_u64 v[220:221], s[22:23], 0, v[130:131]
	global_load_lds_dwordx4 v[218:219], off
	v_lshl_add_u64 v[218:219], s[16:17], 0, v[132:133]
	s_add_i32 m0, s48, 0x2000
	s_nop 0
	global_load_lds_dwordx4 v[218:219], off
	v_lshl_add_u64 v[218:219], s[22:23], 0, v[128:129]
	s_mov_b32 m0, s30
	s_nop 0
	global_load_lds_dwordx4 v[218:219], off
	s_mov_b32 m0, s31
	s_nop 0
	global_load_lds_dwordx4 v[220:221], off
	s_waitcnt vmcnt(8)
	s_waitcnt lgkmcnt(0)
	s_barrier
; #define PG8_STAGE(bufoff, gbase, voff) do { _Pragma("unroll") for (int _i = 0; _i < 2; ++_i) \
;         __builtin_amdgcn_global_load_lds((const unsigned*)((const char*)(gbase) + (voff)[_i]), (PG8_LAS unsigned*)(lds + (bufoff) + ldsw + _i * 8192), 16, 0, 0); } while (0)
; #define PG8_LDA(dst, b, h) do { _Pragma("unroll") for (int m = 0; m < 4; ++m) _Pragma("unroll") for (int k = 0; k < 2; ++k) dst[m][k] = *(const PG8_LAS bf16x8*)(lds + PG8_SA(b, h) + aoff + m * 2048 + k * 1024); } while (0)
; #define PG8_LDB(dst, b, h) do { _Pragma("unroll") for (int n = 0; n < 2; ++n) _Pragma("unroll") for (int k = 0; k < 2; ++k) dst[n][k] = *(const PG8_LAS bf16x8*)(lds + PG8_SB(b, h) + boff + n * 2048 + k * 1024); } while (0)
; #define PG8_MMA(ai, bj, At, Bt) do { __builtin_amdgcn_s_setprio(1); _Pragma("unroll") for (int m = 0; m < 4; ++m) _Pragma("unroll") for (int n = 0; n < 2; ++n) _Pragma("unroll") for (int k = 0; k < 2; ++k) \
;         acc[ai][bj][m][n] = __builtin_amdgcn_mfma_f32_16x16x32_bf16(Bt[n][k], At[m][k], acc[ai][bj][m][n], 0, 0, 0); __builtin_amdgcn_s_setprio(0); } while (0)
; #define PG8_WAIT_V(n) asm volatile("s_waitcnt vmcnt(" #n ")" ::: "memory")
; #define PG8_WAIT_L(n) asm volatile("s_waitcnt lgkmcnt(" #n ")" ::: "memory")
; #define PG8_BAR __builtin_amdgcn_s_barrier()
; #define PG8_SCHED __builtin_amdgcn_sched_barrier(0)
; template <class Epi, class Sched, bool ALIGN_EPI = false, bool SP2 = false>
; __device__ __forceinline__ void gemm_phase(PG8_LAS unsigned char* lds, const Gemm g, const Sched& S, const Epi& E, int wave_s_) {
;     ...
;             PG8_WAIT_V(8); PG8_WAIT_L(0); PG8_BAR; PG8_MMA(1, 0, At, B0); PG8_MMA(1, 1, At, B1); PG8_BAR; PG8_SCHED;
;             PG8_LDB(B0, 1, 0); PG8_LDB(B1, 1, 1); PG8_SCHED; PG8_LDA(At, 1, 0); PG8_STAGE(PG8_SA(0, 1), a2 + hstep, voffA);
;             PG8_WAIT_V(8); PG8_WAIT_L(0); PG8_BAR; PG8_MMA(0, 0, At, B0); PG8_MMA(0, 1, At, B1); PG8_BAR; PG8_SCHED;
	s_setprio 1
	s_waitcnt lgkmcnt(0)
	v_mfma_f32_16x16x32_bf16 v[60:63], v[138:141], v[172:175], 0
	v_mfma_f32_16x16x32_bf16 v[56:59], v[148:151], v[172:175], 0
	v_mfma_f32_16x16x32_bf16 v[52:55], v[138:141], v[180:183], 0
	v_mfma_f32_16x16x32_bf16 v[44:47], v[148:151], v[180:183], 0
	v_mfma_f32_16x16x32_bf16 v[36:39], v[138:141], v[188:191], 0
	v_mfma_f32_16x16x32_bf16 v[28:31], v[148:151], v[188:191], 0
	v_mfma_f32_16x16x32_bf16 v[20:23], v[138:141], v[206:209], 0
	v_mfma_f32_16x16x32_bf16 v[12:15], v[148:151], v[206:209], 0
	v_mfma_f32_16x16x32_bf16 v[60:63], v[144:147], v[176:179], v[60:63]
	v_mfma_f32_16x16x32_bf16 v[56:59], v[152:155], v[176:179], v[56:59]
	v_mfma_f32_16x16x32_bf16 v[52:55], v[144:147], v[184:187], v[52:55]
	v_mfma_f32_16x16x32_bf16 v[44:47], v[152:155], v[184:187], v[44:47]
	v_mfma_f32_16x16x32_bf16 v[36:39], v[144:147], v[192:195], v[36:39]
	v_mfma_f32_16x16x32_bf16 v[28:31], v[152:155], v[192:195], v[28:31]
	v_mfma_f32_16x16x32_bf16 v[20:23], v[144:147], v[210:213], v[20:23]
	v_mfma_f32_16x16x32_bf16 v[12:15], v[152:155], v[210:213], v[12:15]
	s_setprio 0
	s_setprio 1
	v_mfma_f32_16x16x32_bf16 v[48:51], v[156:159], v[172:175], 0
	v_mfma_f32_16x16x32_bf16 v[40:43], v[164:167], v[172:175], 0
	v_mfma_f32_16x16x32_bf16 v[32:35], v[156:159], v[180:183], 0
	v_mfma_f32_16x16x32_bf16 v[24:27], v[164:167], v[180:183], 0
	v_mfma_f32_16x16x32_bf16 v[16:19], v[156:159], v[188:191], 0
	v_mfma_f32_16x16x32_bf16 v[8:11], v[164:167], v[188:191], 0
	v_mfma_f32_16x16x32_bf16 v[4:7], v[156:159], v[206:209], 0
	v_mfma_f32_16x16x32_bf16 v[0:3], v[164:167], v[206:209], 0
	v_mfma_f32_16x16x32_bf16 v[48:51], v[160:163], v[176:179], v[48:51]
	v_mfma_f32_16x16x32_bf16 v[40:43], v[168:171], v[176:179], v[40:43]
	v_mfma_f32_16x16x32_bf16 v[32:35], v[160:163], v[184:187], v[32:35]
	v_mfma_f32_16x16x32_bf16 v[24:27], v[168:171], v[184:187], v[24:27]
	v_mfma_f32_16x16x32_bf16 v[16:19], v[160:163], v[192:195], v[16:19]
	v_mfma_f32_16x16x32_bf16 v[8:11], v[168:171], v[192:195], v[8:11]
	v_mfma_f32_16x16x32_bf16 v[4:7], v[160:163], v[210:213], v[4:7]
	v_mfma_f32_16x16x32_bf16 v[0:3], v[168:171], v[210:213], v[0:3]
	s_setprio 0
	s_barrier
	s_add_i32 s48, 0, 0x18000
	s_add_i32 s49, 0, 0x1c000
	v_add_u32_e32 v152, s48, v142
	v_add_u32_e32 v168, s49, v142
	ds_read_b128 v[138:141], v152
	ds_read_b128 v[144:147], v152 offset:1024
	ds_read_b128 v[148:151], v152 offset:2048
	ds_read_b128 v[152:155], v152 offset:3072
	ds_read_b128 v[156:159], v168
	ds_read_b128 v[160:163], v168 offset:1024
	ds_read_b128 v[164:167], v168 offset:2048
	ds_read_b128 v[168:171], v168 offset:3072
	s_add_u32 s16, s22, 0x18000
	s_addc_u32 s17, s23, 0
	s_mov_b32 m0, s33
	v_lshl_add_u64 v[222:223], s[16:17], 0, v[128:129]
	ds_read_b128 v[172:175], v143 offset:32768
	ds_read_b128 v[176:179], v143 offset:33792
	ds_read_b128 v[180:183], v143 offset:34816
	ds_read_b128 v[184:187], v143 offset:35840
	ds_read_b128 v[188:191], v143 offset:36864
	ds_read_b128 v[192:195], v143 offset:37888
	ds_read_b128 v[206:209], v143 offset:38912
	ds_read_b128 v[210:213], v143 offset:39936
	global_load_lds_dwordx4 v[222:223], off
	v_lshl_add_u64 v[222:223], s[16:17], 0, v[130:131]
	s_mov_b32 m0, s34
	s_nop 0
	global_load_lds_dwordx4 v[222:223], off
	s_waitcnt vmcnt(8)
	s_waitcnt lgkmcnt(0)
	s_barrier
	s_setprio 1
	s_waitcnt lgkmcnt(0)
	v_mfma_f32_16x16x32_bf16 v[124:127], v[138:141], v[172:175], v[124:127]
	v_mfma_f32_16x16x32_bf16 v[120:123], v[148:151], v[172:175], v[120:123]
	v_mfma_f32_16x16x32_bf16 v[116:119], v[138:141], v[180:183], v[116:119]
	v_mfma_f32_16x16x32_bf16 v[108:111], v[148:151], v[180:183], v[108:111]
	v_mfma_f32_16x16x32_bf16 v[100:103], v[138:141], v[188:191], v[100:103]
	v_mfma_f32_16x16x32_bf16 v[92:95], v[148:151], v[188:191], v[92:95]
	v_mfma_f32_16x16x32_bf16 v[84:87], v[138:141], v[206:209], v[84:87]
	v_mfma_f32_16x16x32_bf16 v[76:79], v[148:151], v[206:209], v[76:79]
	v_mfma_f32_16x16x32_bf16 v[124:127], v[144:147], v[176:179], v[124:127]
	v_mfma_f32_16x16x32_bf16 v[120:123], v[152:155], v[176:179], v[120:123]
	v_mfma_f32_16x16x32_bf16 v[116:119], v[144:147], v[184:187], v[116:119]
	v_mfma_f32_16x16x32_bf16 v[108:111], v[152:155], v[184:187], v[108:111]
	v_mfma_f32_16x16x32_bf16 v[100:103], v[144:147], v[192:195], v[100:103]
	v_mfma_f32_16x16x32_bf16 v[92:95], v[152:155], v[192:195], v[92:95]
	v_mfma_f32_16x16x32_bf16 v[84:87], v[144:147], v[210:213], v[84:87]
	v_mfma_f32_16x16x32_bf16 v[76:79], v[152:155], v[210:213], v[76:79]
	s_setprio 0
	s_setprio 1
	v_mfma_f32_16x16x32_bf16 v[112:115], v[156:159], v[172:175], v[112:115]
	v_mfma_f32_16x16x32_bf16 v[104:107], v[164:167], v[172:175], v[104:107]
	v_mfma_f32_16x16x32_bf16 v[96:99], v[156:159], v[180:183], v[96:99]
	v_mfma_f32_16x16x32_bf16 v[88:91], v[164:167], v[180:183], v[88:91]
	v_mfma_f32_16x16x32_bf16 v[80:83], v[156:159], v[188:191], v[80:83]
	v_mfma_f32_16x16x32_bf16 v[72:75], v[164:167], v[188:191], v[72:75]
	v_mfma_f32_16x16x32_bf16 v[68:71], v[156:159], v[206:209], v[68:71]
	v_mfma_f32_16x16x32_bf16 v[64:67], v[164:167], v[206:209], v[64:67]
	v_mfma_f32_16x16x32_bf16 v[112:115], v[160:163], v[176:179], v[112:115]
	v_mfma_f32_16x16x32_bf16 v[104:107], v[168:171], v[176:179], v[104:107]
	v_mfma_f32_16x16x32_bf16 v[96:99], v[160:163], v[184:187], v[96:99]
	v_mfma_f32_16x16x32_bf16 v[88:91], v[168:171], v[184:187], v[88:91]
	v_mfma_f32_16x16x32_bf16 v[80:83], v[160:163], v[192:195], v[80:83]
	v_mfma_f32_16x16x32_bf16 v[72:75], v[168:171], v[192:195], v[72:75]
	v_mfma_f32_16x16x32_bf16 v[68:71], v[160:163], v[210:213], v[68:71]
	v_mfma_f32_16x16x32_bf16 v[64:67], v[168:171], v[210:213], v[64:67]
	s_setprio 0
	s_barrier
; #define PG8_STAGE(bufoff, gbase, voff) do { _Pragma("unroll") for (int _i = 0; _i < 2; ++_i) \
;         __builtin_amdgcn_global_load_lds((const unsigned*)((const char*)(gbase) + (voff)[_i]), (PG8_LAS unsigned*)(lds + (bufoff) + ldsw + _i * 8192), 16, 0, 0); } while (0)
; #define PG8_LDA(dst, b, h) do { _Pragma("unroll") for (int m = 0; m < 4; ++m) _Pragma("unroll") for (int k = 0; k < 2; ++k) dst[m][k] = *(const PG8_LAS bf16x8*)(lds + PG8_SA(b, h) + aoff + m * 2048 + k * 1024); } while (0)
; #define PG8_MMA(ai, bj, At, Bt) do { __builtin_amdgcn_s_setprio(1); _Pragma("unroll") for (int m = 0; m < 4; ++m) _Pragma("unroll") for (int n = 0; n < 2; ++n) _Pragma("unroll") for (int k = 0; k < 2; ++k) \
;         acc[ai][bj][m][n] = __builtin_amdgcn_mfma_f32_16x16x32_bf16(Bt[n][k], At[m][k], acc[ai][bj][m][n], 0, 0, 0); __builtin_amdgcn_s_setprio(0); } while (0)
; #define PG8_WAIT_V(n) asm volatile("s_waitcnt vmcnt(" #n ")" ::: "memory")
; #define PG8_WAIT_L(n) asm volatile("s_waitcnt lgkmcnt(" #n ")" ::: "memory")
; #define PG8_BAR __builtin_amdgcn_s_barrier()
; #define PG8_SCHED __builtin_amdgcn_sched_barrier(0)
; template <class Epi, class Sched, bool ALIGN_EPI = false, bool SP2 = false>
; __device__ __forceinline__ void gemm_phase(PG8_LAS unsigned char* lds, const Gemm g, const Sched& S, const Epi& E, int wave_s_) {
;     ...
;         for (int t = 0; t < nt; t += 2) {
;     ...
;             PG8_LDA(At, 1, 1); PG8_STAGE(PG8_SB(1, 0), b3, voffB); PG8_STAGE(PG8_SB(1, 1), b3 + hstep, voffB); PG8_STAGE(PG8_SA(1, 0), a3, voffA);
;             PG8_WAIT_V(8); PG8_WAIT_L(0); PG8_BAR; PG8_MMA(1, 0, At, B0); PG8_MMA(1, 1, At, B1); PG8_BAR; PG8_SCHED;
	s_add_i32 s16, s48, s29
	v_lshl_add_u64 v[214:215], v[214:215], 0, s[76:77]
	s_mov_b32 m0, s16
	ds_read_b128 v[172:175], v143 offset:49152
	ds_read_b128 v[176:179], v143 offset:50176
	ds_read_b128 v[180:183], v143 offset:51200
	ds_read_b128 v[184:187], v143 offset:52224
	ds_read_b128 v[188:191], v143 offset:53248
	ds_read_b128 v[192:195], v143 offset:54272
	ds_read_b128 v[206:209], v143 offset:55296
	ds_read_b128 v[210:213], v143 offset:56320
	global_load_lds_dwordx4 v[214:215], off
	s_add_i32 m0, s16, 0x2000
	s_add_u32 s16, s20, 0x18080
	v_lshl_add_u64 v[214:215], v[216:217], 0, s[76:77]
	s_addc_u32 s17, s21, 0
	s_add_i32 s20, s49, s29
	global_load_lds_dwordx4 v[214:215], off
	v_lshl_add_u64 v[214:215], s[16:17], 0, v[196:197]
	s_mov_b32 m0, s20
	s_nop 0
	global_load_lds_dwordx4 v[214:215], off
	v_lshl_add_u64 v[214:215], s[16:17], 0, v[132:133]
	s_add_i32 m0, s20, 0x2000
	s_nop 0
	global_load_lds_dwordx4 v[214:215], off
	v_lshl_add_u64 v[214:215], v[218:219], 0, s[76:77]
	s_mov_b32 m0, s37
	s_nop 0
	global_load_lds_dwordx4 v[214:215], off
	v_lshl_add_u64 v[214:215], v[220:221], 0, s[76:77]
	s_mov_b32 m0, s38
	s_nop 0
	global_load_lds_dwordx4 v[214:215], off
	s_waitcnt vmcnt(8)
	s_waitcnt lgkmcnt(0)
	s_barrier
	s_setprio 1
	s_waitcnt lgkmcnt(0)
	v_mfma_f32_16x16x32_bf16 v[60:63], v[138:141], v[172:175], v[60:63]
	v_mfma_f32_16x16x32_bf16 v[56:59], v[148:151], v[172:175], v[56:59]
	v_mfma_f32_16x16x32_bf16 v[52:55], v[138:141], v[180:183], v[52:55]
	v_mfma_f32_16x16x32_bf16 v[44:47], v[148:151], v[180:183], v[44:47]
	v_mfma_f32_16x16x32_bf16 v[36:39], v[138:141], v[188:191], v[36:39]
	v_mfma_f32_16x16x32_bf16 v[28:31], v[148:151], v[188:191], v[28:31]
	v_mfma_f32_16x16x32_bf16 v[20:23], v[138:141], v[206:209], v[20:23]
	v_mfma_f32_16x16x32_bf16 v[12:15], v[148:151], v[206:209], v[12:15]
	v_mfma_f32_16x16x32_bf16 v[60:63], v[144:147], v[176:179], v[60:63]
	v_mfma_f32_16x16x32_bf16 v[56:59], v[152:155], v[176:179], v[56:59]
	v_mfma_f32_16x16x32_bf16 v[52:55], v[144:147], v[184:187], v[52:55]
	v_mfma_f32_16x16x32_bf16 v[44:47], v[152:155], v[184:187], v[44:47]
	v_mfma_f32_16x16x32_bf16 v[36:39], v[144:147], v[192:195], v[36:39]
	v_mfma_f32_16x16x32_bf16 v[28:31], v[152:155], v[192:195], v[28:31]
	v_mfma_f32_16x16x32_bf16 v[20:23], v[144:147], v[210:213], v[20:23]
	v_mfma_f32_16x16x32_bf16 v[12:15], v[152:155], v[210:213], v[12:15]
	s_setprio 0
	s_setprio 1
	v_mfma_f32_16x16x32_bf16 v[48:51], v[156:159], v[172:175], v[48:51]
	v_mfma_f32_16x16x32_bf16 v[40:43], v[164:167], v[172:175], v[40:43]
	v_mfma_f32_16x16x32_bf16 v[32:35], v[156:159], v[180:183], v[32:35]
	v_mfma_f32_16x16x32_bf16 v[24:27], v[164:167], v[180:183], v[24:27]
	v_mfma_f32_16x16x32_bf16 v[16:19], v[156:159], v[188:191], v[16:19]
	v_mfma_f32_16x16x32_bf16 v[8:11], v[164:167], v[188:191], v[8:11]
	v_mfma_f32_16x16x32_bf16 v[4:7], v[156:159], v[206:209], v[4:7]
	v_mfma_f32_16x16x32_bf16 v[0:3], v[164:167], v[206:209], v[0:3]
	v_mfma_f32_16x16x32_bf16 v[48:51], v[160:163], v[176:179], v[48:51]
	v_mfma_f32_16x16x32_bf16 v[40:43], v[168:171], v[176:179], v[40:43]
	v_mfma_f32_16x16x32_bf16 v[32:35], v[160:163], v[184:187], v[32:35]
	v_mfma_f32_16x16x32_bf16 v[24:27], v[168:171], v[184:187], v[24:27]
	v_mfma_f32_16x16x32_bf16 v[16:19], v[160:163], v[192:195], v[16:19]
	v_mfma_f32_16x16x32_bf16 v[8:11], v[168:171], v[192:195], v[8:11]
	v_mfma_f32_16x16x32_bf16 v[4:7], v[160:163], v[210:213], v[4:7]
	v_mfma_f32_16x16x32_bf16 v[0:3], v[168:171], v[210:213], v[0:3]
	s_setprio 0
	s_barrier
	s_add_i32 s47, s47, 2
	s_add_u32 s45, s45, 0x100
	s_addc_u32 s46, s46, 0
	s_cmp_gt_u32 s47, 3
	s_mov_b64 s[16:17], s[18:19]
	s_cbranch_scc0 .LBB0_1338
	s_branch .Lpeel_exit_4

;     __device__ __forceinline__ int nt_of(const Unit& u) const { return (u.pm >> 12) ? ktper : kt; }
; #define PG8_STAGE(bufoff, gbase, voff) do { _Pragma("unroll") for (int _i = 0; _i < 2; ++_i) \
;         __builtin_amdgcn_global_load_lds((const unsigned*)((const char*)(gbase) + (voff)[_i]), (PG8_LAS unsigned*)(lds + (bufoff) + ldsw + _i * 8192), 16, 0, 0); } while (0)
; #define PG8_LDA(dst, b, h) do { _Pragma("unroll") for (int m = 0; m < 4; ++m) _Pragma("unroll") for (int k = 0; k < 2; ++k) dst[m][k] = *(const PG8_LAS bf16x8*)(lds + PG8_SA(b, h) + aoff + m * 2048 + k * 1024); } while (0)
; #define PG8_LDB(dst, b, h) do { _Pragma("unroll") for (int n = 0; n < 2; ++n) _Pragma("unroll") for (int k = 0; k < 2; ++k) dst[n][k] = *(const PG8_LAS bf16x8*)(lds + PG8_SB(b, h) + boff + n * 2048 + k * 1024); } while (0)
; #define PG8_WAIT_V(n) asm volatile("s_waitcnt vmcnt(" #n ")" ::: "memory")
; template <class Epi, class Sched, bool ALIGN_EPI = false, bool SP2 = false>
; __device__ __forceinline__ void gemm_phase(PG8_LAS unsigned char* lds, const Gemm g, const Sched& S, const Epi& E, int wave_s_) {
;     ...
;         const bool has_next = S.next(ui + 1, nxt);
;         const char* nA = has_next ? (const char*)g.A + (size_t)(nxt.pm & 4095) * tstep + (size_t)S.k0_of(nxt) * kstep : cA; const char* nB = has_next ? (const char*)g.Bt + (size_t)nxt.pn * tstep + (size_t)S.k0_of(nxt) * kstep : cB;
;         const int nt = S.nt_of(cur);
;         for (int t = 0; t < nt; t += 2) {
;             const bool last = (t == nt - 2);
;             const char* a1 = cA + (size_t)(t + 1) * kstep;
;             const char* a2 = last ? nA : cA + (size_t)(t + 2) * kstep; const char* b2 = last ? nB : cB + (size_t)(t + 2) * kstep;
;             const char* a3 = a2 + kstep; const char* b3 = b2 + kstep;
;             if (last && has_next) S.a_ready(nxt);
;             if constexpr (SP2) {
;             PG8_LDB(B0, 0, 0); PG8_LDB(B1, 0, 1); PG8_SCHED; PG8_LDA(At, 0, 0); PG8_STAGE(PG8_SA(1, 1), a1 + hstep, voffA);
;             PG8_WAIT_V(8); PG8_WAIT_L(0); PG8_BAR; PG8_MMA(0, 0, At, B0); PG8_MMA(0, 1, At, B1); PG8_BAR; PG8_SCHED;
;             PG8_LDA(At, 0, 1); PG8_STAGE(PG8_SB(0, 0), b2, voffB); PG8_STAGE(PG8_SB(0, 1), b2 + hstep, voffB); PG8_STAGE(PG8_SA(0, 0), a2, voffA);
;             PG8_WAIT_V(8); PG8_WAIT_L(0); PG8_BAR; PG8_MMA(1, 0, At, B0); PG8_MMA(1, 1, At, B1); PG8_BAR; PG8_SCHED;
.LBB0_1357:
	v_mov_b32_e32 v0, 0
	s_mov_b32 s13, 0
	s_mov_b64 s[20:21], -1
	s_mov_b64 s[22:23], 0
	s_add_u32 s30, s18, s13
	s_addc_u32 s31, s19, 0
	s_add_u32 s26, s30, 0x100
	s_addc_u32 s27, s31, 0
	s_and_b64 s[24:25], s[22:23], exec
	s_cselect_b32 s27, s7, s27
	s_cselect_b32 s26, s6, s26
	s_add_u32 s13, s16, s13
	s_addc_u32 s24, s17, 0
	s_add_u32 s13, s13, 0x100
	s_addc_u32 s24, s24, 0
	s_add_i32 s62, 0, 0x10000
	s_and_b64 s[22:23], s[22:23], exec
	s_cselect_b32 s29, s15, s24
	s_cselect_b32 s28, s14, s13
	s_add_i32 s23, 0, 0x14000
	s_add_u32 s34, s30, 0x10080
	s_addc_u32 s35, s31, 0
	s_add_i32 s61, s62, s39
	s_add_i32 m0, s41, 0xc000
	s_add_i32 s64, s41, 0xe000
	s_add_i32 s58, s61, 0x2000
	s_add_u32 s30, s28, 0x10000
	v_add_u32_e32 v150, s62, v136
	v_add_u32_e32 v166, s23, v136
	s_addc_u32 s31, s29, 0
	s_add_i32 s60, s23, s39
	ds_read_b128 v[138:141], v150
	ds_read_b128 v[142:145], v150 offset:1024
	ds_read_b128 v[146:149], v150 offset:2048
	ds_read_b128 v[150:153], v150 offset:3072
	ds_read_b128 v[154:157], v166
	ds_read_b128 v[158:161], v166 offset:1024
	ds_read_b128 v[162:165], v166 offset:2048
	ds_read_b128 v[166:169], v166 offset:3072
	s_add_i32 s59, s60, 0x2000
	s_add_i32 s57, 0, 0x18000
	s_add_i32 s56, 0, 0x1c000
	s_add_u32 s24, s26, 0x10000
	s_addc_u32 s25, s27, 0
	s_add_i32 s55, s57, s39
	s_add_i32 s13, s55, 0x2000
	s_add_u32 s22, s28, 0x10080
	s_addc_u32 s23, s29, 0
	s_add_i32 s63, s56, s39
	s_add_i32 s62, s63, 0x2000
	v_lshl_add_u64 v[194:195], s[34:35], 0, v[134:135]
	ds_read_b128 v[170:173], v137
	ds_read_b128 v[174:177], v137 offset:1024
	ds_read_b128 v[178:181], v137 offset:2048
	ds_read_b128 v[182:185], v137 offset:3072
	ds_read_b128 v[186:189], v137 offset:4096
	ds_read_b128 v[190:193], v137 offset:5120
	ds_read_b128 v[206:209], v137 offset:6144
	ds_read_b128 v[210:213], v137 offset:7168
	global_load_lds_dwordx4 v[194:195], off
	v_lshl_add_u64 v[194:195], s[34:35], 0, v[130:131]
	s_mov_b32 m0, s64
	s_nop 0
	global_load_lds_dwordx4 v[194:195], off
	s_waitcnt vmcnt(8)
	s_waitcnt lgkmcnt(0)
	s_barrier
	s_setprio 1
	s_waitcnt lgkmcnt(0)
	v_mfma_f32_16x16x32_bf16 v[124:127], v[138:141], v[170:173], 0
	v_mfma_f32_16x16x32_bf16 v[120:123], v[146:149], v[170:173], 0
	v_mfma_f32_16x16x32_bf16 v[116:119], v[138:141], v[178:181], 0
	v_mfma_f32_16x16x32_bf16 v[112:115], v[146:149], v[178:181], 0
	v_mfma_f32_16x16x32_bf16 v[108:111], v[138:141], v[186:189], 0
	v_mfma_f32_16x16x32_bf16 v[104:107], v[146:149], v[186:189], 0
	v_mfma_f32_16x16x32_bf16 v[100:103], v[138:141], v[206:209], 0
	v_mfma_f32_16x16x32_bf16 v[96:99], v[146:149], v[206:209], 0
	v_mfma_f32_16x16x32_bf16 v[124:127], v[142:145], v[174:177], v[124:127]
	v_mfma_f32_16x16x32_bf16 v[120:123], v[150:153], v[174:177], v[120:123]
	v_mfma_f32_16x16x32_bf16 v[116:119], v[142:145], v[182:185], v[116:119]
	v_mfma_f32_16x16x32_bf16 v[112:115], v[150:153], v[182:185], v[112:115]
	v_mfma_f32_16x16x32_bf16 v[108:111], v[142:145], v[190:193], v[108:111]
	v_mfma_f32_16x16x32_bf16 v[104:107], v[150:153], v[190:193], v[104:107]
	v_mfma_f32_16x16x32_bf16 v[100:103], v[142:145], v[210:213], v[100:103]
	v_mfma_f32_16x16x32_bf16 v[96:99], v[150:153], v[210:213], v[96:99]
	s_setprio 0
	s_setprio 1
	v_mfma_f32_16x16x32_bf16 v[76:79], v[154:157], v[170:173], 0
	v_mfma_f32_16x16x32_bf16 v[68:71], v[162:165], v[170:173], 0
	v_mfma_f32_16x16x32_bf16 v[60:63], v[154:157], v[178:181], 0
	v_mfma_f32_16x16x32_bf16 v[52:55], v[162:165], v[178:181], 0
	v_mfma_f32_16x16x32_bf16 v[44:47], v[154:157], v[186:189], 0
	v_mfma_f32_16x16x32_bf16 v[40:43], v[162:165], v[186:189], 0
	v_mfma_f32_16x16x32_bf16 v[36:39], v[154:157], v[206:209], 0
	v_mfma_f32_16x16x32_bf16 v[32:35], v[162:165], v[206:209], 0
	v_mfma_f32_16x16x32_bf16 v[76:79], v[158:161], v[174:177], v[76:79]
	v_mfma_f32_16x16x32_bf16 v[68:71], v[166:169], v[174:177], v[68:71]
	v_mfma_f32_16x16x32_bf16 v[60:63], v[158:161], v[182:185], v[60:63]
	v_mfma_f32_16x16x32_bf16 v[52:55], v[166:169], v[182:185], v[52:55]
	v_mfma_f32_16x16x32_bf16 v[44:47], v[158:161], v[190:193], v[44:47]
	v_mfma_f32_16x16x32_bf16 v[40:43], v[166:169], v[190:193], v[40:43]
	v_mfma_f32_16x16x32_bf16 v[36:39], v[158:161], v[210:213], v[36:39]
	v_mfma_f32_16x16x32_bf16 v[32:35], v[166:169], v[210:213], v[32:35]
	s_setprio 0
	s_barrier
	s_mov_b32 m0, s61
	v_lshl_add_u64 v[194:195], s[28:29], 0, v[132:133]
	ds_read_b128 v[170:173], v137 offset:16384
	ds_read_b128 v[174:177], v137 offset:17408
	ds_read_b128 v[178:181], v137 offset:18432
	ds_read_b128 v[182:185], v137 offset:19456
	ds_read_b128 v[186:189], v137 offset:20480
	ds_read_b128 v[190:193], v137 offset:21504
	ds_read_b128 v[206:209], v137 offset:22528
	ds_read_b128 v[210:213], v137 offset:23552
	global_load_lds_dwordx4 v[194:195], off
	v_lshl_add_u64 v[214:215], s[28:29], 0, v[128:129]
	s_mov_b32 m0, s58
	v_lshl_add_u64 v[216:217], s[30:31], 0, v[132:133]
	global_load_lds_dwordx4 v[214:215], off
	s_mov_b32 m0, s60
	v_lshl_add_u64 v[218:219], s[26:27], 0, v[130:131]
	global_load_lds_dwordx4 v[216:217], off
	v_lshl_add_u64 v[216:217], s[30:31], 0, v[128:129]
	s_mov_b32 m0, s59
	s_nop 0
	global_load_lds_dwordx4 v[216:217], off
	v_lshl_add_u64 v[216:217], s[26:27], 0, v[134:135]
	s_mov_b32 m0, s41
	s_nop 0
	global_load_lds_dwordx4 v[216:217], off
	s_mov_b32 m0, s42
	s_nop 0
	global_load_lds_dwordx4 v[218:219], off
	s_waitcnt vmcnt(8)
	s_waitcnt lgkmcnt(0)
	s_barrier
; #define PG8_STAGE(bufoff, gbase, voff) do { _Pragma("unroll") for (int _i = 0; _i < 2; ++_i) \
;         __builtin_amdgcn_global_load_lds((const unsigned*)((const char*)(gbase) + (voff)[_i]), (PG8_LAS unsigned*)(lds + (bufoff) + ldsw + _i * 8192), 16, 0, 0); } while (0)
; #define PG8_LDA(dst, b, h) do { _Pragma("unroll") for (int m = 0; m < 4; ++m) _Pragma("unroll") for (int k = 0; k < 2; ++k) dst[m][k] = *(const PG8_LAS bf16x8*)(lds + PG8_SA(b, h) + aoff + m * 2048 + k * 1024); } while (0)
; #define PG8_LDB(dst, b, h) do { _Pragma("unroll") for (int n = 0; n < 2; ++n) _Pragma("unroll") for (int k = 0; k < 2; ++k) dst[n][k] = *(const PG8_LAS bf16x8*)(lds + PG8_SB(b, h) + boff + n * 2048 + k * 1024); } while (0)
; #define PG8_MMA(ai, bj, At, Bt) do { __builtin_amdgcn_s_setprio(1); _Pragma("unroll") for (int m = 0; m < 4; ++m) _Pragma("unroll") for (int n = 0; n < 2; ++n) _Pragma("unroll") for (int k = 0; k < 2; ++k) \
;         acc[ai][bj][m][n] = __builtin_amdgcn_mfma_f32_16x16x32_bf16(Bt[n][k], At[m][k], acc[ai][bj][m][n], 0, 0, 0); __builtin_amdgcn_s_setprio(0); } while (0)
; #define PG8_WAIT_V(n) asm volatile("s_waitcnt vmcnt(" #n ")" ::: "memory")
; #define PG8_WAIT_L(n) asm volatile("s_waitcnt lgkmcnt(" #n ")" ::: "memory")
; #define PG8_BAR __builtin_amdgcn_s_barrier()
; #define PG8_SCHED __builtin_amdgcn_sched_barrier(0)
; template <class Epi, class Sched, bool ALIGN_EPI = false, bool SP2 = false>
; __device__ __forceinline__ void gemm_phase(PG8_LAS unsigned char* lds, const Gemm g, const Sched& S, const Epi& E, int wave_s_) {
;     ...
;             PG8_WAIT_V(8); PG8_WAIT_L(0); PG8_BAR; PG8_MMA(1, 0, At, B0); PG8_MMA(1, 1, At, B1); PG8_BAR; PG8_SCHED;
;             PG8_LDB(B0, 1, 0); PG8_LDB(B1, 1, 1); PG8_SCHED; PG8_LDA(At, 1, 0); PG8_STAGE(PG8_SA(0, 1), a2 + hstep, voffA);
;             PG8_WAIT_V(8); PG8_WAIT_L(0); PG8_BAR; PG8_MMA(0, 0, At, B0); PG8_MMA(0, 1, At, B1); PG8_BAR; PG8_SCHED;
	s_setprio 1
	s_waitcnt lgkmcnt(0)
	v_mfma_f32_16x16x32_bf16 v[92:95], v[138:141], v[170:173], 0
	v_mfma_f32_16x16x32_bf16 v[88:91], v[146:149], v[170:173], 0
	v_mfma_f32_16x16x32_bf16 v[84:87], v[138:141], v[178:181], 0
	v_mfma_f32_16x16x32_bf16 v[80:83], v[146:149], v[178:181], 0
	v_mfma_f32_16x16x32_bf16 v[72:75], v[138:141], v[186:189], 0
	v_mfma_f32_16x16x32_bf16 v[64:67], v[146:149], v[186:189], 0
	v_mfma_f32_16x16x32_bf16 v[56:59], v[138:141], v[206:209], 0
	v_mfma_f32_16x16x32_bf16 v[48:51], v[146:149], v[206:209], 0
	v_mfma_f32_16x16x32_bf16 v[92:95], v[142:145], v[174:177], v[92:95]
	v_mfma_f32_16x16x32_bf16 v[88:91], v[150:153], v[174:177], v[88:91]
	v_mfma_f32_16x16x32_bf16 v[84:87], v[142:145], v[182:185], v[84:87]
	v_mfma_f32_16x16x32_bf16 v[80:83], v[150:153], v[182:185], v[80:83]
	v_mfma_f32_16x16x32_bf16 v[72:75], v[142:145], v[190:193], v[72:75]
	v_mfma_f32_16x16x32_bf16 v[64:67], v[150:153], v[190:193], v[64:67]
	v_mfma_f32_16x16x32_bf16 v[56:59], v[142:145], v[210:213], v[56:59]
	v_mfma_f32_16x16x32_bf16 v[48:51], v[150:153], v[210:213], v[48:51]
	s_setprio 0
	s_setprio 1
	v_mfma_f32_16x16x32_bf16 v[28:31], v[154:157], v[170:173], 0
	v_mfma_f32_16x16x32_bf16 v[24:27], v[162:165], v[170:173], 0
	v_mfma_f32_16x16x32_bf16 v[20:23], v[154:157], v[178:181], 0
	v_mfma_f32_16x16x32_bf16 v[16:19], v[162:165], v[178:181], 0
	v_mfma_f32_16x16x32_bf16 v[12:15], v[154:157], v[186:189], 0
	v_mfma_f32_16x16x32_bf16 v[8:11], v[162:165], v[186:189], 0
	v_mfma_f32_16x16x32_bf16 v[4:7], v[154:157], v[206:209], 0
	v_mfma_f32_16x16x32_bf16 v[0:3], v[162:165], v[206:209], 0
	v_mfma_f32_16x16x32_bf16 v[28:31], v[158:161], v[174:177], v[28:31]
	v_mfma_f32_16x16x32_bf16 v[24:27], v[166:169], v[174:177], v[24:27]
	v_mfma_f32_16x16x32_bf16 v[20:23], v[158:161], v[182:185], v[20:23]
	v_mfma_f32_16x16x32_bf16 v[16:19], v[166:169], v[182:185], v[16:19]
	v_mfma_f32_16x16x32_bf16 v[12:15], v[158:161], v[190:193], v[12:15]
	v_mfma_f32_16x16x32_bf16 v[8:11], v[166:169], v[190:193], v[8:11]
	v_mfma_f32_16x16x32_bf16 v[4:7], v[158:161], v[210:213], v[4:7]
	v_mfma_f32_16x16x32_bf16 v[0:3], v[166:169], v[210:213], v[0:3]
	s_setprio 0
	s_barrier
	v_add_u32_e32 v150, s57, v136
	v_add_u32_e32 v166, s56, v136
	ds_read_b128 v[138:141], v150
	ds_read_b128 v[142:145], v150 offset:1024
	ds_read_b128 v[146:149], v150 offset:2048
	ds_read_b128 v[150:153], v150 offset:3072
	ds_read_b128 v[154:157], v166
	ds_read_b128 v[158:161], v166 offset:1024
	ds_read_b128 v[162:165], v166 offset:2048
	ds_read_b128 v[166:169], v166 offset:3072
	s_mov_b32 m0, s43
	v_lshl_add_u64 v[220:221], s[24:25], 0, v[134:135]
	ds_read_b128 v[170:173], v137 offset:32768
	ds_read_b128 v[174:177], v137 offset:33792
	ds_read_b128 v[178:181], v137 offset:34816
	ds_read_b128 v[182:185], v137 offset:35840
	ds_read_b128 v[186:189], v137 offset:36864
	ds_read_b128 v[190:193], v137 offset:37888
	ds_read_b128 v[206:209], v137 offset:38912
	ds_read_b128 v[210:213], v137 offset:39936
	global_load_lds_dwordx4 v[220:221], off
	v_lshl_add_u64 v[220:221], s[24:25], 0, v[130:131]
	s_mov_b32 m0, s44
	s_nop 0
	global_load_lds_dwordx4 v[220:221], off
	s_waitcnt vmcnt(8)
	s_waitcnt lgkmcnt(0)
	s_barrier
	s_setprio 1
	s_waitcnt lgkmcnt(0)
	v_mfma_f32_16x16x32_bf16 v[124:127], v[138:141], v[170:173], v[124:127]
	v_mfma_f32_16x16x32_bf16 v[120:123], v[146:149], v[170:173], v[120:123]
	v_mfma_f32_16x16x32_bf16 v[116:119], v[138:141], v[178:181], v[116:119]
	v_mfma_f32_16x16x32_bf16 v[112:115], v[146:149], v[178:181], v[112:115]
	v_mfma_f32_16x16x32_bf16 v[108:111], v[138:141], v[186:189], v[108:111]
	v_mfma_f32_16x16x32_bf16 v[104:107], v[146:149], v[186:189], v[104:107]
	v_mfma_f32_16x16x32_bf16 v[100:103], v[138:141], v[206:209], v[100:103]
	v_mfma_f32_16x16x32_bf16 v[96:99], v[146:149], v[206:209], v[96:99]
	v_mfma_f32_16x16x32_bf16 v[124:127], v[142:145], v[174:177], v[124:127]
	v_mfma_f32_16x16x32_bf16 v[120:123], v[150:153], v[174:177], v[120:123]
	v_mfma_f32_16x16x32_bf16 v[116:119], v[142:145], v[182:185], v[116:119]
	v_mfma_f32_16x16x32_bf16 v[112:115], v[150:153], v[182:185], v[112:115]
	v_mfma_f32_16x16x32_bf16 v[108:111], v[142:145], v[190:193], v[108:111]
	v_mfma_f32_16x16x32_bf16 v[104:107], v[150:153], v[190:193], v[104:107]
	v_mfma_f32_16x16x32_bf16 v[100:103], v[142:145], v[210:213], v[100:103]
	v_mfma_f32_16x16x32_bf16 v[96:99], v[150:153], v[210:213], v[96:99]
	s_setprio 0
	s_setprio 1
	v_mfma_f32_16x16x32_bf16 v[76:79], v[154:157], v[170:173], v[76:79]
	v_mfma_f32_16x16x32_bf16 v[68:71], v[162:165], v[170:173], v[68:71]
	v_mfma_f32_16x16x32_bf16 v[60:63], v[154:157], v[178:181], v[60:63]
	v_mfma_f32_16x16x32_bf16 v[52:55], v[162:165], v[178:181], v[52:55]
	v_mfma_f32_16x16x32_bf16 v[44:47], v[154:157], v[186:189], v[44:47]
	v_mfma_f32_16x16x32_bf16 v[40:43], v[162:165], v[186:189], v[40:43]
	v_mfma_f32_16x16x32_bf16 v[36:39], v[154:157], v[206:209], v[36:39]
	v_mfma_f32_16x16x32_bf16 v[32:35], v[162:165], v[206:209], v[32:35]
	v_mfma_f32_16x16x32_bf16 v[76:79], v[158:161], v[174:177], v[76:79]
	v_mfma_f32_16x16x32_bf16 v[68:71], v[166:169], v[174:177], v[68:71]
	v_mfma_f32_16x16x32_bf16 v[60:63], v[158:161], v[182:185], v[60:63]
	v_mfma_f32_16x16x32_bf16 v[52:55], v[166:169], v[182:185], v[52:55]
	v_mfma_f32_16x16x32_bf16 v[44:47], v[158:161], v[190:193], v[44:47]
	v_mfma_f32_16x16x32_bf16 v[40:43], v[166:169], v[190:193], v[40:43]
	v_mfma_f32_16x16x32_bf16 v[36:39], v[158:161], v[210:213], v[36:39]
	v_mfma_f32_16x16x32_bf16 v[32:35], v[166:169], v[210:213], v[32:35]
	s_setprio 0
	s_barrier
; #define PG8_STAGE(bufoff, gbase, voff) do { _Pragma("unroll") for (int _i = 0; _i < 2; ++_i) \
;         __builtin_amdgcn_global_load_lds((const unsigned*)((const char*)(gbase) + (voff)[_i]), (PG8_LAS unsigned*)(lds + (bufoff) + ldsw + _i * 8192), 16, 0, 0); } while (0)
; #define PG8_LDA(dst, b, h) do { _Pragma("unroll") for (int m = 0; m < 4; ++m) _Pragma("unroll") for (int k = 0; k < 2; ++k) dst[m][k] = *(const PG8_LAS bf16x8*)(lds + PG8_SA(b, h) + aoff + m * 2048 + k * 1024); } while (0)
; #define PG8_MMA(ai, bj, At, Bt) do { __builtin_amdgcn_s_setprio(1); _Pragma("unroll") for (int m = 0; m < 4; ++m) _Pragma("unroll") for (int n = 0; n < 2; ++n) _Pragma("unroll") for (int k = 0; k < 2; ++k) \
;         acc[ai][bj][m][n] = __builtin_amdgcn_mfma_f32_16x16x32_bf16(Bt[n][k], At[m][k], acc[ai][bj][m][n], 0, 0, 0); __builtin_amdgcn_s_setprio(0); } while (0)
; #define PG8_WAIT_V(n) asm volatile("s_waitcnt vmcnt(" #n ")" ::: "memory")
; #define PG8_WAIT_L(n) asm volatile("s_waitcnt lgkmcnt(" #n ")" ::: "memory")
; #define PG8_BAR __builtin_amdgcn_s_barrier()
; #define PG8_SCHED __builtin_amdgcn_sched_barrier(0)
; template <class Epi, class Sched, bool ALIGN_EPI = false, bool SP2 = false>
; __device__ __forceinline__ void gemm_phase(PG8_LAS unsigned char* lds, const Gemm g, const Sched& S, const Epi& E, int wave_s_) {
;     ...
;         for (int t = 0; t < nt; t += 2) {
;     ...
;             PG8_LDA(At, 1, 1); PG8_STAGE(PG8_SB(1, 0), b3, voffB); PG8_STAGE(PG8_SB(1, 1), b3 + hstep, voffB); PG8_STAGE(PG8_SA(1, 0), a3, voffA);
;             PG8_WAIT_V(8); PG8_WAIT_L(0); PG8_BAR; PG8_MMA(1, 0, At, B0); PG8_MMA(1, 1, At, B1); PG8_BAR; PG8_SCHED;
	s_mov_b32 m0, s55
	v_lshl_add_u64 v[194:195], v[194:195], 0, s[76:77]
	ds_read_b128 v[170:173], v137 offset:49152
	ds_read_b128 v[174:177], v137 offset:50176
	ds_read_b128 v[178:181], v137 offset:51200
	ds_read_b128 v[182:185], v137 offset:52224
	ds_read_b128 v[186:189], v137 offset:53248
	ds_read_b128 v[190:193], v137 offset:54272
	ds_read_b128 v[206:209], v137 offset:55296
	ds_read_b128 v[210:213], v137 offset:56320
	global_load_lds_dwordx4 v[194:195], off
	v_lshl_add_u64 v[194:195], v[214:215], 0, s[76:77]
	s_mov_b32 m0, s13
	s_nop 0
	global_load_lds_dwordx4 v[194:195], off
	v_lshl_add_u64 v[194:195], s[22:23], 0, v[132:133]
	s_mov_b32 m0, s63
	s_nop 0
	global_load_lds_dwordx4 v[194:195], off
	v_lshl_add_u64 v[194:195], s[22:23], 0, v[128:129]
	s_mov_b32 m0, s62
	s_nop 0
	global_load_lds_dwordx4 v[194:195], off
	v_lshl_add_u64 v[194:195], v[216:217], 0, s[76:77]
	s_mov_b32 m0, s46
	s_nop 0
	global_load_lds_dwordx4 v[194:195], off
	v_lshl_add_u64 v[194:195], v[218:219], 0, s[76:77]
	s_mov_b32 m0, s47
	s_nop 0
	global_load_lds_dwordx4 v[194:195], off
	s_waitcnt vmcnt(8)
	s_waitcnt lgkmcnt(0)
	s_barrier
	s_setprio 1
	s_waitcnt lgkmcnt(0)
	v_mfma_f32_16x16x32_bf16 v[92:95], v[138:141], v[170:173], v[92:95]
	v_mfma_f32_16x16x32_bf16 v[88:91], v[146:149], v[170:173], v[88:91]
	v_mfma_f32_16x16x32_bf16 v[84:87], v[138:141], v[178:181], v[84:87]
	v_mfma_f32_16x16x32_bf16 v[80:83], v[146:149], v[178:181], v[80:83]
	v_mfma_f32_16x16x32_bf16 v[72:75], v[138:141], v[186:189], v[72:75]
	v_mfma_f32_16x16x32_bf16 v[64:67], v[146:149], v[186:189], v[64:67]
	v_mfma_f32_16x16x32_bf16 v[56:59], v[138:141], v[206:209], v[56:59]
	v_mfma_f32_16x16x32_bf16 v[48:51], v[146:149], v[206:209], v[48:51]
	v_mfma_f32_16x16x32_bf16 v[92:95], v[142:145], v[174:177], v[92:95]
	v_mfma_f32_16x16x32_bf16 v[88:91], v[150:153], v[174:177], v[88:91]
	v_mfma_f32_16x16x32_bf16 v[84:87], v[142:145], v[182:185], v[84:87]
	v_mfma_f32_16x16x32_bf16 v[80:83], v[150:153], v[182:185], v[80:83]
	v_mfma_f32_16x16x32_bf16 v[72:75], v[142:145], v[190:193], v[72:75]
	v_mfma_f32_16x16x32_bf16 v[64:67], v[150:153], v[190:193], v[64:67]
	v_mfma_f32_16x16x32_bf16 v[56:59], v[142:145], v[210:213], v[56:59]
	v_mfma_f32_16x16x32_bf16 v[48:51], v[150:153], v[210:213], v[48:51]
	s_setprio 0
	s_setprio 1
	v_mfma_f32_16x16x32_bf16 v[28:31], v[154:157], v[170:173], v[28:31]
	v_mfma_f32_16x16x32_bf16 v[24:27], v[162:165], v[170:173], v[24:27]
	v_mfma_f32_16x16x32_bf16 v[20:23], v[154:157], v[178:181], v[20:23]
	v_mfma_f32_16x16x32_bf16 v[16:19], v[162:165], v[178:181], v[16:19]
	v_mfma_f32_16x16x32_bf16 v[12:15], v[154:157], v[186:189], v[12:15]
	v_mfma_f32_16x16x32_bf16 v[8:11], v[162:165], v[186:189], v[8:11]
	v_mfma_f32_16x16x32_bf16 v[4:7], v[154:157], v[206:209], v[4:7]
	v_mfma_f32_16x16x32_bf16 v[0:3], v[162:165], v[206:209], v[0:3]
	v_mfma_f32_16x16x32_bf16 v[28:31], v[158:161], v[174:177], v[28:31]
	v_mfma_f32_16x16x32_bf16 v[24:27], v[166:169], v[174:177], v[24:27]
	v_mfma_f32_16x16x32_bf16 v[20:23], v[158:161], v[182:185], v[20:23]
	v_mfma_f32_16x16x32_bf16 v[16:19], v[166:169], v[182:185], v[16:19]
	v_mfma_f32_16x16x32_bf16 v[12:15], v[158:161], v[190:193], v[12:15]
	v_mfma_f32_16x16x32_bf16 v[8:11], v[166:169], v[190:193], v[8:11]
	v_mfma_f32_16x16x32_bf16 v[4:7], v[158:161], v[210:213], v[4:7]
	v_mfma_f32_16x16x32_bf16 v[0:3], v[166:169], v[210:213], v[0:3]
	s_setprio 0
	s_barrier
	s_movk_i32 s13, 0x100
	s_andn2_b64 vcc, exec, s[20:21]
	s_mov_b64 s[22:23], -1
	s_mov_b64 s[20:21], 0
	s_cbranch_vccz .LBB0_1358
	s_branch .Lpeel_exit_5

; #define PG8_BAR __builtin_amdgcn_s_barrier()
; template <class Epi, class Sched, bool ALIGN_EPI = false, bool SP2 = false>
; __device__ __forceinline__ void gemm_phase(PG8_LAS unsigned char* lds, const Gemm g, const Sched& S, const Epi& E, int wave_s_) {
;     ...
;         if constexpr (ALIGN_EPI) { if (wr == 0) PG8_BAR; }
.Lpeel_exit_5:
	s_and_b64 vcc, exec, s[10:11]
	s_cbranch_vccz .LBB0_1361
	s_barrier

;     __device__ __forceinline__ int nt_of(const Unit& u) const { return (u.pm >> 12) ? ktper : kt; }
; #define PG8_STAGE(bufoff, gbase, voff) do { _Pragma("unroll") for (int _i = 0; _i < 2; ++_i) \
;         __builtin_amdgcn_global_load_lds((const unsigned*)((const char*)(gbase) + (voff)[_i]), (PG8_LAS unsigned*)(lds + (bufoff) + ldsw + _i * 8192), 16, 0, 0); } while (0)
; #define PG8_LDA(dst, b, h) do { _Pragma("unroll") for (int m = 0; m < 4; ++m) _Pragma("unroll") for (int k = 0; k < 2; ++k) dst[m][k] = *(const PG8_LAS bf16x8*)(lds + PG8_SA(b, h) + aoff + m * 2048 + k * 1024); } while (0)
; #define PG8_LDB(dst, b, h) do { _Pragma("unroll") for (int n = 0; n < 2; ++n) _Pragma("unroll") for (int k = 0; k < 2; ++k) dst[n][k] = *(const PG8_LAS bf16x8*)(lds + PG8_SB(b, h) + boff + n * 2048 + k * 1024); } while (0)
; #define PG8_WAIT_V(n) asm volatile("s_waitcnt vmcnt(" #n ")" ::: "memory")
; template <class Epi, class Sched, bool ALIGN_EPI = false, bool SP2 = false>
; __device__ __forceinline__ void gemm_phase(PG8_LAS unsigned char* lds, const Gemm g, const Sched& S, const Epi& E, int wave_s_) {
;     ...
;         const int nt = S.nt_of(cur);
;         for (int t = 0; t < nt; t += 2) {
;             const bool last = (t == nt - 2);
;             const char* a1 = cA + (size_t)(t + 1) * kstep;
;             const char* a2 = last ? nA : cA + (size_t)(t + 2) * kstep; const char* b2 = last ? nB : cB + (size_t)(t + 2) * kstep;
;             const char* a3 = a2 + kstep; const char* b3 = b2 + kstep;
;             if (last && has_next) S.a_ready(nxt);
;             if constexpr (SP2) {
;             PG8_LDB(B0, 0, 0); PG8_LDB(B1, 0, 1); PG8_SCHED; PG8_LDA(At, 0, 0); PG8_STAGE(PG8_SA(1, 1), a1 + hstep, voffA);
;             PG8_WAIT_V(8); PG8_WAIT_L(0); PG8_BAR; PG8_MMA(0, 0, At, B0); PG8_MMA(0, 1, At, B1); PG8_BAR; PG8_SCHED;
;             PG8_LDA(At, 0, 1); PG8_STAGE(PG8_SB(0, 0), b2, voffB); PG8_STAGE(PG8_SB(0, 1), b2 + hstep, voffB); PG8_STAGE(PG8_SA(0, 0), a2, voffA);
;             PG8_WAIT_V(8); PG8_WAIT_L(0); PG8_BAR; PG8_MMA(1, 0, At, B0); PG8_MMA(1, 1, At, B1); PG8_BAR; PG8_SCHED;
;     ...
;         for (int a = 0; a < 2; ++a)
; #pragma unroll
;             for (int b = 0; b < 2; ++b)
; #pragma unroll
;                 for (int m = 0; m < 4; ++m)
; #pragma unroll
;                     for (int n = 0; n < 2; ++n) acc[a][b][m][n] = (f32x4){0.f, 0.f, 0.f, 0.f};
.LBB0_1580:
	s_cmpk_gt_u32 s54, 0xfff
	s_cselect_b64 s[26:27], -1, 0
	s_cmpk_lt_u32 s54, 0x1000
	s_cselect_b64 s[6:7], -1, 0
	s_and_b64 s[30:31], s[6:7], exec
	s_cselect_b32 s9, 16, 4
	s_add_i32 s21, s9, -2
	s_add_u32 s55, s28, 0x100
	v_mov_b32_e32 v0, 0
	s_addc_u32 s56, s29, 0
	s_mov_b32 s30, 0
	v_mov_b32_e32 v1, v0
	v_mov_b64_e32 v[2:3], 0
	v_mov_b64_e32 v[4:5], 0
	v_mov_b64_e32 v[6:7], 0
	v_mov_b64_e32 v[12:13], 0
	v_mov_b64_e32 v[14:15], 0
	v_mov_b64_e32 v[20:21], 0
	v_mov_b64_e32 v[22:23], 0
	v_mov_b64_e32 v[32:33], 0
	v_mov_b64_e32 v[34:35], 0
	v_mov_b64_e32 v[36:37], 0
	v_mov_b64_e32 v[38:39], 0
	v_mov_b64_e32 v[44:45], 0
	v_mov_b64_e32 v[46:47], 0
	v_mov_b64_e32 v[52:53], 0
	v_mov_b64_e32 v[54:55], 0
	v_mov_b64_e32 v[8:9], 0
	v_mov_b64_e32 v[10:11], 0
	v_mov_b64_e32 v[16:17], 0
	v_mov_b64_e32 v[18:19], 0
	v_mov_b64_e32 v[24:25], 0
	v_mov_b64_e32 v[26:27], 0
	v_mov_b64_e32 v[28:29], 0
	v_mov_b64_e32 v[30:31], 0
	v_mov_b64_e32 v[40:41], 0
	v_mov_b64_e32 v[42:43], 0
	v_mov_b64_e32 v[48:49], 0
	v_mov_b64_e32 v[50:51], 0
	v_mov_b64_e32 v[56:57], 0
	v_mov_b64_e32 v[58:59], 0
	v_mov_b64_e32 v[60:61], 0
	v_mov_b64_e32 v[62:63], 0
	v_mov_b64_e32 v[64:65], 0
	v_mov_b64_e32 v[66:67], 0
	v_mov_b64_e32 v[68:69], 0
	v_mov_b64_e32 v[70:71], 0
	v_mov_b64_e32 v[76:77], 0
	v_mov_b64_e32 v[78:79], 0
	v_mov_b64_e32 v[84:85], 0
	v_mov_b64_e32 v[86:87], 0
	s_waitcnt vmcnt(0)
	s_add_i32 s57, s30, 2
	s_add_u32 s28, s10, 0x100
	s_addc_u32 s29, s11, 0
	s_add_i32 s58, 0, 0x10000
	s_cmp_eq_u32 s21, s30
	s_cselect_b32 s35, s23, s29
	s_cselect_b32 s34, s22, s28
	s_cselect_b32 s31, s25, s56
	s_cselect_b32 s30, s24, s55
	s_add_i32 s59, 0, 0x14000
	v_add_u32_e32 v100, s58, v224
	v_add_u32_e32 v120, s59, v224
	ds_read_b128 v[88:91], v100
	ds_read_b128 v[92:95], v100 offset:1024
	ds_read_b128 v[96:99], v100 offset:2048
	ds_read_b128 v[100:103], v100 offset:3072
	ds_read_b128 v[108:111], v120
	ds_read_b128 v[112:115], v120 offset:1024
	ds_read_b128 v[116:119], v120 offset:2048
	ds_read_b128 v[120:123], v120 offset:3072
	v_lshl_add_u64 v[198:199], s[10:11], 0, v[206:207]
	s_add_i32 m0, s40, 0xc000
	ds_read_b128 v[160:163], v225
	ds_read_b128 v[164:167], v225 offset:1024
	ds_read_b128 v[168:171], v225 offset:2048
	ds_read_b128 v[172:175], v225 offset:3072
	ds_read_b128 v[176:179], v225 offset:4096
	ds_read_b128 v[180:183], v225 offset:5120
	ds_read_b128 v[184:187], v225 offset:6144
	ds_read_b128 v[188:191], v225 offset:7168
	global_load_lds_dwordx4 v[198:199], off
	v_lshl_add_u64 v[198:199], s[10:11], 0, v[194:195]
	s_add_i32 m0, s40, 0xe000
	s_nop 0
	global_load_lds_dwordx4 v[198:199], off
	s_waitcnt vmcnt(8)
	s_waitcnt lgkmcnt(0)
	s_barrier
	s_setprio 1
	s_waitcnt lgkmcnt(0)
	v_mfma_f32_16x16x32_bf16 v[156:159], v[88:91], v[160:163], 0
	v_mfma_f32_16x16x32_bf16 v[152:155], v[96:99], v[160:163], 0
	v_mfma_f32_16x16x32_bf16 v[144:147], v[88:91], v[168:171], 0
	v_mfma_f32_16x16x32_bf16 v[136:139], v[96:99], v[168:171], 0
	v_mfma_f32_16x16x32_bf16 v[124:127], v[88:91], v[176:179], 0
	v_mfma_f32_16x16x32_bf16 v[104:107], v[96:99], v[176:179], 0
	v_mfma_f32_16x16x32_bf16 v[80:83], v[88:91], v[184:187], 0
	v_mfma_f32_16x16x32_bf16 v[72:75], v[96:99], v[184:187], 0
	v_mfma_f32_16x16x32_bf16 v[156:159], v[92:95], v[164:167], v[156:159]
	v_mfma_f32_16x16x32_bf16 v[152:155], v[100:103], v[164:167], v[152:155]
	v_mfma_f32_16x16x32_bf16 v[144:147], v[92:95], v[172:175], v[144:147]
	v_mfma_f32_16x16x32_bf16 v[136:139], v[100:103], v[172:175], v[136:139]
	v_mfma_f32_16x16x32_bf16 v[124:127], v[92:95], v[180:183], v[124:127]
	v_mfma_f32_16x16x32_bf16 v[104:107], v[100:103], v[180:183], v[104:107]
	v_mfma_f32_16x16x32_bf16 v[80:83], v[92:95], v[188:191], v[80:83]
	v_mfma_f32_16x16x32_bf16 v[72:75], v[100:103], v[188:191], v[72:75]
	s_setprio 0
	s_setprio 1
	v_mfma_f32_16x16x32_bf16 v[148:151], v[108:111], v[160:163], 0
	v_mfma_f32_16x16x32_bf16 v[140:143], v[116:119], v[160:163], 0
	v_mfma_f32_16x16x32_bf16 v[132:135], v[108:111], v[168:171], 0
	v_mfma_f32_16x16x32_bf16 v[128:131], v[116:119], v[168:171], 0
	v_mfma_f32_16x16x32_bf16 v[84:87], v[108:111], v[176:179], 0
	v_mfma_f32_16x16x32_bf16 v[76:79], v[116:119], v[176:179], 0
	v_mfma_f32_16x16x32_bf16 v[68:71], v[108:111], v[184:187], 0
	v_mfma_f32_16x16x32_bf16 v[64:67], v[116:119], v[184:187], 0
	v_mfma_f32_16x16x32_bf16 v[148:151], v[112:115], v[164:167], v[148:151]
	v_mfma_f32_16x16x32_bf16 v[140:143], v[120:123], v[164:167], v[140:143]
	v_mfma_f32_16x16x32_bf16 v[132:135], v[112:115], v[172:175], v[132:135]
	v_mfma_f32_16x16x32_bf16 v[128:131], v[120:123], v[172:175], v[128:131]
	v_mfma_f32_16x16x32_bf16 v[84:87], v[112:115], v[180:183], v[84:87]
	v_mfma_f32_16x16x32_bf16 v[76:79], v[120:123], v[180:183], v[76:79]
	v_mfma_f32_16x16x32_bf16 v[68:71], v[112:115], v[188:191], v[68:71]
	v_mfma_f32_16x16x32_bf16 v[64:67], v[120:123], v[188:191], v[64:67]
	s_setprio 0
	s_barrier
	s_add_i32 s10, s58, s39
	v_lshl_add_u64 v[198:199], s[30:31], 0, v[196:197]
	s_mov_b32 m0, s10
	ds_read_b128 v[160:163], v225 offset:16384
	ds_read_b128 v[164:167], v225 offset:17408
	ds_read_b128 v[168:171], v225 offset:18432
	ds_read_b128 v[172:175], v225 offset:19456
	ds_read_b128 v[176:179], v225 offset:20480
	ds_read_b128 v[180:183], v225 offset:21504
	ds_read_b128 v[184:187], v225 offset:22528
	ds_read_b128 v[188:191], v225 offset:23552
	global_load_lds_dwordx4 v[198:199], off
	s_add_i32 m0, s10, 0x2000
	s_add_u32 s10, s30, 0x40000
	v_lshl_add_u64 v[204:205], s[30:31], 0, v[192:193]
	s_addc_u32 s11, s31, 0
	s_add_i32 s58, s59, s39
	global_load_lds_dwordx4 v[204:205], off
	v_lshl_add_u64 v[208:209], s[10:11], 0, v[196:197]
	s_mov_b32 m0, s58
	v_lshl_add_u64 v[210:211], s[34:35], 0, v[192:193]
	global_load_lds_dwordx4 v[208:209], off
	v_lshl_add_u64 v[208:209], s[10:11], 0, v[192:193]
	s_add_i32 m0, s58, 0x2000
	s_nop 0
	global_load_lds_dwordx4 v[208:209], off
	v_lshl_add_u64 v[208:209], s[34:35], 0, v[196:197]
	s_mov_b32 m0, s40
	s_nop 0
	global_load_lds_dwordx4 v[208:209], off
	s_mov_b32 m0, s41
	s_nop 0
	global_load_lds_dwordx4 v[210:211], off
	s_waitcnt vmcnt(8)
	s_waitcnt lgkmcnt(0)
	s_barrier
; #define PG8_STAGE(bufoff, gbase, voff) do { _Pragma("unroll") for (int _i = 0; _i < 2; ++_i) \
;         __builtin_amdgcn_global_load_lds((const unsigned*)((const char*)(gbase) + (voff)[_i]), (PG8_LAS unsigned*)(lds + (bufoff) + ldsw + _i * 8192), 16, 0, 0); } while (0)
; #define PG8_LDA(dst, b, h) do { _Pragma("unroll") for (int m = 0; m < 4; ++m) _Pragma("unroll") for (int k = 0; k < 2; ++k) dst[m][k] = *(const PG8_LAS bf16x8*)(lds + PG8_SA(b, h) + aoff + m * 2048 + k * 1024); } while (0)
; #define PG8_LDB(dst, b, h) do { _Pragma("unroll") for (int n = 0; n < 2; ++n) _Pragma("unroll") for (int k = 0; k < 2; ++k) dst[n][k] = *(const PG8_LAS bf16x8*)(lds + PG8_SB(b, h) + boff + n * 2048 + k * 1024); } while (0)
; #define PG8_MMA(ai, bj, At, Bt) do { __builtin_amdgcn_s_setprio(1); _Pragma("unroll") for (int m = 0; m < 4; ++m) _Pragma("unroll") for (int n = 0; n < 2; ++n) _Pragma("unroll") for (int k = 0; k < 2; ++k) \
;         acc[ai][bj][m][n] = __builtin_amdgcn_mfma_f32_16x16x32_bf16(Bt[n][k], At[m][k], acc[ai][bj][m][n], 0, 0, 0); __builtin_amdgcn_s_setprio(0); } while (0)
; #define PG8_WAIT_V(n) asm volatile("s_waitcnt vmcnt(" #n ")" ::: "memory")
; #define PG8_WAIT_L(n) asm volatile("s_waitcnt lgkmcnt(" #n ")" ::: "memory")
; #define PG8_BAR __builtin_amdgcn_s_barrier()
; #define PG8_SCHED __builtin_amdgcn_sched_barrier(0)
; template <class Epi, class Sched, bool ALIGN_EPI = false, bool SP2 = false>
; __device__ __forceinline__ void gemm_phase(PG8_LAS unsigned char* lds, const Gemm g, const Sched& S, const Epi& E, int wave_s_) {
;     ...
;             PG8_WAIT_V(8); PG8_WAIT_L(0); PG8_BAR; PG8_MMA(1, 0, At, B0); PG8_MMA(1, 1, At, B1); PG8_BAR; PG8_SCHED;
;             PG8_LDB(B0, 1, 0); PG8_LDB(B1, 1, 1); PG8_SCHED; PG8_LDA(At, 1, 0); PG8_STAGE(PG8_SA(0, 1), a2 + hstep, voffA);
;             PG8_WAIT_V(8); PG8_WAIT_L(0); PG8_BAR; PG8_MMA(0, 0, At, B0); PG8_MMA(0, 1, At, B1); PG8_BAR; PG8_SCHED;
	s_setprio 1
	s_waitcnt lgkmcnt(0)
	v_mfma_f32_16x16x32_bf16 v[60:63], v[88:91], v[160:163], 0
	v_mfma_f32_16x16x32_bf16 v[56:59], v[96:99], v[160:163], 0
	v_mfma_f32_16x16x32_bf16 v[48:51], v[88:91], v[168:171], 0
	v_mfma_f32_16x16x32_bf16 v[40:43], v[96:99], v[168:171], 0
	v_mfma_f32_16x16x32_bf16 v[28:31], v[88:91], v[176:179], 0
	v_mfma_f32_16x16x32_bf16 v[24:27], v[96:99], v[176:179], 0
	v_mfma_f32_16x16x32_bf16 v[16:19], v[88:91], v[184:187], 0
	v_mfma_f32_16x16x32_bf16 v[8:11], v[96:99], v[184:187], 0
	v_mfma_f32_16x16x32_bf16 v[60:63], v[92:95], v[164:167], v[60:63]
	v_mfma_f32_16x16x32_bf16 v[56:59], v[100:103], v[164:167], v[56:59]
	v_mfma_f32_16x16x32_bf16 v[48:51], v[92:95], v[172:175], v[48:51]
	v_mfma_f32_16x16x32_bf16 v[40:43], v[100:103], v[172:175], v[40:43]
	v_mfma_f32_16x16x32_bf16 v[28:31], v[92:95], v[180:183], v[28:31]
	v_mfma_f32_16x16x32_bf16 v[24:27], v[100:103], v[180:183], v[24:27]
	v_mfma_f32_16x16x32_bf16 v[16:19], v[92:95], v[188:191], v[16:19]
	v_mfma_f32_16x16x32_bf16 v[8:11], v[100:103], v[188:191], v[8:11]
	s_setprio 0
	s_setprio 1
	v_mfma_f32_16x16x32_bf16 v[52:55], v[108:111], v[160:163], 0
	v_mfma_f32_16x16x32_bf16 v[44:47], v[116:119], v[160:163], 0
	v_mfma_f32_16x16x32_bf16 v[36:39], v[108:111], v[168:171], 0
	v_mfma_f32_16x16x32_bf16 v[32:35], v[116:119], v[168:171], 0
	v_mfma_f32_16x16x32_bf16 v[20:23], v[108:111], v[176:179], 0
	v_mfma_f32_16x16x32_bf16 v[12:15], v[116:119], v[176:179], 0
	v_mfma_f32_16x16x32_bf16 v[4:7], v[108:111], v[184:187], 0
	v_mfma_f32_16x16x32_bf16 v[0:3], v[116:119], v[184:187], 0
	v_mfma_f32_16x16x32_bf16 v[52:55], v[112:115], v[164:167], v[52:55]
	v_mfma_f32_16x16x32_bf16 v[44:47], v[120:123], v[164:167], v[44:47]
	v_mfma_f32_16x16x32_bf16 v[36:39], v[112:115], v[172:175], v[36:39]
	v_mfma_f32_16x16x32_bf16 v[32:35], v[120:123], v[172:175], v[32:35]
	v_mfma_f32_16x16x32_bf16 v[20:23], v[112:115], v[180:183], v[20:23]
	v_mfma_f32_16x16x32_bf16 v[12:15], v[120:123], v[180:183], v[12:15]
	v_mfma_f32_16x16x32_bf16 v[4:7], v[112:115], v[188:191], v[4:7]
	v_mfma_f32_16x16x32_bf16 v[0:3], v[120:123], v[188:191], v[0:3]
	s_setprio 0
	s_barrier
	s_add_i32 s58, 0, 0x18000
	s_add_i32 s59, 0, 0x1c000
	v_add_u32_e32 v100, s58, v224
	v_add_u32_e32 v120, s59, v224
	ds_read_b128 v[88:91], v100
	ds_read_b128 v[92:95], v100 offset:1024
	ds_read_b128 v[96:99], v100 offset:2048
	ds_read_b128 v[100:103], v100 offset:3072
	ds_read_b128 v[108:111], v120
	ds_read_b128 v[112:115], v120 offset:1024
	ds_read_b128 v[116:119], v120 offset:2048
	ds_read_b128 v[120:123], v120 offset:3072
	s_add_u32 s10, s34, 0x40000
	s_addc_u32 s11, s35, 0
	s_mov_b32 m0, s42
	v_lshl_add_u64 v[212:213], s[10:11], 0, v[196:197]
	ds_read_b128 v[160:163], v225 offset:32768
	ds_read_b128 v[164:167], v225 offset:33792
	ds_read_b128 v[168:171], v225 offset:34816
	ds_read_b128 v[172:175], v225 offset:35840
	ds_read_b128 v[176:179], v225 offset:36864
	ds_read_b128 v[180:183], v225 offset:37888
	ds_read_b128 v[184:187], v225 offset:38912
	ds_read_b128 v[188:191], v225 offset:39936
	global_load_lds_dwordx4 v[212:213], off
	v_lshl_add_u64 v[212:213], s[10:11], 0, v[192:193]
	s_mov_b32 m0, s43
	s_nop 0
	global_load_lds_dwordx4 v[212:213], off
	s_waitcnt vmcnt(8)
	s_waitcnt lgkmcnt(0)
	s_barrier
	s_setprio 1
	s_waitcnt lgkmcnt(0)
	v_mfma_f32_16x16x32_bf16 v[156:159], v[88:91], v[160:163], v[156:159]
	v_mfma_f32_16x16x32_bf16 v[152:155], v[96:99], v[160:163], v[152:155]
	v_mfma_f32_16x16x32_bf16 v[144:147], v[88:91], v[168:171], v[144:147]
	v_mfma_f32_16x16x32_bf16 v[136:139], v[96:99], v[168:171], v[136:139]
	v_mfma_f32_16x16x32_bf16 v[124:127], v[88:91], v[176:179], v[124:127]
	v_mfma_f32_16x16x32_bf16 v[104:107], v[96:99], v[176:179], v[104:107]
	v_mfma_f32_16x16x32_bf16 v[80:83], v[88:91], v[184:187], v[80:83]
	v_mfma_f32_16x16x32_bf16 v[72:75], v[96:99], v[184:187], v[72:75]
	v_mfma_f32_16x16x32_bf16 v[156:159], v[92:95], v[164:167], v[156:159]
	v_mfma_f32_16x16x32_bf16 v[152:155], v[100:103], v[164:167], v[152:155]
	v_mfma_f32_16x16x32_bf16 v[144:147], v[92:95], v[172:175], v[144:147]
	v_mfma_f32_16x16x32_bf16 v[136:139], v[100:103], v[172:175], v[136:139]
	v_mfma_f32_16x16x32_bf16 v[124:127], v[92:95], v[180:183], v[124:127]
	v_mfma_f32_16x16x32_bf16 v[104:107], v[100:103], v[180:183], v[104:107]
	v_mfma_f32_16x16x32_bf16 v[80:83], v[92:95], v[188:191], v[80:83]
	v_mfma_f32_16x16x32_bf16 v[72:75], v[100:103], v[188:191], v[72:75]
	s_setprio 0
	s_setprio 1
	v_mfma_f32_16x16x32_bf16 v[148:151], v[108:111], v[160:163], v[148:151]
	v_mfma_f32_16x16x32_bf16 v[140:143], v[116:119], v[160:163], v[140:143]
	v_mfma_f32_16x16x32_bf16 v[132:135], v[108:111], v[168:171], v[132:135]
	v_mfma_f32_16x16x32_bf16 v[128:131], v[116:119], v[168:171], v[128:131]
	v_mfma_f32_16x16x32_bf16 v[84:87], v[108:111], v[176:179], v[84:87]
	v_mfma_f32_16x16x32_bf16 v[76:79], v[116:119], v[176:179], v[76:79]
	v_mfma_f32_16x16x32_bf16 v[68:71], v[108:111], v[184:187], v[68:71]
	v_mfma_f32_16x16x32_bf16 v[64:67], v[116:119], v[184:187], v[64:67]
	v_mfma_f32_16x16x32_bf16 v[148:151], v[112:115], v[164:167], v[148:151]
	v_mfma_f32_16x16x32_bf16 v[140:143], v[120:123], v[164:167], v[140:143]
	v_mfma_f32_16x16x32_bf16 v[132:135], v[112:115], v[172:175], v[132:135]
	v_mfma_f32_16x16x32_bf16 v[128:131], v[120:123], v[172:175], v[128:131]
	v_mfma_f32_16x16x32_bf16 v[84:87], v[112:115], v[180:183], v[84:87]
	v_mfma_f32_16x16x32_bf16 v[76:79], v[120:123], v[180:183], v[76:79]
	v_mfma_f32_16x16x32_bf16 v[68:71], v[112:115], v[188:191], v[68:71]
	v_mfma_f32_16x16x32_bf16 v[64:67], v[120:123], v[188:191], v[64:67]
	s_setprio 0
	s_barrier
; #define PG8_STAGE(bufoff, gbase, voff) do { _Pragma("unroll") for (int _i = 0; _i < 2; ++_i) \
;         __builtin_amdgcn_global_load_lds((const unsigned*)((const char*)(gbase) + (voff)[_i]), (PG8_LAS unsigned*)(lds + (bufoff) + ldsw + _i * 8192), 16, 0, 0); } while (0)
; #define PG8_LDA(dst, b, h) do { _Pragma("unroll") for (int m = 0; m < 4; ++m) _Pragma("unroll") for (int k = 0; k < 2; ++k) dst[m][k] = *(const PG8_LAS bf16x8*)(lds + PG8_SA(b, h) + aoff + m * 2048 + k * 1024); } while (0)
; #define PG8_MMA(ai, bj, At, Bt) do { __builtin_amdgcn_s_setprio(1); _Pragma("unroll") for (int m = 0; m < 4; ++m) _Pragma("unroll") for (int n = 0; n < 2; ++n) _Pragma("unroll") for (int k = 0; k < 2; ++k) \
;         acc[ai][bj][m][n] = __builtin_amdgcn_mfma_f32_16x16x32_bf16(Bt[n][k], At[m][k], acc[ai][bj][m][n], 0, 0, 0); __builtin_amdgcn_s_setprio(0); } while (0)
; #define PG8_WAIT_V(n) asm volatile("s_waitcnt vmcnt(" #n ")" ::: "memory")
; #define PG8_WAIT_L(n) asm volatile("s_waitcnt lgkmcnt(" #n ")" ::: "memory")
; #define PG8_BAR __builtin_amdgcn_s_barrier()
; #define PG8_SCHED __builtin_amdgcn_sched_barrier(0)
; template <class Epi, class Sched, bool ALIGN_EPI = false, bool SP2 = false>
; __device__ __forceinline__ void gemm_phase(PG8_LAS unsigned char* lds, const Gemm g, const Sched& S, const Epi& E, int wave_s_) {
;     ...
;         for (int t = 0; t < nt; t += 2) {
;     ...
;             PG8_LDA(At, 1, 1); PG8_STAGE(PG8_SB(1, 0), b3, voffB); PG8_STAGE(PG8_SB(1, 1), b3 + hstep, voffB); PG8_STAGE(PG8_SA(1, 0), a3, voffA);
;             PG8_WAIT_V(8); PG8_WAIT_L(0); PG8_BAR; PG8_MMA(1, 0, At, B0); PG8_MMA(1, 1, At, B1); PG8_BAR; PG8_SCHED;
	s_add_i32 s10, s58, s39
	v_lshl_add_u64 v[198:199], v[198:199], 0, s[76:77]
	s_mov_b32 m0, s10
	ds_read_b128 v[160:163], v225 offset:49152
	ds_read_b128 v[164:167], v225 offset:50176
	ds_read_b128 v[168:171], v225 offset:51200
	ds_read_b128 v[172:175], v225 offset:52224
	ds_read_b128 v[176:179], v225 offset:53248
	ds_read_b128 v[180:183], v225 offset:54272
	ds_read_b128 v[184:187], v225 offset:55296
	ds_read_b128 v[188:191], v225 offset:56320
	global_load_lds_dwordx4 v[198:199], off
	s_add_i32 m0, s10, 0x2000
	s_add_u32 s10, s30, 0x40080
	v_lshl_add_u64 v[198:199], v[204:205], 0, s[76:77]
	s_addc_u32 s11, s31, 0
	s_add_i32 s30, s59, s39
	global_load_lds_dwordx4 v[198:199], off
	v_lshl_add_u64 v[198:199], s[10:11], 0, v[196:197]
	s_mov_b32 m0, s30
	s_nop 0
	global_load_lds_dwordx4 v[198:199], off
	v_lshl_add_u64 v[198:199], s[10:11], 0, v[192:193]
	s_add_i32 m0, s30, 0x2000
	s_nop 0
	global_load_lds_dwordx4 v[198:199], off
	v_lshl_add_u64 v[198:199], v[208:209], 0, s[76:77]
	s_mov_b32 m0, s46
	s_nop 0
	global_load_lds_dwordx4 v[198:199], off
	v_lshl_add_u64 v[198:199], v[210:211], 0, s[76:77]
	s_mov_b32 m0, s47
	s_nop 0
	global_load_lds_dwordx4 v[198:199], off
	s_waitcnt vmcnt(8)
	s_waitcnt lgkmcnt(0)
	s_barrier
	s_setprio 1
	s_waitcnt lgkmcnt(0)
	v_mfma_f32_16x16x32_bf16 v[60:63], v[88:91], v[160:163], v[60:63]
	v_mfma_f32_16x16x32_bf16 v[56:59], v[96:99], v[160:163], v[56:59]
	v_mfma_f32_16x16x32_bf16 v[48:51], v[88:91], v[168:171], v[48:51]
	v_mfma_f32_16x16x32_bf16 v[40:43], v[96:99], v[168:171], v[40:43]
	v_mfma_f32_16x16x32_bf16 v[28:31], v[88:91], v[176:179], v[28:31]
	v_mfma_f32_16x16x32_bf16 v[24:27], v[96:99], v[176:179], v[24:27]
	v_mfma_f32_16x16x32_bf16 v[16:19], v[88:91], v[184:187], v[16:19]
	v_mfma_f32_16x16x32_bf16 v[8:11], v[96:99], v[184:187], v[8:11]
	v_mfma_f32_16x16x32_bf16 v[60:63], v[92:95], v[164:167], v[60:63]
	v_mfma_f32_16x16x32_bf16 v[56:59], v[100:103], v[164:167], v[56:59]
	v_mfma_f32_16x16x32_bf16 v[48:51], v[92:95], v[172:175], v[48:51]
	v_mfma_f32_16x16x32_bf16 v[40:43], v[100:103], v[172:175], v[40:43]
	v_mfma_f32_16x16x32_bf16 v[28:31], v[92:95], v[180:183], v[28:31]
	v_mfma_f32_16x16x32_bf16 v[24:27], v[100:103], v[180:183], v[24:27]
	v_mfma_f32_16x16x32_bf16 v[16:19], v[92:95], v[188:191], v[16:19]
	v_mfma_f32_16x16x32_bf16 v[8:11], v[100:103], v[188:191], v[8:11]
	s_setprio 0
	s_setprio 1
	v_mfma_f32_16x16x32_bf16 v[52:55], v[108:111], v[160:163], v[52:55]
	v_mfma_f32_16x16x32_bf16 v[44:47], v[116:119], v[160:163], v[44:47]
	v_mfma_f32_16x16x32_bf16 v[36:39], v[108:111], v[168:171], v[36:39]
	v_mfma_f32_16x16x32_bf16 v[32:35], v[116:119], v[168:171], v[32:35]
	v_mfma_f32_16x16x32_bf16 v[20:23], v[108:111], v[176:179], v[20:23]
	v_mfma_f32_16x16x32_bf16 v[12:15], v[116:119], v[176:179], v[12:15]
	v_mfma_f32_16x16x32_bf16 v[4:7], v[108:111], v[184:187], v[4:7]
	v_mfma_f32_16x16x32_bf16 v[0:3], v[116:119], v[184:187], v[0:3]
	v_mfma_f32_16x16x32_bf16 v[52:55], v[112:115], v[164:167], v[52:55]
	v_mfma_f32_16x16x32_bf16 v[44:47], v[120:123], v[164:167], v[44:47]
	v_mfma_f32_16x16x32_bf16 v[36:39], v[112:115], v[172:175], v[36:39]
	v_mfma_f32_16x16x32_bf16 v[32:35], v[120:123], v[172:175], v[32:35]
	v_mfma_f32_16x16x32_bf16 v[20:23], v[112:115], v[180:183], v[20:23]
	v_mfma_f32_16x16x32_bf16 v[12:15], v[120:123], v[180:183], v[12:15]
	v_mfma_f32_16x16x32_bf16 v[4:7], v[112:115], v[188:191], v[4:7]
	v_mfma_f32_16x16x32_bf16 v[0:3], v[120:123], v[188:191], v[0:3]
	s_setprio 0
	s_barrier
	s_add_u32 s55, s55, 0x100
	s_addc_u32 s56, s56, 0
	s_cmp_ge_u32 s57, s9
	s_mov_b64 s[10:11], s[28:29]
	s_mov_b32 s30, s57
	s_cbranch_scc0 .LBB0_1581
	s_branch .Lpeel_exit_6

; #define PG8_BAR __builtin_amdgcn_s_barrier()
; template <class Epi, class Sched, bool ALIGN_EPI = false, bool SP2 = false>
; __device__ __forceinline__ void gemm_phase(PG8_LAS unsigned char* lds, const Gemm g, const Sched& S, const Epi& E, int wave_s_) {
;     ...
;         if constexpr (ALIGN_EPI) { if (wr == 0) PG8_BAR; }
.Lpeel_exit_6:
	s_and_b64 vcc, exec, s[18:19]
	s_cbranch_vccz .LBB0_1584
	s_barrier

; #define PG8_STAGE(bufoff, gbase, voff) do { _Pragma("unroll") for (int _i = 0; _i < 2; ++_i) \
;         __builtin_amdgcn_global_load_lds((const unsigned*)((const char*)(gbase) + (voff)[_i]), (PG8_LAS unsigned*)(lds + (bufoff) + ldsw + _i * 8192), 16, 0, 0); } while (0)
; #define PG8_LDA(dst, b, h) do { _Pragma("unroll") for (int m = 0; m < 4; ++m) _Pragma("unroll") for (int k = 0; k < 2; ++k) dst[m][k] = *(const PG8_LAS bf16x8*)(lds + PG8_SA(b, h) + aoff + m * 2048 + k * 1024); } while (0)
; #define PG8_LDB(dst, b, h) do { _Pragma("unroll") for (int n = 0; n < 2; ++n) _Pragma("unroll") for (int k = 0; k < 2; ++k) dst[n][k] = *(const PG8_LAS bf16x8*)(lds + PG8_SB(b, h) + boff + n * 2048 + k * 1024); } while (0)
; #define PG8_MMA(ai, bj, At, Bt) do { __builtin_amdgcn_s_setprio(1); _Pragma("unroll") for (int m = 0; m < 4; ++m) _Pragma("unroll") for (int n = 0; n < 2; ++n) _Pragma("unroll") for (int k = 0; k < 2; ++k) \
;         acc[ai][bj][m][n] = __builtin_amdgcn_mfma_f32_16x16x32_bf16(Bt[n][k], At[m][k], acc[ai][bj][m][n], 0, 0, 0); __builtin_amdgcn_s_setprio(0); } while (0)
; #define PG8_WAIT_V(n) asm volatile("s_waitcnt vmcnt(" #n ")" ::: "memory")
; #define PG8_BAR __builtin_amdgcn_s_barrier()
; template <class Epi, class Sched, bool ALIGN_EPI = false, bool SP2 = false>
; __device__ __forceinline__ void gemm_phase(PG8_LAS unsigned char* lds, const Gemm g, const Sched& S, const Epi& E, int wave_s_) {
;     ...
;         for (int t = 0; t < nt; t += 2) {
;             const bool last = (t == nt - 2);
;             const char* a1 = cA + (size_t)(t + 1) * kstep;
;             const char* a2 = last ? nA : cA + (size_t)(t + 2) * kstep; const char* b2 = last ? nB : cB + (size_t)(t + 2) * kstep;
;             const char* a3 = a2 + kstep; const char* b3 = b2 + kstep;
;             if (last && has_next) S.a_ready(nxt);
;             if constexpr (SP2) {
;             PG8_LDB(B0, 0, 0); PG8_LDB(B1, 0, 1); PG8_SCHED; PG8_LDA(At, 0, 0); PG8_STAGE(PG8_SA(1, 1), a1 + hstep, voffA);
;             PG8_WAIT_V(8); PG8_WAIT_L(0); PG8_BAR; PG8_MMA(0, 0, At, B0); PG8_MMA(0, 1, At, B1); PG8_BAR; PG8_SCHED;
;             PG8_LDA(At, 0, 1); PG8_STAGE(PG8_SB(0, 0), b2, voffB); PG8_STAGE(PG8_SB(0, 1), b2 + hstep, voffB); PG8_STAGE(PG8_SA(0, 0), a2, voffA);
;             PG8_WAIT_V(8); PG8_WAIT_L(0); PG8_BAR; PG8_MMA(1, 0, At, B0); PG8_MMA(1, 1, At, B1); PG8_BAR; PG8_SCHED;
.LBB0_1819:
	s_add_u32 s15, s18, 0x100
	s_addc_u32 s45, s19, 0
	s_add_u32 s18, s20, 0x40080
	v_mov_b32_e32 v0, 0
	s_addc_u32 s19, s21, 0
	s_mov_b32 s46, -2
	s_add_u32 s20, s18, 0xfffc0080
	s_addc_u32 s21, s19, -1
	s_add_i32 s47, 0, 0x10000
	s_cmp_eq_u32 s46, 12
	s_cselect_b32 s23, s7, s21
	s_cselect_b32 s22, s6, s20
	s_cselect_b32 s21, s17, s45
	s_cselect_b32 s20, s16, s15
	s_add_i32 s50, 0, 0x14000
	v_add_u32_e32 v152, s47, v138
	v_add_u32_e32 v168, s50, v138
	ds_read_b128 v[140:143], v152
	ds_read_b128 v[144:147], v152 offset:1024
	ds_read_b128 v[148:151], v152 offset:2048
	ds_read_b128 v[152:155], v152 offset:3072
	ds_read_b128 v[156:159], v168
	ds_read_b128 v[160:163], v168 offset:1024
	ds_read_b128 v[164:167], v168 offset:2048
	ds_read_b128 v[168:171], v168 offset:3072
	v_lshl_add_u64 v[198:199], s[18:19], 0, v[136:137]
	s_add_i32 m0, s31, 0xc000
	ds_read_b128 v[172:175], v139
	ds_read_b128 v[176:179], v139 offset:1024
	ds_read_b128 v[180:183], v139 offset:2048
	ds_read_b128 v[184:187], v139 offset:3072
	ds_read_b128 v[188:191], v139 offset:4096
	ds_read_b128 v[192:195], v139 offset:5120
	ds_read_b128 v[206:209], v139 offset:6144
	ds_read_b128 v[210:213], v139 offset:7168
	global_load_lds_dwordx4 v[198:199], off
	v_lshl_add_u64 v[198:199], s[18:19], 0, v[134:135]
	s_add_i32 m0, s31, 0xe000
	s_nop 0
	global_load_lds_dwordx4 v[198:199], off
	s_waitcnt vmcnt(8)
	s_waitcnt lgkmcnt(0)
	s_barrier
	s_setprio 1
	s_waitcnt lgkmcnt(0)
	v_mfma_f32_16x16x32_bf16 v[124:127], v[140:143], v[172:175], 0
	v_mfma_f32_16x16x32_bf16 v[116:119], v[148:151], v[172:175], 0
	v_mfma_f32_16x16x32_bf16 v[108:111], v[140:143], v[180:183], 0
	v_mfma_f32_16x16x32_bf16 v[100:103], v[148:151], v[180:183], 0
	v_mfma_f32_16x16x32_bf16 v[92:95], v[140:143], v[188:191], 0
	v_mfma_f32_16x16x32_bf16 v[84:87], v[148:151], v[188:191], 0
	v_mfma_f32_16x16x32_bf16 v[76:79], v[140:143], v[206:209], 0
	v_mfma_f32_16x16x32_bf16 v[68:71], v[148:151], v[206:209], 0
	v_mfma_f32_16x16x32_bf16 v[124:127], v[144:147], v[176:179], v[124:127]
	v_mfma_f32_16x16x32_bf16 v[116:119], v[152:155], v[176:179], v[116:119]
	v_mfma_f32_16x16x32_bf16 v[108:111], v[144:147], v[184:187], v[108:111]
	v_mfma_f32_16x16x32_bf16 v[100:103], v[152:155], v[184:187], v[100:103]
	v_mfma_f32_16x16x32_bf16 v[92:95], v[144:147], v[192:195], v[92:95]
	v_mfma_f32_16x16x32_bf16 v[84:87], v[152:155], v[192:195], v[84:87]
	v_mfma_f32_16x16x32_bf16 v[76:79], v[144:147], v[210:213], v[76:79]
	v_mfma_f32_16x16x32_bf16 v[68:71], v[152:155], v[210:213], v[68:71]
	s_setprio 0
	s_setprio 1
	v_mfma_f32_16x16x32_bf16 v[120:123], v[156:159], v[172:175], 0
	v_mfma_f32_16x16x32_bf16 v[112:115], v[164:167], v[172:175], 0
	v_mfma_f32_16x16x32_bf16 v[104:107], v[156:159], v[180:183], 0
	v_mfma_f32_16x16x32_bf16 v[96:99], v[164:167], v[180:183], 0
	v_mfma_f32_16x16x32_bf16 v[88:91], v[156:159], v[188:191], 0
	v_mfma_f32_16x16x32_bf16 v[80:83], v[164:167], v[188:191], 0
	v_mfma_f32_16x16x32_bf16 v[72:75], v[156:159], v[206:209], 0
	v_mfma_f32_16x16x32_bf16 v[64:67], v[164:167], v[206:209], 0
	v_mfma_f32_16x16x32_bf16 v[120:123], v[160:163], v[176:179], v[120:123]
	v_mfma_f32_16x16x32_bf16 v[112:115], v[168:171], v[176:179], v[112:115]
	v_mfma_f32_16x16x32_bf16 v[104:107], v[160:163], v[184:187], v[104:107]
	v_mfma_f32_16x16x32_bf16 v[96:99], v[168:171], v[184:187], v[96:99]
	v_mfma_f32_16x16x32_bf16 v[88:91], v[160:163], v[192:195], v[88:91]
	v_mfma_f32_16x16x32_bf16 v[80:83], v[168:171], v[192:195], v[80:83]
	v_mfma_f32_16x16x32_bf16 v[72:75], v[160:163], v[210:213], v[72:75]
	v_mfma_f32_16x16x32_bf16 v[64:67], v[168:171], v[210:213], v[64:67]
	s_setprio 0
	s_barrier
	s_add_i32 s47, s47, s30
	v_lshl_add_u64 v[198:199], s[20:21], 0, v[196:197]
	s_mov_b32 m0, s47
	ds_read_b128 v[172:175], v139 offset:16384
	ds_read_b128 v[176:179], v139 offset:17408
	ds_read_b128 v[180:183], v139 offset:18432
	ds_read_b128 v[184:187], v139 offset:19456
	ds_read_b128 v[188:191], v139 offset:20480
	ds_read_b128 v[192:195], v139 offset:21504
	ds_read_b128 v[206:209], v139 offset:22528
	ds_read_b128 v[210:213], v139 offset:23552
	global_load_lds_dwordx4 v[198:199], off
	s_add_i32 m0, s47, 0x2000
	s_add_u32 s48, s20, 0x40000
	v_lshl_add_u64 v[204:205], s[20:21], 0, v[132:133]
	s_addc_u32 s49, s21, 0
	s_add_i32 s47, s50, s30
	global_load_lds_dwordx4 v[204:205], off
	v_lshl_add_u64 v[214:215], s[48:49], 0, v[196:197]
	s_mov_b32 m0, s47
	v_lshl_add_u64 v[216:217], s[22:23], 0, v[130:131]
	global_load_lds_dwordx4 v[214:215], off
	v_lshl_add_u64 v[214:215], s[48:49], 0, v[132:133]
	s_add_i32 m0, s47, 0x2000
	s_nop 0
	global_load_lds_dwordx4 v[214:215], off
	v_lshl_add_u64 v[214:215], s[22:23], 0, v[128:129]
	s_mov_b32 m0, s31
	s_nop 0
	global_load_lds_dwordx4 v[214:215], off
	s_mov_b32 m0, s33
	s_nop 0
	global_load_lds_dwordx4 v[216:217], off
	s_waitcnt vmcnt(8)
	s_waitcnt lgkmcnt(0)
	s_barrier
; #define PG8_STAGE(bufoff, gbase, voff) do { _Pragma("unroll") for (int _i = 0; _i < 2; ++_i) \
;         __builtin_amdgcn_global_load_lds((const unsigned*)((const char*)(gbase) + (voff)[_i]), (PG8_LAS unsigned*)(lds + (bufoff) + ldsw + _i * 8192), 16, 0, 0); } while (0)
; #define PG8_LDA(dst, b, h) do { _Pragma("unroll") for (int m = 0; m < 4; ++m) _Pragma("unroll") for (int k = 0; k < 2; ++k) dst[m][k] = *(const PG8_LAS bf16x8*)(lds + PG8_SA(b, h) + aoff + m * 2048 + k * 1024); } while (0)
; #define PG8_LDB(dst, b, h) do { _Pragma("unroll") for (int n = 0; n < 2; ++n) _Pragma("unroll") for (int k = 0; k < 2; ++k) dst[n][k] = *(const PG8_LAS bf16x8*)(lds + PG8_SB(b, h) + boff + n * 2048 + k * 1024); } while (0)
; #define PG8_MMA(ai, bj, At, Bt) do { __builtin_amdgcn_s_setprio(1); _Pragma("unroll") for (int m = 0; m < 4; ++m) _Pragma("unroll") for (int n = 0; n < 2; ++n) _Pragma("unroll") for (int k = 0; k < 2; ++k) \
;         acc[ai][bj][m][n] = __builtin_amdgcn_mfma_f32_16x16x32_bf16(Bt[n][k], At[m][k], acc[ai][bj][m][n], 0, 0, 0); __builtin_amdgcn_s_setprio(0); } while (0)
; #define PG8_WAIT_V(n) asm volatile("s_waitcnt vmcnt(" #n ")" ::: "memory")
; #define PG8_WAIT_L(n) asm volatile("s_waitcnt lgkmcnt(" #n ")" ::: "memory")
; #define PG8_BAR __builtin_amdgcn_s_barrier()
; #define PG8_SCHED __builtin_amdgcn_sched_barrier(0)
; template <class Epi, class Sched, bool ALIGN_EPI = false, bool SP2 = false>
; __device__ __forceinline__ void gemm_phase(PG8_LAS unsigned char* lds, const Gemm g, const Sched& S, const Epi& E, int wave_s_) {
;     ...
;             PG8_WAIT_V(8); PG8_WAIT_L(0); PG8_BAR; PG8_MMA(1, 0, At, B0); PG8_MMA(1, 1, At, B1); PG8_BAR; PG8_SCHED;
;             PG8_LDB(B0, 1, 0); PG8_LDB(B1, 1, 1); PG8_SCHED; PG8_LDA(At, 1, 0); PG8_STAGE(PG8_SA(0, 1), a2 + hstep, voffA);
;             PG8_WAIT_V(8); PG8_WAIT_L(0); PG8_BAR; PG8_MMA(0, 0, At, B0); PG8_MMA(0, 1, At, B1); PG8_BAR; PG8_SCHED;
	s_setprio 1
	s_waitcnt lgkmcnt(0)
	v_mfma_f32_16x16x32_bf16 v[60:63], v[140:143], v[172:175], 0
	v_mfma_f32_16x16x32_bf16 v[52:55], v[148:151], v[172:175], 0
	v_mfma_f32_16x16x32_bf16 v[44:47], v[140:143], v[180:183], 0
	v_mfma_f32_16x16x32_bf16 v[36:39], v[148:151], v[180:183], 0
	v_mfma_f32_16x16x32_bf16 v[28:31], v[140:143], v[188:191], 0
	v_mfma_f32_16x16x32_bf16 v[20:23], v[148:151], v[188:191], 0
	v_mfma_f32_16x16x32_bf16 v[12:15], v[140:143], v[206:209], 0
	v_mfma_f32_16x16x32_bf16 v[4:7], v[148:151], v[206:209], 0
	v_mfma_f32_16x16x32_bf16 v[60:63], v[144:147], v[176:179], v[60:63]
	v_mfma_f32_16x16x32_bf16 v[52:55], v[152:155], v[176:179], v[52:55]
	v_mfma_f32_16x16x32_bf16 v[44:47], v[144:147], v[184:187], v[44:47]
	v_mfma_f32_16x16x32_bf16 v[36:39], v[152:155], v[184:187], v[36:39]
	v_mfma_f32_16x16x32_bf16 v[28:31], v[144:147], v[192:195], v[28:31]
	v_mfma_f32_16x16x32_bf16 v[20:23], v[152:155], v[192:195], v[20:23]
	v_mfma_f32_16x16x32_bf16 v[12:15], v[144:147], v[210:213], v[12:15]
	v_mfma_f32_16x16x32_bf16 v[4:7], v[152:155], v[210:213], v[4:7]
	s_setprio 0
	s_setprio 1
	v_mfma_f32_16x16x32_bf16 v[56:59], v[156:159], v[172:175], 0
	v_mfma_f32_16x16x32_bf16 v[48:51], v[164:167], v[172:175], 0
	v_mfma_f32_16x16x32_bf16 v[40:43], v[156:159], v[180:183], 0
	v_mfma_f32_16x16x32_bf16 v[32:35], v[164:167], v[180:183], 0
	v_mfma_f32_16x16x32_bf16 v[24:27], v[156:159], v[188:191], 0
	v_mfma_f32_16x16x32_bf16 v[16:19], v[164:167], v[188:191], 0
	v_mfma_f32_16x16x32_bf16 v[8:11], v[156:159], v[206:209], 0
	v_mfma_f32_16x16x32_bf16 v[0:3], v[164:167], v[206:209], 0
	v_mfma_f32_16x16x32_bf16 v[56:59], v[160:163], v[176:179], v[56:59]
	v_mfma_f32_16x16x32_bf16 v[48:51], v[168:171], v[176:179], v[48:51]
	v_mfma_f32_16x16x32_bf16 v[40:43], v[160:163], v[184:187], v[40:43]
	v_mfma_f32_16x16x32_bf16 v[32:35], v[168:171], v[184:187], v[32:35]
	v_mfma_f32_16x16x32_bf16 v[24:27], v[160:163], v[192:195], v[24:27]
	v_mfma_f32_16x16x32_bf16 v[16:19], v[168:171], v[192:195], v[16:19]
	v_mfma_f32_16x16x32_bf16 v[8:11], v[160:163], v[210:213], v[8:11]
	v_mfma_f32_16x16x32_bf16 v[0:3], v[168:171], v[210:213], v[0:3]
	s_setprio 0
	s_barrier
	s_add_i32 s47, 0, 0x18000
	s_add_i32 s48, 0, 0x1c000
	v_add_u32_e32 v152, s47, v138
	v_add_u32_e32 v168, s48, v138
	ds_read_b128 v[140:143], v152
	ds_read_b128 v[144:147], v152 offset:1024
	ds_read_b128 v[148:151], v152 offset:2048
	ds_read_b128 v[152:155], v152 offset:3072
	ds_read_b128 v[156:159], v168
	ds_read_b128 v[160:163], v168 offset:1024
	ds_read_b128 v[164:167], v168 offset:2048
	ds_read_b128 v[168:171], v168 offset:3072
	s_add_u32 s22, s22, 0x40000
	s_addc_u32 s23, s23, 0
	s_mov_b32 m0, s34
	v_lshl_add_u64 v[218:219], s[22:23], 0, v[128:129]
	ds_read_b128 v[172:175], v139 offset:32768
	ds_read_b128 v[176:179], v139 offset:33792
	ds_read_b128 v[180:183], v139 offset:34816
	ds_read_b128 v[184:187], v139 offset:35840
	ds_read_b128 v[188:191], v139 offset:36864
	ds_read_b128 v[192:195], v139 offset:37888
	ds_read_b128 v[206:209], v139 offset:38912
	ds_read_b128 v[210:213], v139 offset:39936
	global_load_lds_dwordx4 v[218:219], off
	v_lshl_add_u64 v[218:219], s[22:23], 0, v[130:131]
	s_mov_b32 m0, s35
	s_nop 0
	global_load_lds_dwordx4 v[218:219], off
	s_waitcnt vmcnt(8)
	s_waitcnt lgkmcnt(0)
	s_barrier
	s_setprio 1
	s_waitcnt lgkmcnt(0)
	v_mfma_f32_16x16x32_bf16 v[124:127], v[140:143], v[172:175], v[124:127]
	v_mfma_f32_16x16x32_bf16 v[116:119], v[148:151], v[172:175], v[116:119]
	v_mfma_f32_16x16x32_bf16 v[108:111], v[140:143], v[180:183], v[108:111]
	v_mfma_f32_16x16x32_bf16 v[100:103], v[148:151], v[180:183], v[100:103]
	v_mfma_f32_16x16x32_bf16 v[92:95], v[140:143], v[188:191], v[92:95]
	v_mfma_f32_16x16x32_bf16 v[84:87], v[148:151], v[188:191], v[84:87]
	v_mfma_f32_16x16x32_bf16 v[76:79], v[140:143], v[206:209], v[76:79]
	v_mfma_f32_16x16x32_bf16 v[68:71], v[148:151], v[206:209], v[68:71]
	v_mfma_f32_16x16x32_bf16 v[124:127], v[144:147], v[176:179], v[124:127]
	v_mfma_f32_16x16x32_bf16 v[116:119], v[152:155], v[176:179], v[116:119]
	v_mfma_f32_16x16x32_bf16 v[108:111], v[144:147], v[184:187], v[108:111]
	v_mfma_f32_16x16x32_bf16 v[100:103], v[152:155], v[184:187], v[100:103]
	v_mfma_f32_16x16x32_bf16 v[92:95], v[144:147], v[192:195], v[92:95]
	v_mfma_f32_16x16x32_bf16 v[84:87], v[152:155], v[192:195], v[84:87]
	v_mfma_f32_16x16x32_bf16 v[76:79], v[144:147], v[210:213], v[76:79]
	v_mfma_f32_16x16x32_bf16 v[68:71], v[152:155], v[210:213], v[68:71]
	s_setprio 0
	s_setprio 1
	v_mfma_f32_16x16x32_bf16 v[120:123], v[156:159], v[172:175], v[120:123]
	v_mfma_f32_16x16x32_bf16 v[112:115], v[164:167], v[172:175], v[112:115]
	v_mfma_f32_16x16x32_bf16 v[104:107], v[156:159], v[180:183], v[104:107]
	v_mfma_f32_16x16x32_bf16 v[96:99], v[164:167], v[180:183], v[96:99]
	v_mfma_f32_16x16x32_bf16 v[88:91], v[156:159], v[188:191], v[88:91]
	v_mfma_f32_16x16x32_bf16 v[80:83], v[164:167], v[188:191], v[80:83]
	v_mfma_f32_16x16x32_bf16 v[72:75], v[156:159], v[206:209], v[72:75]
	v_mfma_f32_16x16x32_bf16 v[64:67], v[164:167], v[206:209], v[64:67]
	v_mfma_f32_16x16x32_bf16 v[120:123], v[160:163], v[176:179], v[120:123]
	v_mfma_f32_16x16x32_bf16 v[112:115], v[168:171], v[176:179], v[112:115]
	v_mfma_f32_16x16x32_bf16 v[104:107], v[160:163], v[184:187], v[104:107]
	v_mfma_f32_16x16x32_bf16 v[96:99], v[168:171], v[184:187], v[96:99]
	v_mfma_f32_16x16x32_bf16 v[88:91], v[160:163], v[192:195], v[88:91]
	v_mfma_f32_16x16x32_bf16 v[80:83], v[168:171], v[192:195], v[80:83]
	v_mfma_f32_16x16x32_bf16 v[72:75], v[160:163], v[210:213], v[72:75]
	v_mfma_f32_16x16x32_bf16 v[64:67], v[168:171], v[210:213], v[64:67]
	s_setprio 0
	s_barrier
; #define PG8_STAGE(bufoff, gbase, voff) do { _Pragma("unroll") for (int _i = 0; _i < 2; ++_i) \
;         __builtin_amdgcn_global_load_lds((const unsigned*)((const char*)(gbase) + (voff)[_i]), (PG8_LAS unsigned*)(lds + (bufoff) + ldsw + _i * 8192), 16, 0, 0); } while (0)
; #define PG8_LDA(dst, b, h) do { _Pragma("unroll") for (int m = 0; m < 4; ++m) _Pragma("unroll") for (int k = 0; k < 2; ++k) dst[m][k] = *(const PG8_LAS bf16x8*)(lds + PG8_SA(b, h) + aoff + m * 2048 + k * 1024); } while (0)
; #define PG8_MMA(ai, bj, At, Bt) do { __builtin_amdgcn_s_setprio(1); _Pragma("unroll") for (int m = 0; m < 4; ++m) _Pragma("unroll") for (int n = 0; n < 2; ++n) _Pragma("unroll") for (int k = 0; k < 2; ++k) \
;         acc[ai][bj][m][n] = __builtin_amdgcn_mfma_f32_16x16x32_bf16(Bt[n][k], At[m][k], acc[ai][bj][m][n], 0, 0, 0); __builtin_amdgcn_s_setprio(0); } while (0)
; #define PG8_WAIT_V(n) asm volatile("s_waitcnt vmcnt(" #n ")" ::: "memory")
; #define PG8_WAIT_L(n) asm volatile("s_waitcnt lgkmcnt(" #n ")" ::: "memory")
; #define PG8_BAR __builtin_amdgcn_s_barrier()
; #define PG8_SCHED __builtin_amdgcn_sched_barrier(0)
; template <class Epi, class Sched, bool ALIGN_EPI = false, bool SP2 = false>
; __device__ __forceinline__ void gemm_phase(PG8_LAS unsigned char* lds, const Gemm g, const Sched& S, const Epi& E, int wave_s_) {
;     ...
;         for (int t = 0; t < nt; t += 2) {
;     ...
;             PG8_LDA(At, 1, 1); PG8_STAGE(PG8_SB(1, 0), b3, voffB); PG8_STAGE(PG8_SB(1, 1), b3 + hstep, voffB); PG8_STAGE(PG8_SA(1, 0), a3, voffA);
;             PG8_WAIT_V(8); PG8_WAIT_L(0); PG8_BAR; PG8_MMA(1, 0, At, B0); PG8_MMA(1, 1, At, B1); PG8_BAR; PG8_SCHED;
	s_add_i32 s22, s47, s30
	v_lshl_add_u64 v[198:199], v[198:199], 0, s[76:77]
	s_mov_b32 m0, s22
	ds_read_b128 v[172:175], v139 offset:49152
	ds_read_b128 v[176:179], v139 offset:50176
	ds_read_b128 v[180:183], v139 offset:51200
	ds_read_b128 v[184:187], v139 offset:52224
	ds_read_b128 v[188:191], v139 offset:53248
	ds_read_b128 v[192:195], v139 offset:54272
	ds_read_b128 v[206:209], v139 offset:55296
	ds_read_b128 v[210:213], v139 offset:56320
	global_load_lds_dwordx4 v[198:199], off
	s_add_i32 m0, s22, 0x2000
	s_add_u32 s20, s20, 0x40080
	v_lshl_add_u64 v[198:199], v[204:205], 0, s[76:77]
	s_addc_u32 s21, s21, 0
	s_add_i32 s22, s48, s30
	global_load_lds_dwordx4 v[198:199], off
	v_lshl_add_u64 v[198:199], s[20:21], 0, v[196:197]
	s_mov_b32 m0, s22
	s_nop 0
	global_load_lds_dwordx4 v[198:199], off
	v_lshl_add_u64 v[198:199], s[20:21], 0, v[132:133]
	s_add_i32 m0, s22, 0x2000
	s_nop 0
	global_load_lds_dwordx4 v[198:199], off
	v_lshl_add_u64 v[198:199], v[214:215], 0, s[76:77]
	s_mov_b32 m0, s38
	s_nop 0
	global_load_lds_dwordx4 v[198:199], off
	v_lshl_add_u64 v[198:199], v[216:217], 0, s[76:77]
	s_mov_b32 m0, s39
	s_nop 0
	global_load_lds_dwordx4 v[198:199], off
	s_waitcnt vmcnt(8)
	s_waitcnt lgkmcnt(0)
	s_barrier
	s_setprio 1
	s_waitcnt lgkmcnt(0)
	v_mfma_f32_16x16x32_bf16 v[60:63], v[140:143], v[172:175], v[60:63]
	v_mfma_f32_16x16x32_bf16 v[52:55], v[148:151], v[172:175], v[52:55]
	v_mfma_f32_16x16x32_bf16 v[44:47], v[140:143], v[180:183], v[44:47]
	v_mfma_f32_16x16x32_bf16 v[36:39], v[148:151], v[180:183], v[36:39]
	v_mfma_f32_16x16x32_bf16 v[28:31], v[140:143], v[188:191], v[28:31]
	v_mfma_f32_16x16x32_bf16 v[20:23], v[148:151], v[188:191], v[20:23]
	v_mfma_f32_16x16x32_bf16 v[12:15], v[140:143], v[206:209], v[12:15]
	v_mfma_f32_16x16x32_bf16 v[4:7], v[148:151], v[206:209], v[4:7]
	v_mfma_f32_16x16x32_bf16 v[60:63], v[144:147], v[176:179], v[60:63]
	v_mfma_f32_16x16x32_bf16 v[52:55], v[152:155], v[176:179], v[52:55]
	v_mfma_f32_16x16x32_bf16 v[44:47], v[144:147], v[184:187], v[44:47]
	v_mfma_f32_16x16x32_bf16 v[36:39], v[152:155], v[184:187], v[36:39]
	v_mfma_f32_16x16x32_bf16 v[28:31], v[144:147], v[192:195], v[28:31]
	v_mfma_f32_16x16x32_bf16 v[20:23], v[152:155], v[192:195], v[20:23]
	v_mfma_f32_16x16x32_bf16 v[12:15], v[144:147], v[210:213], v[12:15]
	v_mfma_f32_16x16x32_bf16 v[4:7], v[152:155], v[210:213], v[4:7]
	s_setprio 0
	s_setprio 1
	v_mfma_f32_16x16x32_bf16 v[56:59], v[156:159], v[172:175], v[56:59]
	v_mfma_f32_16x16x32_bf16 v[48:51], v[164:167], v[172:175], v[48:51]
	v_mfma_f32_16x16x32_bf16 v[40:43], v[156:159], v[180:183], v[40:43]
	v_mfma_f32_16x16x32_bf16 v[32:35], v[164:167], v[180:183], v[32:35]
	v_mfma_f32_16x16x32_bf16 v[24:27], v[156:159], v[188:191], v[24:27]
	v_mfma_f32_16x16x32_bf16 v[16:19], v[164:167], v[188:191], v[16:19]
	v_mfma_f32_16x16x32_bf16 v[8:11], v[156:159], v[206:209], v[8:11]
	v_mfma_f32_16x16x32_bf16 v[0:3], v[164:167], v[206:209], v[0:3]
	v_mfma_f32_16x16x32_bf16 v[56:59], v[160:163], v[176:179], v[56:59]
	v_mfma_f32_16x16x32_bf16 v[48:51], v[168:171], v[176:179], v[48:51]
	v_mfma_f32_16x16x32_bf16 v[40:43], v[160:163], v[184:187], v[40:43]
	v_mfma_f32_16x16x32_bf16 v[32:35], v[168:171], v[184:187], v[32:35]
	v_mfma_f32_16x16x32_bf16 v[24:27], v[160:163], v[192:195], v[24:27]
	v_mfma_f32_16x16x32_bf16 v[16:19], v[168:171], v[192:195], v[16:19]
	v_mfma_f32_16x16x32_bf16 v[8:11], v[160:163], v[210:213], v[8:11]
	v_mfma_f32_16x16x32_bf16 v[0:3], v[168:171], v[210:213], v[0:3]
	s_setprio 0
	s_barrier
	s_add_i32 s46, s46, 2
	s_add_u32 s15, s15, 0x100
	s_addc_u32 s45, s45, 0
	s_add_u32 s18, s18, 0x100
	s_addc_u32 s19, s19, 0
	s_cmp_gt_u32 s46, 13
	s_cbranch_scc0 .LBB0_1820
	s_branch .Lpeel_exit_7

; #define PG8_STAGE(bufoff, gbase, voff) do { _Pragma("unroll") for (int _i = 0; _i < 2; ++_i) \
;         __builtin_amdgcn_global_load_lds((const unsigned*)((const char*)(gbase) + (voff)[_i]), (PG8_LAS unsigned*)(lds + (bufoff) + ldsw + _i * 8192), 16, 0, 0); } while (0)
; #define PG8_LDA(dst, b, h) do { _Pragma("unroll") for (int m = 0; m < 4; ++m) _Pragma("unroll") for (int k = 0; k < 2; ++k) dst[m][k] = *(const PG8_LAS bf16x8*)(lds + PG8_SA(b, h) + aoff + m * 2048 + k * 1024); } while (0)
; #define PG8_LDB(dst, b, h) do { _Pragma("unroll") for (int n = 0; n < 2; ++n) _Pragma("unroll") for (int k = 0; k < 2; ++k) dst[n][k] = *(const PG8_LAS bf16x8*)(lds + PG8_SB(b, h) + boff + n * 2048 + k * 1024); } while (0)
; #define PG8_WAIT_V(n) asm volatile("s_waitcnt vmcnt(" #n ")" ::: "memory")
; #define PG8_WAIT_L(n) asm volatile("s_waitcnt lgkmcnt(" #n ")" ::: "memory")
; #define PG8_BAR __builtin_amdgcn_s_barrier()
; #define PG8_SCHED __builtin_amdgcn_sched_barrier(0)
; template <class Epi, class Sched, bool ALIGN_EPI = false, bool SP2 = false>
; __device__ __forceinline__ void gemm_phase(PG8_LAS unsigned char* lds, const Gemm g, const Sched& S, const Epi& E, int wave_s_) {
;     ...
;     f32x4 acc[2][2][4][2];
; #pragma unroll
;     for (int a = 0; a < 2; ++a)
; #pragma unroll
;         for (int b = 0; b < 2; ++b)
; #pragma unroll
;             for (int m = 0; m < 4; ++m)
; #pragma unroll
;                 for (int n = 0; n < 2; ++n) acc[a][b][m][n] = (f32x4){0.f, 0.f, 0.f, 0.f};
;     ...
;         for (int t = 0; t < nt; t += 2) {
;             const bool last = (t == nt - 2);
;             const char* a1 = cA + (size_t)(t + 1) * kstep;
;             const char* a2 = last ? nA : cA + (size_t)(t + 2) * kstep; const char* b2 = last ? nB : cB + (size_t)(t + 2) * kstep;
;             const char* a3 = a2 + kstep; const char* b3 = b2 + kstep;
;             if (last && has_next) S.a_ready(nxt);
;             if constexpr (SP2) {
;             PG8_LDB(B0, 0, 0); PG8_LDB(B1, 0, 1); PG8_SCHED; PG8_LDA(At, 0, 0); PG8_STAGE(PG8_SA(1, 1), a1 + hstep, voffA);
;             PG8_WAIT_V(8); PG8_WAIT_L(0); PG8_BAR; PG8_MMA(0, 0, At, B0); PG8_MMA(0, 1, At, B1); PG8_BAR; PG8_SCHED;
;             PG8_LDA(At, 0, 1); PG8_STAGE(PG8_SB(0, 0), b2, voffB); PG8_STAGE(PG8_SB(0, 1), b2 + hstep, voffB); PG8_STAGE(PG8_SA(0, 0), a2, voffA);
.LBB0_1907:
	s_cmpk_gt_u32 s51, 0xfff
	s_cselect_b64 s[24:25], -1, 0
	s_cmpk_lt_u32 s51, 0x1000
	s_cselect_b64 s[6:7], -1, 0
	s_and_b64 s[26:27], s[6:7], exec
	s_cselect_b32 s53, 44, 4
	s_add_i32 s54, s53, -2
	s_add_u32 s55, s10, 0x100
	v_mov_b32_e32 v0, 0
	s_addc_u32 s56, s11, 0
	s_mov_b32 s26, 0
	s_add_i32 s57, s26, 2
	s_add_u32 s10, s8, 0x100
	s_addc_u32 s11, s9, 0
	s_add_i32 s58, 0, 0x10000
	s_cmp_eq_u32 s54, s26
	s_cselect_b32 s29, s21, s11
	s_cselect_b32 s28, s20, s10
	s_cselect_b32 s27, s23, s56
	s_cselect_b32 s26, s22, s55
	s_add_i32 s59, 0, 0x14000
	v_add_u32_e32 v100, s58, v224
	v_add_u32_e32 v120, s59, v224
	ds_read_b128 v[76:79], v100
	ds_read_b128 v[84:87], v100 offset:1024
	ds_read_b128 v[92:95], v100 offset:2048
	ds_read_b128 v[100:103], v100 offset:3072
	ds_read_b128 v[104:107], v120
	ds_read_b128 v[108:111], v120 offset:1024
	ds_read_b128 v[112:115], v120 offset:2048
	ds_read_b128 v[120:123], v120 offset:3072
	v_lshl_add_u64 v[198:199], s[8:9], 0, v[206:207]
	s_add_i32 m0, s36, 0xc000
	ds_read_b128 v[160:163], v225
	ds_read_b128 v[164:167], v225 offset:1024
	ds_read_b128 v[168:171], v225 offset:2048
	ds_read_b128 v[172:175], v225 offset:3072
	ds_read_b128 v[176:179], v225 offset:4096
	ds_read_b128 v[180:183], v225 offset:5120
	ds_read_b128 v[184:187], v225 offset:6144
	ds_read_b128 v[188:191], v225 offset:7168
	global_load_lds_dwordx4 v[198:199], off
	v_lshl_add_u64 v[198:199], s[8:9], 0, v[194:195]
	s_add_i32 m0, s36, 0xe000
	s_nop 0
	global_load_lds_dwordx4 v[198:199], off
	s_waitcnt vmcnt(8)
	s_waitcnt lgkmcnt(0)
	s_barrier
	s_setprio 1
	s_waitcnt lgkmcnt(0)
	v_mfma_f32_16x16x32_bf16 v[156:159], v[76:79], v[160:163], 0
	v_mfma_f32_16x16x32_bf16 v[152:155], v[92:95], v[160:163], 0
	v_mfma_f32_16x16x32_bf16 v[144:147], v[76:79], v[168:171], 0
	v_mfma_f32_16x16x32_bf16 v[136:139], v[92:95], v[168:171], 0
	v_mfma_f32_16x16x32_bf16 v[124:127], v[76:79], v[176:179], 0
	v_mfma_f32_16x16x32_bf16 v[116:119], v[92:95], v[176:179], 0
	v_mfma_f32_16x16x32_bf16 v[88:91], v[76:79], v[184:187], 0
	v_mfma_f32_16x16x32_bf16 v[72:75], v[92:95], v[184:187], 0
	v_mfma_f32_16x16x32_bf16 v[156:159], v[84:87], v[164:167], v[156:159]
	v_mfma_f32_16x16x32_bf16 v[152:155], v[100:103], v[164:167], v[152:155]
	v_mfma_f32_16x16x32_bf16 v[144:147], v[84:87], v[172:175], v[144:147]
	v_mfma_f32_16x16x32_bf16 v[136:139], v[100:103], v[172:175], v[136:139]
	v_mfma_f32_16x16x32_bf16 v[124:127], v[84:87], v[180:183], v[124:127]
	v_mfma_f32_16x16x32_bf16 v[116:119], v[100:103], v[180:183], v[116:119]
	v_mfma_f32_16x16x32_bf16 v[88:91], v[84:87], v[188:191], v[88:91]
	v_mfma_f32_16x16x32_bf16 v[72:75], v[100:103], v[188:191], v[72:75]
	s_setprio 0
	s_setprio 1
	v_mfma_f32_16x16x32_bf16 v[148:151], v[104:107], v[160:163], 0
	v_mfma_f32_16x16x32_bf16 v[140:143], v[112:115], v[160:163], 0
	v_mfma_f32_16x16x32_bf16 v[132:135], v[104:107], v[168:171], 0
	v_mfma_f32_16x16x32_bf16 v[128:131], v[112:115], v[168:171], 0
	v_mfma_f32_16x16x32_bf16 v[96:99], v[104:107], v[176:179], 0
	v_mfma_f32_16x16x32_bf16 v[80:83], v[112:115], v[176:179], 0
	v_mfma_f32_16x16x32_bf16 v[68:71], v[104:107], v[184:187], 0
	v_mfma_f32_16x16x32_bf16 v[64:67], v[112:115], v[184:187], 0
	v_mfma_f32_16x16x32_bf16 v[148:151], v[108:111], v[164:167], v[148:151]
	v_mfma_f32_16x16x32_bf16 v[140:143], v[120:123], v[164:167], v[140:143]
	v_mfma_f32_16x16x32_bf16 v[132:135], v[108:111], v[172:175], v[132:135]
	v_mfma_f32_16x16x32_bf16 v[128:131], v[120:123], v[172:175], v[128:131]
	v_mfma_f32_16x16x32_bf16 v[96:99], v[108:111], v[180:183], v[96:99]
	v_mfma_f32_16x16x32_bf16 v[80:83], v[120:123], v[180:183], v[80:83]
	v_mfma_f32_16x16x32_bf16 v[68:71], v[108:111], v[188:191], v[68:71]
	v_mfma_f32_16x16x32_bf16 v[64:67], v[120:123], v[188:191], v[64:67]
	s_setprio 0
	s_barrier
	s_add_i32 s8, s58, s35
	v_lshl_add_u64 v[198:199], s[26:27], 0, v[196:197]
	s_mov_b32 m0, s8
	ds_read_b128 v[160:163], v225 offset:16384
	ds_read_b128 v[164:167], v225 offset:17408
	ds_read_b128 v[168:171], v225 offset:18432
	ds_read_b128 v[172:175], v225 offset:19456
	ds_read_b128 v[176:179], v225 offset:20480
	ds_read_b128 v[180:183], v225 offset:21504
	ds_read_b128 v[184:187], v225 offset:22528
	ds_read_b128 v[188:191], v225 offset:23552
	global_load_lds_dwordx4 v[198:199], off
	s_add_i32 m0, s8, 0x2000
	s_add_u32 s8, s26, 0xb0000
	v_lshl_add_u64 v[204:205], s[26:27], 0, v[192:193]
	s_addc_u32 s9, s27, 0
	s_add_i32 s58, s59, s35
	global_load_lds_dwordx4 v[204:205], off
	v_lshl_add_u64 v[208:209], s[8:9], 0, v[196:197]
	s_mov_b32 m0, s58
	v_lshl_add_u64 v[210:211], s[28:29], 0, v[192:193]
	global_load_lds_dwordx4 v[208:209], off
	v_lshl_add_u64 v[208:209], s[8:9], 0, v[192:193]
	s_add_i32 m0, s58, 0x2000
	s_nop 0
	global_load_lds_dwordx4 v[208:209], off
	v_lshl_add_u64 v[208:209], s[28:29], 0, v[196:197]
	s_mov_b32 m0, s36
	s_nop 0
	global_load_lds_dwordx4 v[208:209], off
	s_mov_b32 m0, s37
	s_nop 0
	global_load_lds_dwordx4 v[210:211], off
	s_waitcnt vmcnt(8)
	s_waitcnt lgkmcnt(0)
	s_barrier
; #define PG8_STAGE(bufoff, gbase, voff) do { _Pragma("unroll") for (int _i = 0; _i < 2; ++_i) \
;         __builtin_amdgcn_global_load_lds((const unsigned*)((const char*)(gbase) + (voff)[_i]), (PG8_LAS unsigned*)(lds + (bufoff) + ldsw + _i * 8192), 16, 0, 0); } while (0)
; #define PG8_LDA(dst, b, h) do { _Pragma("unroll") for (int m = 0; m < 4; ++m) _Pragma("unroll") for (int k = 0; k < 2; ++k) dst[m][k] = *(const PG8_LAS bf16x8*)(lds + PG8_SA(b, h) + aoff + m * 2048 + k * 1024); } while (0)
; #define PG8_LDB(dst, b, h) do { _Pragma("unroll") for (int n = 0; n < 2; ++n) _Pragma("unroll") for (int k = 0; k < 2; ++k) dst[n][k] = *(const PG8_LAS bf16x8*)(lds + PG8_SB(b, h) + boff + n * 2048 + k * 1024); } while (0)
; #define PG8_MMA(ai, bj, At, Bt) do { __builtin_amdgcn_s_setprio(1); _Pragma("unroll") for (int m = 0; m < 4; ++m) _Pragma("unroll") for (int n = 0; n < 2; ++n) _Pragma("unroll") for (int k = 0; k < 2; ++k) \
;         acc[ai][bj][m][n] = __builtin_amdgcn_mfma_f32_16x16x32_bf16(Bt[n][k], At[m][k], acc[ai][bj][m][n], 0, 0, 0); __builtin_amdgcn_s_setprio(0); } while (0)
; #define PG8_WAIT_V(n) asm volatile("s_waitcnt vmcnt(" #n ")" ::: "memory")
; #define PG8_WAIT_L(n) asm volatile("s_waitcnt lgkmcnt(" #n ")" ::: "memory")
; #define PG8_BAR __builtin_amdgcn_s_barrier()
; #define PG8_SCHED __builtin_amdgcn_sched_barrier(0)
; template <class Epi, class Sched, bool ALIGN_EPI = false, bool SP2 = false>
; __device__ __forceinline__ void gemm_phase(PG8_LAS unsigned char* lds, const Gemm g, const Sched& S, const Epi& E, int wave_s_) {
;     ...
;             PG8_WAIT_V(8); PG8_WAIT_L(0); PG8_BAR; PG8_MMA(0, 0, At, B0); PG8_MMA(0, 1, At, B1); PG8_BAR; PG8_SCHED;
;             PG8_LDA(At, 0, 1); PG8_STAGE(PG8_SB(0, 0), b2, voffB); PG8_STAGE(PG8_SB(0, 1), b2 + hstep, voffB); PG8_STAGE(PG8_SA(0, 0), a2, voffA);
;             PG8_WAIT_V(8); PG8_WAIT_L(0); PG8_BAR; PG8_MMA(1, 0, At, B0); PG8_MMA(1, 1, At, B1); PG8_BAR; PG8_SCHED;
;             PG8_LDB(B0, 1, 0); PG8_LDB(B1, 1, 1); PG8_SCHED; PG8_LDA(At, 1, 0); PG8_STAGE(PG8_SA(0, 1), a2 + hstep, voffA);
;             PG8_WAIT_V(8); PG8_WAIT_L(0); PG8_BAR; PG8_MMA(0, 0, At, B0); PG8_MMA(0, 1, At, B1); PG8_BAR; PG8_SCHED;
	s_setprio 1
	s_waitcnt lgkmcnt(0)
	v_mfma_f32_16x16x32_bf16 v[60:63], v[76:79], v[160:163], 0
	v_mfma_f32_16x16x32_bf16 v[56:59], v[92:95], v[160:163], 0
	v_mfma_f32_16x16x32_bf16 v[48:51], v[76:79], v[168:171], 0
	v_mfma_f32_16x16x32_bf16 v[40:43], v[92:95], v[168:171], 0
	v_mfma_f32_16x16x32_bf16 v[28:31], v[76:79], v[176:179], 0
	v_mfma_f32_16x16x32_bf16 v[24:27], v[92:95], v[176:179], 0
	v_mfma_f32_16x16x32_bf16 v[16:19], v[76:79], v[184:187], 0
	v_mfma_f32_16x16x32_bf16 v[8:11], v[92:95], v[184:187], 0
	v_mfma_f32_16x16x32_bf16 v[60:63], v[84:87], v[164:167], v[60:63]
	v_mfma_f32_16x16x32_bf16 v[56:59], v[100:103], v[164:167], v[56:59]
	v_mfma_f32_16x16x32_bf16 v[48:51], v[84:87], v[172:175], v[48:51]
	v_mfma_f32_16x16x32_bf16 v[40:43], v[100:103], v[172:175], v[40:43]
	v_mfma_f32_16x16x32_bf16 v[28:31], v[84:87], v[180:183], v[28:31]
	v_mfma_f32_16x16x32_bf16 v[24:27], v[100:103], v[180:183], v[24:27]
	v_mfma_f32_16x16x32_bf16 v[16:19], v[84:87], v[188:191], v[16:19]
	v_mfma_f32_16x16x32_bf16 v[8:11], v[100:103], v[188:191], v[8:11]
	s_setprio 0
	s_setprio 1
	v_mfma_f32_16x16x32_bf16 v[52:55], v[104:107], v[160:163], 0
	v_mfma_f32_16x16x32_bf16 v[44:47], v[112:115], v[160:163], 0
	v_mfma_f32_16x16x32_bf16 v[36:39], v[104:107], v[168:171], 0
	v_mfma_f32_16x16x32_bf16 v[32:35], v[112:115], v[168:171], 0
	v_mfma_f32_16x16x32_bf16 v[20:23], v[104:107], v[176:179], 0
	v_mfma_f32_16x16x32_bf16 v[12:15], v[112:115], v[176:179], 0
	v_mfma_f32_16x16x32_bf16 v[4:7], v[104:107], v[184:187], 0
	v_mfma_f32_16x16x32_bf16 v[0:3], v[112:115], v[184:187], 0
	v_mfma_f32_16x16x32_bf16 v[52:55], v[108:111], v[164:167], v[52:55]
	v_mfma_f32_16x16x32_bf16 v[44:47], v[120:123], v[164:167], v[44:47]
	v_mfma_f32_16x16x32_bf16 v[36:39], v[108:111], v[172:175], v[36:39]
	v_mfma_f32_16x16x32_bf16 v[32:35], v[120:123], v[172:175], v[32:35]
	v_mfma_f32_16x16x32_bf16 v[20:23], v[108:111], v[180:183], v[20:23]
	v_mfma_f32_16x16x32_bf16 v[12:15], v[120:123], v[180:183], v[12:15]
	v_mfma_f32_16x16x32_bf16 v[4:7], v[108:111], v[188:191], v[4:7]
	v_mfma_f32_16x16x32_bf16 v[0:3], v[120:123], v[188:191], v[0:3]
	s_setprio 0
	s_barrier
	s_add_i32 s58, 0, 0x18000
	s_add_i32 s59, 0, 0x1c000
	v_add_u32_e32 v100, s58, v224
	v_add_u32_e32 v120, s59, v224
	ds_read_b128 v[76:79], v100
	ds_read_b128 v[84:87], v100 offset:1024
	ds_read_b128 v[92:95], v100 offset:2048
	ds_read_b128 v[100:103], v100 offset:3072
	ds_read_b128 v[104:107], v120
	ds_read_b128 v[108:111], v120 offset:1024
	ds_read_b128 v[112:115], v120 offset:2048
	ds_read_b128 v[120:123], v120 offset:3072
	s_add_u32 s8, s28, 0xb0000
	s_addc_u32 s9, s29, 0
	s_mov_b32 m0, s38
	v_lshl_add_u64 v[212:213], s[8:9], 0, v[196:197]
	ds_read_b128 v[160:163], v225 offset:32768
	ds_read_b128 v[164:167], v225 offset:33792
	ds_read_b128 v[168:171], v225 offset:34816
	ds_read_b128 v[172:175], v225 offset:35840
	ds_read_b128 v[176:179], v225 offset:36864
	ds_read_b128 v[180:183], v225 offset:37888
	ds_read_b128 v[184:187], v225 offset:38912
	ds_read_b128 v[188:191], v225 offset:39936
	global_load_lds_dwordx4 v[212:213], off
	v_lshl_add_u64 v[212:213], s[8:9], 0, v[192:193]
	s_mov_b32 m0, s39
	s_nop 0
	global_load_lds_dwordx4 v[212:213], off
	s_waitcnt vmcnt(8)
	s_waitcnt lgkmcnt(0)
	s_barrier
	s_setprio 1
	s_waitcnt lgkmcnt(0)
	v_mfma_f32_16x16x32_bf16 v[156:159], v[76:79], v[160:163], v[156:159]
	v_mfma_f32_16x16x32_bf16 v[152:155], v[92:95], v[160:163], v[152:155]
	v_mfma_f32_16x16x32_bf16 v[144:147], v[76:79], v[168:171], v[144:147]
	v_mfma_f32_16x16x32_bf16 v[136:139], v[92:95], v[168:171], v[136:139]
	v_mfma_f32_16x16x32_bf16 v[124:127], v[76:79], v[176:179], v[124:127]
	v_mfma_f32_16x16x32_bf16 v[116:119], v[92:95], v[176:179], v[116:119]
	v_mfma_f32_16x16x32_bf16 v[88:91], v[76:79], v[184:187], v[88:91]
	v_mfma_f32_16x16x32_bf16 v[72:75], v[92:95], v[184:187], v[72:75]
	v_mfma_f32_16x16x32_bf16 v[156:159], v[84:87], v[164:167], v[156:159]
	v_mfma_f32_16x16x32_bf16 v[152:155], v[100:103], v[164:167], v[152:155]
	v_mfma_f32_16x16x32_bf16 v[144:147], v[84:87], v[172:175], v[144:147]
	v_mfma_f32_16x16x32_bf16 v[136:139], v[100:103], v[172:175], v[136:139]
	v_mfma_f32_16x16x32_bf16 v[124:127], v[84:87], v[180:183], v[124:127]
	v_mfma_f32_16x16x32_bf16 v[116:119], v[100:103], v[180:183], v[116:119]
	v_mfma_f32_16x16x32_bf16 v[88:91], v[84:87], v[188:191], v[88:91]
	v_mfma_f32_16x16x32_bf16 v[72:75], v[100:103], v[188:191], v[72:75]
	s_setprio 0
	s_setprio 1
	v_mfma_f32_16x16x32_bf16 v[148:151], v[104:107], v[160:163], v[148:151]
	v_mfma_f32_16x16x32_bf16 v[140:143], v[112:115], v[160:163], v[140:143]
	v_mfma_f32_16x16x32_bf16 v[132:135], v[104:107], v[168:171], v[132:135]
	v_mfma_f32_16x16x32_bf16 v[128:131], v[112:115], v[168:171], v[128:131]
	v_mfma_f32_16x16x32_bf16 v[96:99], v[104:107], v[176:179], v[96:99]
	v_mfma_f32_16x16x32_bf16 v[80:83], v[112:115], v[176:179], v[80:83]
	v_mfma_f32_16x16x32_bf16 v[68:71], v[104:107], v[184:187], v[68:71]
	v_mfma_f32_16x16x32_bf16 v[64:67], v[112:115], v[184:187], v[64:67]
	v_mfma_f32_16x16x32_bf16 v[148:151], v[108:111], v[164:167], v[148:151]
	v_mfma_f32_16x16x32_bf16 v[140:143], v[120:123], v[164:167], v[140:143]
	v_mfma_f32_16x16x32_bf16 v[132:135], v[108:111], v[172:175], v[132:135]
	v_mfma_f32_16x16x32_bf16 v[128:131], v[120:123], v[172:175], v[128:131]
	v_mfma_f32_16x16x32_bf16 v[96:99], v[108:111], v[180:183], v[96:99]
	v_mfma_f32_16x16x32_bf16 v[80:83], v[120:123], v[180:183], v[80:83]
	v_mfma_f32_16x16x32_bf16 v[68:71], v[108:111], v[188:191], v[68:71]
	v_mfma_f32_16x16x32_bf16 v[64:67], v[120:123], v[188:191], v[64:67]
	s_setprio 0
	s_barrier
; #define PG8_STAGE(bufoff, gbase, voff) do { _Pragma("unroll") for (int _i = 0; _i < 2; ++_i) \
;         __builtin_amdgcn_global_load_lds((const unsigned*)((const char*)(gbase) + (voff)[_i]), (PG8_LAS unsigned*)(lds + (bufoff) + ldsw + _i * 8192), 16, 0, 0); } while (0)
; #define PG8_LDA(dst, b, h) do { _Pragma("unroll") for (int m = 0; m < 4; ++m) _Pragma("unroll") for (int k = 0; k < 2; ++k) dst[m][k] = *(const PG8_LAS bf16x8*)(lds + PG8_SA(b, h) + aoff + m * 2048 + k * 1024); } while (0)
; #define PG8_WAIT_V(n) asm volatile("s_waitcnt vmcnt(" #n ")" ::: "memory")
; #define PG8_WAIT_L(n) asm volatile("s_waitcnt lgkmcnt(" #n ")" ::: "memory")
; #define PG8_BAR __builtin_amdgcn_s_barrier()
; template <class Epi, class Sched, bool ALIGN_EPI = false, bool SP2 = false>
; __device__ __forceinline__ void gemm_phase(PG8_LAS unsigned char* lds, const Gemm g, const Sched& S, const Epi& E, int wave_s_) {
;     ...
;         for (int t = 0; t < nt; t += 2) {
;             const bool last = (t == nt - 2);
;             const char* a1 = cA + (size_t)(t + 1) * kstep;
;             const char* a2 = last ? nA : cA + (size_t)(t + 2) * kstep; const char* b2 = last ? nB : cB + (size_t)(t + 2) * kstep;
;             const char* a3 = a2 + kstep; const char* b3 = b2 + kstep;
;             if (last && has_next) S.a_ready(nxt);
;             if constexpr (SP2) {
;             PG8_LDB(B0, 0, 0); PG8_LDB(B1, 0, 1); PG8_SCHED; PG8_LDA(At, 0, 0); PG8_STAGE(PG8_SA(1, 1), a1 + hstep, voffA);
;             PG8_WAIT_V(8); PG8_WAIT_L(0); PG8_BAR; PG8_MMA(0, 0, At, B0); PG8_MMA(0, 1, At, B1); PG8_BAR; PG8_SCHED;
;             PG8_LDA(At, 0, 1); PG8_STAGE(PG8_SB(0, 0), b2, voffB); PG8_STAGE(PG8_SB(0, 1), b2 + hstep, voffB); PG8_STAGE(PG8_SA(0, 0), a2, voffA);
;             PG8_WAIT_V(8); PG8_WAIT_L(0); PG8_BAR; PG8_MMA(1, 0, At, B0); PG8_MMA(1, 1, At, B1); PG8_BAR; PG8_SCHED;
;             PG8_LDB(B0, 1, 0); PG8_LDB(B1, 1, 1); PG8_SCHED; PG8_LDA(At, 1, 0); PG8_STAGE(PG8_SA(0, 1), a2 + hstep, voffA);
;             PG8_WAIT_V(8); PG8_WAIT_L(0); PG8_BAR; PG8_MMA(0, 0, At, B0); PG8_MMA(0, 1, At, B1); PG8_BAR; PG8_SCHED;
;             PG8_LDA(At, 1, 1); PG8_STAGE(PG8_SB(1, 0), b3, voffB); PG8_STAGE(PG8_SB(1, 1), b3 + hstep, voffB); PG8_STAGE(PG8_SA(1, 0), a3, voffA);
;             PG8_WAIT_V(8); PG8_WAIT_L(0); PG8_BAR; PG8_MMA(1, 0, At, B0); PG8_MMA(1, 1, At, B1); PG8_BAR; PG8_SCHED;
	s_add_i32 s8, s58, s35
	v_lshl_add_u64 v[198:199], v[198:199], 0, s[76:77]
	s_mov_b32 m0, s8
	ds_read_b128 v[160:163], v225 offset:49152
	ds_read_b128 v[164:167], v225 offset:50176
	ds_read_b128 v[168:171], v225 offset:51200
	ds_read_b128 v[172:175], v225 offset:52224
	ds_read_b128 v[176:179], v225 offset:53248
	ds_read_b128 v[180:183], v225 offset:54272
	ds_read_b128 v[184:187], v225 offset:55296
	ds_read_b128 v[188:191], v225 offset:56320
	global_load_lds_dwordx4 v[198:199], off
	s_add_i32 m0, s8, 0x2000
	s_add_u32 s8, s26, 0xb0080
	v_lshl_add_u64 v[198:199], v[204:205], 0, s[76:77]
	s_addc_u32 s9, s27, 0
	s_add_i32 s26, s59, s35
	global_load_lds_dwordx4 v[198:199], off
	v_lshl_add_u64 v[198:199], s[8:9], 0, v[196:197]
	s_mov_b32 m0, s26
	s_nop 0
	global_load_lds_dwordx4 v[198:199], off
	v_lshl_add_u64 v[198:199], s[8:9], 0, v[192:193]
	s_add_i32 m0, s26, 0x2000
	s_nop 0
	global_load_lds_dwordx4 v[198:199], off
	v_lshl_add_u64 v[198:199], v[208:209], 0, s[76:77]
	s_mov_b32 m0, s42
	s_nop 0
	global_load_lds_dwordx4 v[198:199], off
	v_lshl_add_u64 v[198:199], v[210:211], 0, s[76:77]
	s_mov_b32 m0, s43
	s_nop 0
	global_load_lds_dwordx4 v[198:199], off
	s_waitcnt vmcnt(8)
	s_waitcnt lgkmcnt(0)
	s_barrier
	s_setprio 1
	s_waitcnt lgkmcnt(0)
	v_mfma_f32_16x16x32_bf16 v[60:63], v[76:79], v[160:163], v[60:63]
	v_mfma_f32_16x16x32_bf16 v[56:59], v[92:95], v[160:163], v[56:59]
	v_mfma_f32_16x16x32_bf16 v[48:51], v[76:79], v[168:171], v[48:51]
	v_mfma_f32_16x16x32_bf16 v[40:43], v[92:95], v[168:171], v[40:43]
	v_mfma_f32_16x16x32_bf16 v[28:31], v[76:79], v[176:179], v[28:31]
	v_mfma_f32_16x16x32_bf16 v[24:27], v[92:95], v[176:179], v[24:27]
	v_mfma_f32_16x16x32_bf16 v[16:19], v[76:79], v[184:187], v[16:19]
	v_mfma_f32_16x16x32_bf16 v[8:11], v[92:95], v[184:187], v[8:11]
	v_mfma_f32_16x16x32_bf16 v[60:63], v[84:87], v[164:167], v[60:63]
	v_mfma_f32_16x16x32_bf16 v[56:59], v[100:103], v[164:167], v[56:59]
	v_mfma_f32_16x16x32_bf16 v[48:51], v[84:87], v[172:175], v[48:51]
	v_mfma_f32_16x16x32_bf16 v[40:43], v[100:103], v[172:175], v[40:43]
	v_mfma_f32_16x16x32_bf16 v[28:31], v[84:87], v[180:183], v[28:31]
	v_mfma_f32_16x16x32_bf16 v[24:27], v[100:103], v[180:183], v[24:27]
	v_mfma_f32_16x16x32_bf16 v[16:19], v[84:87], v[188:191], v[16:19]
	v_mfma_f32_16x16x32_bf16 v[8:11], v[100:103], v[188:191], v[8:11]
	s_setprio 0
	s_setprio 1
	v_mfma_f32_16x16x32_bf16 v[52:55], v[104:107], v[160:163], v[52:55]
	v_mfma_f32_16x16x32_bf16 v[44:47], v[112:115], v[160:163], v[44:47]
	v_mfma_f32_16x16x32_bf16 v[36:39], v[104:107], v[168:171], v[36:39]
	v_mfma_f32_16x16x32_bf16 v[32:35], v[112:115], v[168:171], v[32:35]
	v_mfma_f32_16x16x32_bf16 v[20:23], v[104:107], v[176:179], v[20:23]
	v_mfma_f32_16x16x32_bf16 v[12:15], v[112:115], v[176:179], v[12:15]
	v_mfma_f32_16x16x32_bf16 v[4:7], v[104:107], v[184:187], v[4:7]
	v_mfma_f32_16x16x32_bf16 v[0:3], v[112:115], v[184:187], v[0:3]
	v_mfma_f32_16x16x32_bf16 v[52:55], v[108:111], v[164:167], v[52:55]
	v_mfma_f32_16x16x32_bf16 v[44:47], v[120:123], v[164:167], v[44:47]
	v_mfma_f32_16x16x32_bf16 v[36:39], v[108:111], v[172:175], v[36:39]
	v_mfma_f32_16x16x32_bf16 v[32:35], v[120:123], v[172:175], v[32:35]
	v_mfma_f32_16x16x32_bf16 v[20:23], v[108:111], v[180:183], v[20:23]
	v_mfma_f32_16x16x32_bf16 v[12:15], v[120:123], v[180:183], v[12:15]
	v_mfma_f32_16x16x32_bf16 v[4:7], v[108:111], v[188:191], v[4:7]
	v_mfma_f32_16x16x32_bf16 v[0:3], v[120:123], v[188:191], v[0:3]
	s_setprio 0
	s_barrier
	s_add_u32 s55, s55, 0x100
	s_addc_u32 s56, s56, 0
	s_cmp_ge_u32 s57, s53
	s_mov_b64 s[8:9], s[10:11]
	s_mov_b32 s26, s57
	s_cbranch_scc0 .LBB0_1908
	s_branch .Lpeel_exit_8
